# removed the per-MFMA-block s_setprio 1/0 flips in all GEMM K-loops
# speedup vs baseline: 1.0277x; 1.0048x over previous
; #define STAGE(P, BASE, br, kt) STAGET(tid_, P, BASE, br, kt)
; #define LDA(dst, b, h) UFOR(m, 4) UFOR(k, 2) \
;     dst[m][k] = *reinterpret_cast<const bf16x8*>((char*)SA(b, h) + lds_byte(wr * 64 + m * 16 + fr, k * 32 + fq * 8))
; #define LDB(dst, b, h) UFOR(n, 2) UFOR(k, 2) \
;     dst[n][k] = *reinterpret_cast<const bf16x8*>((char*)SB(b, h) + lds_byte(wc * 32 + n * 16 + fr, k * 32 + fq * 8))
; #define MMA(ai, bj, At, Bq) do { __builtin_amdgcn_s_setprio(1); \
;     UFOR(m, 4) UFOR(n, 2) UFOR(k, 2) \
;       acc[ai][bj][m][n] = __builtin_amdgcn_mfma_f32_16x16x32_bf16(Bq[n][k], At[m][k], acc[ai][bj][m][n], 0, 0, 0); \
;     __builtin_amdgcn_s_setprio(0); } while (0)
; #define WAIT_L(n) asm volatile("s_waitcnt lgkmcnt(" #n ")" ::: "memory")
; #define BAR __builtin_amdgcn_s_barrier()
; #define SCHED __builtin_amdgcn_sched_barrier(0)
; template <int EPI, int K, int KL> ...
;     ...
;     LDB(B0, 0, 0); SCHED; LDA(At, 0, 0); STAGE(SA(1, 1), A, brow + HALF, t + 1);
;     WAIT_L(8); BAR; WAIT_L(0); MMA(0, 0, At, B0); BAR; SCHED;
;     LDB(B1, 0, 1); STAGE(SB(0, 0), Bt, bcol, t + 2);
;     BAR; WAIT_L(0); MMA(0, 1, At, B1); BAR;
;     LDA(At, 0, 1); STAGE(SA(0, 0), A, brow, t + 2);
;     BAR; WAIT_L(0); MMA(1, 0, At, B0); BAR; SCHED;
.LBB0_236:
	ds_read_b128 v[174:177], v170
	ds_read_b128 v[178:181], v170 offset:1024
	ds_read_b128 v[182:185], v170 offset:2048
	ds_read_b128 v[186:189], v170 offset:3072
	v_add_u32_e32 v171, 0xc000, v157
	v_lshl_add_u64 v[136:137], s[92:93], 0, v[150:151]
	v_readfirstlane_b32 s18, v171
	v_lshl_add_u64 v[138:139], v[136:137], 0, s[88:89]
	s_mov_b32 m0, s18
	v_add_u32_e32 v172, 0xe000, v157
	ds_read_b128 v[190:193], v162
	ds_read_b128 v[194:197], v162 offset:1024
	ds_read_b128 v[198:201], v161
	ds_read_b128 v[202:205], v161 offset:1024
	ds_read_b128 v[218:221], v160
	ds_read_b128 v[222:225], v160 offset:1024
	ds_read_b128 v[226:229], v159
	ds_read_b128 v[230:233], v159 offset:1024
	global_load_lds_dwordx4 v[138:139], off
	v_lshl_add_u64 v[138:139], s[92:93], 0, v[152:153]
	v_readfirstlane_b32 s18, v172
	v_lshl_add_u64 v[208:209], v[138:139], 0, s[88:89]
	s_mov_b32 m0, s18
	s_nop 0
	global_load_lds_dwordx4 v[208:209], off
	s_waitcnt lgkmcnt(8)
	s_barrier
	s_waitcnt lgkmcnt(0)
	s_waitcnt lgkmcnt(0)
	v_mfma_f32_16x16x32_bf16 v[124:127], v[174:177], v[190:193], v[124:127]
	v_mfma_f32_16x16x32_bf16 v[120:123], v[182:185], v[190:193], v[120:123]
	v_mfma_f32_16x16x32_bf16 v[116:119], v[174:177], v[198:201], v[116:119]
	v_mfma_f32_16x16x32_bf16 v[112:115], v[182:185], v[198:201], v[112:115]
	v_mfma_f32_16x16x32_bf16 v[108:111], v[174:177], v[218:221], v[108:111]
	v_mfma_f32_16x16x32_bf16 v[104:107], v[182:185], v[218:221], v[104:107]
	v_mfma_f32_16x16x32_bf16 v[100:103], v[174:177], v[226:229], v[100:103]
	v_mfma_f32_16x16x32_bf16 v[96:99], v[182:185], v[226:229], v[96:99]
	v_mfma_f32_16x16x32_bf16 v[124:127], v[178:181], v[194:197], v[124:127]
	v_mfma_f32_16x16x32_bf16 v[120:123], v[186:189], v[194:197], v[120:123]
	v_mfma_f32_16x16x32_bf16 v[116:119], v[178:181], v[202:205], v[116:119]
	v_mfma_f32_16x16x32_bf16 v[112:115], v[186:189], v[202:205], v[112:115]
	v_mfma_f32_16x16x32_bf16 v[108:111], v[178:181], v[222:225], v[108:111]
	v_mfma_f32_16x16x32_bf16 v[104:107], v[186:189], v[222:225], v[104:107]
	v_mfma_f32_16x16x32_bf16 v[100:103], v[178:181], v[230:233], v[100:103]
	v_mfma_f32_16x16x32_bf16 v[96:99], v[186:189], v[230:233], v[96:99]
	s_barrier
	v_lshl_add_u64 v[208:209], s[92:93], 0, v[146:147]
	v_readfirstlane_b32 s18, v156
	v_lshl_add_u64 v[210:211], v[208:209], 0, s[52:53]
	s_mov_b32 m0, s18
	v_add_u32_e32 v134, 0x2000, v156
	ds_read_b128 v[234:237], v168
	ds_read_b128 v[238:241], v168 offset:1024
	ds_read_b128 v[242:245], v168 offset:2048
	ds_read_b128 v[246:249], v168 offset:3072
	global_load_lds_dwordx4 v[210:211], off
	v_lshl_add_u64 v[210:211], s[92:93], 0, v[148:149]
	v_readfirstlane_b32 s18, v134
	v_lshl_add_u64 v[214:215], v[210:211], 0, s[52:53]
	s_mov_b32 m0, s18
	s_nop 0
	global_load_lds_dwordx4 v[214:215], off
	s_barrier
	s_waitcnt lgkmcnt(0)
	s_waitcnt lgkmcnt(0)
	v_mfma_f32_16x16x32_bf16 v[92:95], v[234:237], v[190:193], v[92:95]
	v_mfma_f32_16x16x32_bf16 v[88:91], v[242:245], v[190:193], v[88:91]
	v_mfma_f32_16x16x32_bf16 v[84:87], v[234:237], v[198:201], v[84:87]
	v_mfma_f32_16x16x32_bf16 v[80:83], v[242:245], v[198:201], v[80:83]
	v_mfma_f32_16x16x32_bf16 v[76:79], v[234:237], v[218:221], v[76:79]
	v_mfma_f32_16x16x32_bf16 v[72:75], v[242:245], v[218:221], v[72:75]
	v_mfma_f32_16x16x32_bf16 v[68:71], v[234:237], v[226:229], v[68:71]
	v_mfma_f32_16x16x32_bf16 v[64:67], v[242:245], v[226:229], v[64:67]
	v_mfma_f32_16x16x32_bf16 v[92:95], v[238:241], v[194:197], v[92:95]
	v_mfma_f32_16x16x32_bf16 v[88:91], v[246:249], v[194:197], v[88:91]
	v_mfma_f32_16x16x32_bf16 v[84:87], v[238:241], v[202:205], v[84:87]
	v_mfma_f32_16x16x32_bf16 v[80:83], v[246:249], v[202:205], v[80:83]
	v_mfma_f32_16x16x32_bf16 v[76:79], v[238:241], v[222:225], v[76:79]
	v_mfma_f32_16x16x32_bf16 v[72:75], v[246:249], v[222:225], v[72:75]
	v_mfma_f32_16x16x32_bf16 v[68:71], v[238:241], v[230:233], v[68:71]
	v_mfma_f32_16x16x32_bf16 v[64:67], v[246:249], v[230:233], v[64:67]
	v_readfirstlane_b32 s18, v157
	v_add_u32_e32 v134, 0x2000, v157
	v_lshl_add_u64 v[214:215], v[136:137], 0, s[8:9]
	s_mov_b32 m0, s18
	v_readfirstlane_b32 s18, v134
	s_barrier
	ds_read_b128 v[190:193], v162 offset:16384
	ds_read_b128 v[194:197], v162 offset:17408
	ds_read_b128 v[198:201], v161 offset:16384
	ds_read_b128 v[202:205], v161 offset:17408
	ds_read_b128 v[218:221], v160 offset:16384
	ds_read_b128 v[222:225], v160 offset:17408
	ds_read_b128 v[226:229], v159 offset:16384
	ds_read_b128 v[230:233], v159 offset:17408
	global_load_lds_dwordx4 v[214:215], off
	v_lshl_add_u64 v[214:215], v[138:139], 0, s[8:9]
	s_mov_b32 m0, s18
	s_nop 0
	global_load_lds_dwordx4 v[214:215], off
	s_barrier
	s_waitcnt lgkmcnt(0)
	s_waitcnt lgkmcnt(0)
	v_mfma_f32_16x16x32_bf16 v[60:63], v[174:177], v[190:193], v[60:63]
	v_mfma_f32_16x16x32_bf16 v[56:59], v[182:185], v[190:193], v[56:59]
	v_mfma_f32_16x16x32_bf16 v[52:55], v[174:177], v[198:201], v[52:55]
	v_mfma_f32_16x16x32_bf16 v[48:51], v[182:185], v[198:201], v[48:51]
	v_mfma_f32_16x16x32_bf16 v[44:47], v[174:177], v[218:221], v[44:47]
	v_mfma_f32_16x16x32_bf16 v[40:43], v[182:185], v[218:221], v[40:43]
	v_mfma_f32_16x16x32_bf16 v[36:39], v[174:177], v[226:229], v[36:39]
	v_mfma_f32_16x16x32_bf16 v[32:35], v[182:185], v[226:229], v[32:35]
	v_mfma_f32_16x16x32_bf16 v[60:63], v[178:181], v[194:197], v[60:63]
	v_mfma_f32_16x16x32_bf16 v[56:59], v[186:189], v[194:197], v[56:59]
	v_mfma_f32_16x16x32_bf16 v[52:55], v[178:181], v[202:205], v[52:55]
	v_mfma_f32_16x16x32_bf16 v[48:51], v[186:189], v[202:205], v[48:51]
	v_mfma_f32_16x16x32_bf16 v[44:47], v[178:181], v[222:225], v[44:47]
	v_mfma_f32_16x16x32_bf16 v[40:43], v[186:189], v[222:225], v[40:43]
	v_mfma_f32_16x16x32_bf16 v[36:39], v[178:181], v[230:233], v[36:39]
	v_mfma_f32_16x16x32_bf16 v[32:35], v[186:189], v[230:233], v[32:35]
	s_barrier
; #define STAGE(P, BASE, br, kt) STAGET(tid_, P, BASE, br, kt)
; #define LDA(dst, b, h) UFOR(m, 4) UFOR(k, 2) \
;     dst[m][k] = *reinterpret_cast<const bf16x8*>((char*)SA(b, h) + lds_byte(wr * 64 + m * 16 + fr, k * 32 + fq * 8))
; #define LDB(dst, b, h) UFOR(n, 2) UFOR(k, 2) \
;     dst[n][k] = *reinterpret_cast<const bf16x8*>((char*)SB(b, h) + lds_byte(wc * 32 + n * 16 + fr, k * 32 + fq * 8))
; #define MMA(ai, bj, At, Bq) do { __builtin_amdgcn_s_setprio(1); \
;     UFOR(m, 4) UFOR(n, 2) UFOR(k, 2) \
;       acc[ai][bj][m][n] = __builtin_amdgcn_mfma_f32_16x16x32_bf16(Bq[n][k], At[m][k], acc[ai][bj][m][n], 0, 0, 0); \
;     __builtin_amdgcn_s_setprio(0); } while (0)
; #define WAIT_V(n) asm volatile("s_waitcnt vmcnt(" #n ")" ::: "memory")
; #define WAIT_L(n) asm volatile("s_waitcnt lgkmcnt(" #n ")" ::: "memory")
; #define BAR __builtin_amdgcn_s_barrier()
; #define SCHED __builtin_amdgcn_sched_barrier(0)
; template <int EPI, int K, int KL> ...
;     ...
;     STAGE(SB(0, 1), Bt, bcol + HALF, t + 2);
;     WAIT_V(6); BAR; MMA(1, 1, At, B1); BAR;
;     LDB(B0, 1, 0); SCHED; LDA(At, 1, 0); STAGE(SA(0, 1), A, brow + HALF, t + 2);
;     WAIT_L(8); BAR; WAIT_L(0); MMA(0, 0, At, B0); BAR; SCHED;
;     LDB(B1, 1, 1); STAGE(SB(1, 0), Bt, bcol, t + 3);
;     BAR; WAIT_L(0); MMA(0, 1, At, B1); BAR;
;     LDA(At, 1, 1); STAGE(SA(1, 0), A, brow, t + 3);
	v_readfirstlane_b32 s18, v158
	v_add_u32_e32 v134, 0x2000, v158
	v_lshl_add_u64 v[174:175], v[208:209], 0, s[54:55]
	s_mov_b32 m0, s18
	v_readfirstlane_b32 s18, v134
	global_load_lds_dwordx4 v[174:175], off
	v_lshl_add_u64 v[174:175], v[210:211], 0, s[54:55]
	s_mov_b32 m0, s18
	s_nop 0
	global_load_lds_dwordx4 v[174:175], off
	s_waitcnt vmcnt(6)
	s_barrier
	v_mfma_f32_16x16x32_bf16 v[28:31], v[234:237], v[190:193], v[28:31]
	v_mfma_f32_16x16x32_bf16 v[24:27], v[242:245], v[190:193], v[24:27]
	v_mfma_f32_16x16x32_bf16 v[20:23], v[234:237], v[198:201], v[20:23]
	v_mfma_f32_16x16x32_bf16 v[16:19], v[242:245], v[198:201], v[16:19]
	v_mfma_f32_16x16x32_bf16 v[12:15], v[234:237], v[218:221], v[12:15]
	v_mfma_f32_16x16x32_bf16 v[8:11], v[242:245], v[218:221], v[8:11]
	v_mfma_f32_16x16x32_bf16 v[4:7], v[234:237], v[226:229], v[4:7]
	v_mfma_f32_16x16x32_bf16 v[0:3], v[242:245], v[226:229], v[0:3]
	v_mfma_f32_16x16x32_bf16 v[28:31], v[238:241], v[194:197], v[28:31]
	v_mfma_f32_16x16x32_bf16 v[24:27], v[246:249], v[194:197], v[24:27]
	v_mfma_f32_16x16x32_bf16 v[20:23], v[238:241], v[202:205], v[20:23]
	v_mfma_f32_16x16x32_bf16 v[16:19], v[246:249], v[202:205], v[16:19]
	v_mfma_f32_16x16x32_bf16 v[12:15], v[238:241], v[222:225], v[12:15]
	v_mfma_f32_16x16x32_bf16 v[8:11], v[246:249], v[222:225], v[8:11]
	v_mfma_f32_16x16x32_bf16 v[4:7], v[238:241], v[230:233], v[4:7]
	v_mfma_f32_16x16x32_bf16 v[0:3], v[246:249], v[230:233], v[0:3]
	s_barrier
	ds_read_b128 v[174:177], v164
	ds_read_b128 v[178:181], v164 offset:1024
	ds_read_b128 v[182:185], v164 offset:2048
	ds_read_b128 v[186:189], v164 offset:3072
	v_add_u32_e32 v134, 0x4000, v157
	v_lshl_add_u64 v[214:215], v[136:137], 0, s[12:13]
	v_readfirstlane_b32 s18, v134
	v_add_u32_e32 v134, 0x6000, v157
	s_mov_b32 m0, s18
	v_readfirstlane_b32 s18, v134
	ds_read_b128 v[190:193], v162 offset:32768
	ds_read_b128 v[194:197], v162 offset:33792
	ds_read_b128 v[198:201], v161 offset:32768
	ds_read_b128 v[202:205], v161 offset:33792
	ds_read_b128 v[218:221], v160 offset:32768
	ds_read_b128 v[222:225], v160 offset:33792
	ds_read_b128 v[226:229], v159 offset:32768
	ds_read_b128 v[230:233], v159 offset:33792
	global_load_lds_dwordx4 v[214:215], off
	v_lshl_add_u64 v[214:215], v[138:139], 0, s[12:13]
	s_mov_b32 m0, s18
	s_nop 0
	global_load_lds_dwordx4 v[214:215], off
	s_waitcnt lgkmcnt(8)
	s_barrier
	s_waitcnt lgkmcnt(0)
	s_waitcnt lgkmcnt(0)
	v_mfma_f32_16x16x32_bf16 v[124:127], v[174:177], v[190:193], v[124:127]
	v_mfma_f32_16x16x32_bf16 v[120:123], v[182:185], v[190:193], v[120:123]
	v_mfma_f32_16x16x32_bf16 v[116:119], v[174:177], v[198:201], v[116:119]
	v_mfma_f32_16x16x32_bf16 v[112:115], v[182:185], v[198:201], v[112:115]
	v_mfma_f32_16x16x32_bf16 v[108:111], v[174:177], v[218:221], v[108:111]
	v_mfma_f32_16x16x32_bf16 v[104:107], v[182:185], v[218:221], v[104:107]
	v_mfma_f32_16x16x32_bf16 v[100:103], v[174:177], v[226:229], v[100:103]
	v_mfma_f32_16x16x32_bf16 v[96:99], v[182:185], v[226:229], v[96:99]
	v_mfma_f32_16x16x32_bf16 v[124:127], v[178:181], v[194:197], v[124:127]
	v_mfma_f32_16x16x32_bf16 v[120:123], v[186:189], v[194:197], v[120:123]
	v_mfma_f32_16x16x32_bf16 v[116:119], v[178:181], v[202:205], v[116:119]
	v_mfma_f32_16x16x32_bf16 v[112:115], v[186:189], v[202:205], v[112:115]
	v_mfma_f32_16x16x32_bf16 v[108:111], v[178:181], v[222:225], v[108:111]
	v_mfma_f32_16x16x32_bf16 v[104:107], v[186:189], v[222:225], v[104:107]
	v_mfma_f32_16x16x32_bf16 v[100:103], v[178:181], v[230:233], v[100:103]
	v_mfma_f32_16x16x32_bf16 v[96:99], v[186:189], v[230:233], v[96:99]
	s_barrier
	v_readfirstlane_b32 s18, v165
	v_add_u32_e32 v134, 0x2000, v165
	v_lshl_add_u64 v[214:215], v[208:209], 0, s[56:57]
	s_mov_b32 m0, s18
	v_readfirstlane_b32 s18, v134
	ds_read_b128 v[234:237], v163
	ds_read_b128 v[238:241], v163 offset:1024
	ds_read_b128 v[242:245], v163 offset:2048
	ds_read_b128 v[246:249], v163 offset:3072
	global_load_lds_dwordx4 v[214:215], off
	v_lshl_add_u64 v[214:215], v[210:211], 0, s[56:57]
	s_mov_b32 m0, s18
	s_nop 0
	global_load_lds_dwordx4 v[214:215], off
	s_barrier
	s_waitcnt lgkmcnt(0)
	s_waitcnt lgkmcnt(0)
	v_mfma_f32_16x16x32_bf16 v[92:95], v[234:237], v[190:193], v[92:95]
	v_mfma_f32_16x16x32_bf16 v[88:91], v[242:245], v[190:193], v[88:91]
	v_mfma_f32_16x16x32_bf16 v[84:87], v[234:237], v[198:201], v[84:87]
	v_mfma_f32_16x16x32_bf16 v[80:83], v[242:245], v[198:201], v[80:83]
	v_mfma_f32_16x16x32_bf16 v[76:79], v[234:237], v[218:221], v[76:79]
	v_mfma_f32_16x16x32_bf16 v[72:75], v[242:245], v[218:221], v[72:75]
	v_mfma_f32_16x16x32_bf16 v[68:71], v[234:237], v[226:229], v[68:71]
	v_mfma_f32_16x16x32_bf16 v[64:67], v[242:245], v[226:229], v[64:67]
	v_mfma_f32_16x16x32_bf16 v[92:95], v[238:241], v[194:197], v[92:95]
	v_mfma_f32_16x16x32_bf16 v[88:91], v[246:249], v[194:197], v[88:91]
	v_mfma_f32_16x16x32_bf16 v[84:87], v[238:241], v[202:205], v[84:87]
	v_mfma_f32_16x16x32_bf16 v[80:83], v[246:249], v[202:205], v[80:83]
	v_mfma_f32_16x16x32_bf16 v[76:79], v[238:241], v[222:225], v[76:79]
	v_mfma_f32_16x16x32_bf16 v[72:75], v[246:249], v[222:225], v[72:75]
	v_mfma_f32_16x16x32_bf16 v[68:71], v[238:241], v[230:233], v[68:71]
	v_mfma_f32_16x16x32_bf16 v[64:67], v[246:249], v[230:233], v[64:67]
	v_readfirstlane_b32 s18, v166
	v_lshl_add_u64 v[136:137], v[136:137], 0, s[16:17]
	s_mov_b32 m0, s18
	v_readfirstlane_b32 s18, v167
	s_barrier
	ds_read_b128 v[190:193], v162 offset:49152
	ds_read_b128 v[194:197], v162 offset:50176
	ds_read_b128 v[198:201], v161 offset:49152
	ds_read_b128 v[202:205], v161 offset:50176
	ds_read_b128 v[218:221], v160 offset:49152
	ds_read_b128 v[222:225], v160 offset:50176
	ds_read_b128 v[226:229], v159 offset:49152
	ds_read_b128 v[230:233], v159 offset:50176
	global_load_lds_dwordx4 v[136:137], off
	v_lshl_add_u64 v[136:137], v[138:139], 0, s[16:17]
	s_mov_b32 m0, s18
	s_nop 0
	global_load_lds_dwordx4 v[136:137], off
	s_barrier
; #define STAGE(P, BASE, br, kt) STAGET(tid_, P, BASE, br, kt)
; #define LDA(dst, b, h) UFOR(m, 4) UFOR(k, 2) \
;     dst[m][k] = *reinterpret_cast<const bf16x8*>((char*)SA(b, h) + lds_byte(wr * 64 + m * 16 + fr, k * 32 + fq * 8))
; #define LDB(dst, b, h) UFOR(n, 2) UFOR(k, 2) \
;     dst[n][k] = *reinterpret_cast<const bf16x8*>((char*)SB(b, h) + lds_byte(wc * 32 + n * 16 + fr, k * 32 + fq * 8))
; #define MMA(ai, bj, At, Bq) do { __builtin_amdgcn_s_setprio(1); \
;     UFOR(m, 4) UFOR(n, 2) UFOR(k, 2) \
;       acc[ai][bj][m][n] = __builtin_amdgcn_mfma_f32_16x16x32_bf16(Bq[n][k], At[m][k], acc[ai][bj][m][n], 0, 0, 0); \
;     __builtin_amdgcn_s_setprio(0); } while (0)
; #define WAIT_V(n) asm volatile("s_waitcnt vmcnt(" #n ")" ::: "memory")
; #define WAIT_L(n) asm volatile("s_waitcnt lgkmcnt(" #n ")" ::: "memory")
; #define BAR __builtin_amdgcn_s_barrier()
; #define SCHED __builtin_amdgcn_sched_barrier(0)
; template <int EPI, int K, int KL> ...
;     ...
;     BAR; WAIT_L(0); MMA(1, 0, At, B0); BAR; SCHED;
;     STAGE(SB(1, 1), Bt, bcol + HALF, t + 3);
;     WAIT_V(6); BAR; MMA(1, 1, At, B1); BAR;
;   }
;   { LDB(B0, 0, 0); LDA(At, 0, 0); STAGE(SA(1, 1), A, brow + HALF, nt - 1);
;     BAR; WAIT_L(0); MMA(0, 0, At, B0); BAR;
	s_waitcnt lgkmcnt(0)
	s_waitcnt lgkmcnt(0)
	v_mfma_f32_16x16x32_bf16 v[60:63], v[174:177], v[190:193], v[60:63]
	v_mfma_f32_16x16x32_bf16 v[56:59], v[182:185], v[190:193], v[56:59]
	v_mfma_f32_16x16x32_bf16 v[52:55], v[174:177], v[198:201], v[52:55]
	v_mfma_f32_16x16x32_bf16 v[48:51], v[182:185], v[198:201], v[48:51]
	v_mfma_f32_16x16x32_bf16 v[44:47], v[174:177], v[218:221], v[44:47]
	v_mfma_f32_16x16x32_bf16 v[40:43], v[182:185], v[218:221], v[40:43]
	v_mfma_f32_16x16x32_bf16 v[36:39], v[174:177], v[226:229], v[36:39]
	v_mfma_f32_16x16x32_bf16 v[32:35], v[182:185], v[226:229], v[32:35]
	v_mfma_f32_16x16x32_bf16 v[60:63], v[178:181], v[194:197], v[60:63]
	v_mfma_f32_16x16x32_bf16 v[56:59], v[186:189], v[194:197], v[56:59]
	v_mfma_f32_16x16x32_bf16 v[52:55], v[178:181], v[202:205], v[52:55]
	v_mfma_f32_16x16x32_bf16 v[48:51], v[186:189], v[202:205], v[48:51]
	v_mfma_f32_16x16x32_bf16 v[44:47], v[178:181], v[222:225], v[44:47]
	v_mfma_f32_16x16x32_bf16 v[40:43], v[186:189], v[222:225], v[40:43]
	v_mfma_f32_16x16x32_bf16 v[36:39], v[178:181], v[230:233], v[36:39]
	v_mfma_f32_16x16x32_bf16 v[32:35], v[186:189], v[230:233], v[32:35]
	s_barrier
	v_readfirstlane_b32 s18, v169
	v_add_u32_e32 v134, 0x2000, v169
	v_lshl_add_u64 v[136:137], v[208:209], 0, s[58:59]
	s_mov_b32 m0, s18
	v_readfirstlane_b32 s18, v134
	global_load_lds_dwordx4 v[136:137], off
	v_lshl_add_u64 v[136:137], v[210:211], 0, s[58:59]
	s_mov_b32 m0, s18
	s_nop 0
	global_load_lds_dwordx4 v[136:137], off
	s_waitcnt vmcnt(6)
	s_barrier
	v_mfma_f32_16x16x32_bf16 v[28:31], v[234:237], v[190:193], v[28:31]
	v_mfma_f32_16x16x32_bf16 v[24:27], v[242:245], v[190:193], v[24:27]
	v_mfma_f32_16x16x32_bf16 v[20:23], v[234:237], v[198:201], v[20:23]
	v_mfma_f32_16x16x32_bf16 v[16:19], v[242:245], v[198:201], v[16:19]
	v_mfma_f32_16x16x32_bf16 v[12:15], v[234:237], v[218:221], v[12:15]
	v_mfma_f32_16x16x32_bf16 v[8:11], v[242:245], v[218:221], v[8:11]
	v_mfma_f32_16x16x32_bf16 v[4:7], v[234:237], v[226:229], v[4:7]
	v_mfma_f32_16x16x32_bf16 v[0:3], v[242:245], v[226:229], v[0:3]
	v_mfma_f32_16x16x32_bf16 v[28:31], v[238:241], v[194:197], v[28:31]
	v_mfma_f32_16x16x32_bf16 v[24:27], v[246:249], v[194:197], v[24:27]
	v_mfma_f32_16x16x32_bf16 v[20:23], v[238:241], v[202:205], v[20:23]
	v_mfma_f32_16x16x32_bf16 v[16:19], v[246:249], v[202:205], v[16:19]
	v_mfma_f32_16x16x32_bf16 v[12:15], v[238:241], v[222:225], v[12:15]
	v_mfma_f32_16x16x32_bf16 v[8:11], v[246:249], v[222:225], v[8:11]
	v_mfma_f32_16x16x32_bf16 v[4:7], v[238:241], v[230:233], v[4:7]
	v_mfma_f32_16x16x32_bf16 v[0:3], v[246:249], v[230:233], v[0:3]
	s_add_i32 s15, s15, 2
	v_lshl_add_u64 v[146:147], v[146:147], 0, s[20:21]
	v_lshl_add_u64 v[148:149], v[148:149], 0, s[20:21]
	v_lshl_add_u64 v[150:151], v[150:151], 0, s[20:21]
	s_cmp_lt_u32 s15, 28
	v_lshl_add_u64 v[152:153], v[152:153], 0, s[20:21]
	s_barrier
	s_cbranch_scc1 .LBB0_236
	s_add_u32 s18, s50, 0x80f80
	s_addc_u32 s19, s51, 0
	v_lshl_add_u64 v[136:137], s[18:19], 0, v[140:141]
	v_readfirstlane_b32 s15, v171
	v_lshl_add_u64 v[130:131], v[130:131], 1, v[136:137]
	s_mov_b32 m0, s15
	ds_read_b128 v[146:149], v170
	ds_read_b128 v[150:153], v170 offset:1024
	ds_read_b128 v[174:177], v170 offset:2048
	ds_read_b128 v[178:181], v170 offset:3072
	ds_read_b128 v[182:185], v162
	ds_read_b128 v[186:189], v162 offset:1024
	ds_read_b128 v[190:193], v161
	ds_read_b128 v[194:197], v161 offset:1024
	ds_read_b128 v[198:201], v160
	ds_read_b128 v[202:205], v160 offset:1024
	ds_read_b128 v[218:221], v159
	ds_read_b128 v[222:225], v159 offset:1024
	global_load_lds_dwordx4 v[130:131], off
	v_lshl_add_u64 v[130:131], s[18:19], 0, v[144:145]
	v_readfirstlane_b32 s15, v172
	v_lshl_add_u64 v[130:131], v[142:143], 1, v[130:131]
	s_mov_b32 m0, s15
	s_nop 0
	global_load_lds_dwordx4 v[130:131], off
	s_barrier
	s_waitcnt lgkmcnt(0)
	s_waitcnt lgkmcnt(0)
	v_mfma_f32_16x16x32_bf16 v[124:127], v[146:149], v[182:185], v[124:127]
	v_mfma_f32_16x16x32_bf16 v[120:123], v[174:177], v[182:185], v[120:123]
	v_mfma_f32_16x16x32_bf16 v[116:119], v[146:149], v[190:193], v[116:119]
	v_mfma_f32_16x16x32_bf16 v[112:115], v[174:177], v[190:193], v[112:115]
	v_mfma_f32_16x16x32_bf16 v[108:111], v[146:149], v[198:201], v[108:111]
	v_mfma_f32_16x16x32_bf16 v[104:107], v[174:177], v[198:201], v[104:107]
	v_mfma_f32_16x16x32_bf16 v[100:103], v[146:149], v[218:221], v[100:103]
	v_mfma_f32_16x16x32_bf16 v[96:99], v[174:177], v[218:221], v[96:99]
	v_mfma_f32_16x16x32_bf16 v[124:127], v[150:153], v[186:189], v[124:127]
	v_mfma_f32_16x16x32_bf16 v[120:123], v[178:181], v[186:189], v[120:123]
	v_mfma_f32_16x16x32_bf16 v[116:119], v[150:153], v[194:197], v[116:119]
	v_mfma_f32_16x16x32_bf16 v[112:115], v[178:181], v[194:197], v[112:115]
	v_mfma_f32_16x16x32_bf16 v[108:111], v[150:153], v[202:205], v[108:111]
	v_mfma_f32_16x16x32_bf16 v[104:107], v[178:181], v[202:205], v[104:107]
	v_mfma_f32_16x16x32_bf16 v[100:103], v[150:153], v[222:225], v[100:103]
	v_mfma_f32_16x16x32_bf16 v[96:99], v[178:181], v[222:225], v[96:99]
	s_barrier
	ds_read_b128 v[140:143], v168
	ds_read_b128 v[170:173], v168 offset:1024
	ds_read_b128 v[226:229], v168 offset:2048
	ds_read_b128 v[166:169], v168 offset:3072
	s_barrier
; #define LDA(dst, b, h) UFOR(m, 4) UFOR(k, 2) \
;     dst[m][k] = *reinterpret_cast<const bf16x8*>((char*)SA(b, h) + lds_byte(wr * 64 + m * 16 + fr, k * 32 + fq * 8))
; #define LDB(dst, b, h) UFOR(n, 2) UFOR(k, 2) \
;     dst[n][k] = *reinterpret_cast<const bf16x8*>((char*)SB(b, h) + lds_byte(wc * 32 + n * 16 + fr, k * 32 + fq * 8))
; #define MMA(ai, bj, At, Bq) do { __builtin_amdgcn_s_setprio(1); \
;     UFOR(m, 4) UFOR(n, 2) UFOR(k, 2) \
;       acc[ai][bj][m][n] = __builtin_amdgcn_mfma_f32_16x16x32_bf16(Bq[n][k], At[m][k], acc[ai][bj][m][n], 0, 0, 0); \
;     __builtin_amdgcn_s_setprio(0); } while (0)
; #define WAIT_V(n) asm volatile("s_waitcnt vmcnt(" #n ")" ::: "memory")
; #define WAIT_L(n) asm volatile("s_waitcnt lgkmcnt(" #n ")" ::: "memory")
; #define BAR __builtin_amdgcn_s_barrier()
; template <int EPI, int K, int KL> ...
;     ...
;     BAR; WAIT_L(0); MMA(0, 0, At, B0); BAR;
;     LDB(B1, 0, 1); BAR; WAIT_L(0); MMA(0, 1, At, B1); BAR;
;     LDA(At, 0, 1); WAIT_V(4); BAR; WAIT_L(0); MMA(1, 0, At, B0); MMA(1, 1, At, B1); BAR; }
;   { LDB(B0, 1, 0); LDA(At, 1, 0); WAIT_V(2); BAR; WAIT_L(0); MMA(0, 0, At, B0); BAR;
	s_waitcnt lgkmcnt(0)
	s_waitcnt lgkmcnt(0)
	v_mfma_f32_16x16x32_bf16 v[92:95], v[140:143], v[182:185], v[92:95]
	v_mfma_f32_16x16x32_bf16 v[88:91], v[226:229], v[182:185], v[88:91]
	v_mfma_f32_16x16x32_bf16 v[84:87], v[140:143], v[190:193], v[84:87]
	v_mfma_f32_16x16x32_bf16 v[80:83], v[226:229], v[190:193], v[80:83]
	v_mfma_f32_16x16x32_bf16 v[76:79], v[140:143], v[198:201], v[76:79]
	v_mfma_f32_16x16x32_bf16 v[72:75], v[226:229], v[198:201], v[72:75]
	v_mfma_f32_16x16x32_bf16 v[68:71], v[140:143], v[218:221], v[68:71]
	v_mfma_f32_16x16x32_bf16 v[64:67], v[226:229], v[218:221], v[64:67]
	v_mfma_f32_16x16x32_bf16 v[92:95], v[170:173], v[186:189], v[92:95]
	v_mfma_f32_16x16x32_bf16 v[88:91], v[166:169], v[186:189], v[88:91]
	v_mfma_f32_16x16x32_bf16 v[84:87], v[170:173], v[194:197], v[84:87]
	v_mfma_f32_16x16x32_bf16 v[80:83], v[166:169], v[194:197], v[80:83]
	v_mfma_f32_16x16x32_bf16 v[76:79], v[170:173], v[202:205], v[76:79]
	v_mfma_f32_16x16x32_bf16 v[72:75], v[166:169], v[202:205], v[72:75]
	v_mfma_f32_16x16x32_bf16 v[68:71], v[170:173], v[222:225], v[68:71]
	v_mfma_f32_16x16x32_bf16 v[64:67], v[166:169], v[222:225], v[64:67]
	s_barrier
	ds_read_b128 v[182:185], v162 offset:16384
	ds_read_b128 v[186:189], v162 offset:17408
	ds_read_b128 v[190:193], v161 offset:16384
	ds_read_b128 v[194:197], v161 offset:17408
	ds_read_b128 v[198:201], v160 offset:16384
	ds_read_b128 v[202:205], v160 offset:17408
	ds_read_b128 v[218:221], v159 offset:16384
	ds_read_b128 v[222:225], v159 offset:17408
	s_waitcnt vmcnt(4)
	s_barrier
	s_waitcnt lgkmcnt(0)
	s_waitcnt lgkmcnt(0)
	v_mfma_f32_16x16x32_bf16 v[60:63], v[146:149], v[182:185], v[60:63]
	v_mfma_f32_16x16x32_bf16 v[56:59], v[174:177], v[182:185], v[56:59]
	v_mfma_f32_16x16x32_bf16 v[52:55], v[146:149], v[190:193], v[52:55]
	v_mfma_f32_16x16x32_bf16 v[48:51], v[174:177], v[190:193], v[48:51]
	v_mfma_f32_16x16x32_bf16 v[44:47], v[146:149], v[198:201], v[44:47]
	v_mfma_f32_16x16x32_bf16 v[40:43], v[174:177], v[198:201], v[40:43]
	v_mfma_f32_16x16x32_bf16 v[36:39], v[146:149], v[218:221], v[36:39]
	v_mfma_f32_16x16x32_bf16 v[32:35], v[174:177], v[218:221], v[32:35]
	v_mfma_f32_16x16x32_bf16 v[60:63], v[150:153], v[186:189], v[60:63]
	v_mfma_f32_16x16x32_bf16 v[56:59], v[178:181], v[186:189], v[56:59]
	v_mfma_f32_16x16x32_bf16 v[52:55], v[150:153], v[194:197], v[52:55]
	v_mfma_f32_16x16x32_bf16 v[48:51], v[178:181], v[194:197], v[48:51]
	v_mfma_f32_16x16x32_bf16 v[44:47], v[150:153], v[202:205], v[44:47]
	v_mfma_f32_16x16x32_bf16 v[40:43], v[178:181], v[202:205], v[40:43]
	v_mfma_f32_16x16x32_bf16 v[36:39], v[150:153], v[222:225], v[36:39]
	v_mfma_f32_16x16x32_bf16 v[32:35], v[178:181], v[222:225], v[32:35]
	v_mfma_f32_16x16x32_bf16 v[28:31], v[140:143], v[182:185], v[28:31]
	v_mfma_f32_16x16x32_bf16 v[24:27], v[226:229], v[182:185], v[24:27]
	v_mfma_f32_16x16x32_bf16 v[20:23], v[140:143], v[190:193], v[20:23]
	v_mfma_f32_16x16x32_bf16 v[16:19], v[226:229], v[190:193], v[16:19]
	v_mfma_f32_16x16x32_bf16 v[12:15], v[140:143], v[198:201], v[12:15]
	v_mfma_f32_16x16x32_bf16 v[8:11], v[226:229], v[198:201], v[8:11]
	v_mfma_f32_16x16x32_bf16 v[4:7], v[140:143], v[218:221], v[4:7]
	v_mfma_f32_16x16x32_bf16 v[0:3], v[226:229], v[218:221], v[0:3]
	v_mfma_f32_16x16x32_bf16 v[28:31], v[170:173], v[186:189], v[28:31]
	v_mfma_f32_16x16x32_bf16 v[24:27], v[166:169], v[186:189], v[24:27]
	v_mfma_f32_16x16x32_bf16 v[20:23], v[170:173], v[194:197], v[20:23]
	v_mfma_f32_16x16x32_bf16 v[16:19], v[166:169], v[194:197], v[16:19]
	v_mfma_f32_16x16x32_bf16 v[12:15], v[170:173], v[202:205], v[12:15]
	v_mfma_f32_16x16x32_bf16 v[8:11], v[166:169], v[202:205], v[8:11]
	v_mfma_f32_16x16x32_bf16 v[4:7], v[170:173], v[222:225], v[4:7]
	v_mfma_f32_16x16x32_bf16 v[0:3], v[166:169], v[222:225], v[0:3]
	s_barrier
	ds_read_b128 v[140:143], v164
	ds_read_b128 v[144:147], v164 offset:1024
	ds_read_b128 v[148:151], v164 offset:2048
	ds_read_b128 v[164:167], v164 offset:3072
	ds_read_b128 v[168:171], v162 offset:32768
	ds_read_b128 v[172:175], v162 offset:33792
	ds_read_b128 v[176:179], v161 offset:32768
	ds_read_b128 v[180:183], v161 offset:33792
	ds_read_b128 v[184:187], v160 offset:32768
	ds_read_b128 v[188:191], v160 offset:33792
	ds_read_b128 v[192:195], v159 offset:32768
	ds_read_b128 v[196:199], v159 offset:33792
	s_waitcnt vmcnt(2)
	s_barrier
; #define LDA(dst, b, h) UFOR(m, 4) UFOR(k, 2) \
;     dst[m][k] = *reinterpret_cast<const bf16x8*>((char*)SA(b, h) + lds_byte(wr * 64 + m * 16 + fr, k * 32 + fq * 8))
; #define LDB(dst, b, h) UFOR(n, 2) UFOR(k, 2) \
;     dst[n][k] = *reinterpret_cast<const bf16x8*>((char*)SB(b, h) + lds_byte(wc * 32 + n * 16 + fr, k * 32 + fq * 8))
; #define MMA(ai, bj, At, Bq) do { __builtin_amdgcn_s_setprio(1); \
;     UFOR(m, 4) UFOR(n, 2) UFOR(k, 2) \
;       acc[ai][bj][m][n] = __builtin_amdgcn_mfma_f32_16x16x32_bf16(Bq[n][k], At[m][k], acc[ai][bj][m][n], 0, 0, 0); \
;     __builtin_amdgcn_s_setprio(0); } while (0)
; #define WAIT_V(n) asm volatile("s_waitcnt vmcnt(" #n ")" ::: "memory")
; #define WAIT_L(n) asm volatile("s_waitcnt lgkmcnt(" #n ")" ::: "memory")
; #define BAR __builtin_amdgcn_s_barrier()
; template <int EPI, int K, int KL> ...
;     ...
;   { LDB(B0, 1, 0); LDA(At, 1, 0); WAIT_V(2); BAR; WAIT_L(0); MMA(0, 0, At, B0); BAR;
;     LDB(B1, 1, 1); WAIT_V(0); BAR; WAIT_L(0); MMA(0, 1, At, B1); BAR;
;     LDA(At, 1, 1); BAR; WAIT_L(0); MMA(1, 0, At, B0); MMA(1, 1, At, B1); BAR; }
;   if (wr == 0) BAR;
	s_waitcnt lgkmcnt(0)
	s_waitcnt lgkmcnt(0)
	v_mfma_f32_16x16x32_bf16 v[124:127], v[140:143], v[168:171], v[124:127]
	v_mfma_f32_16x16x32_bf16 v[120:123], v[148:151], v[168:171], v[120:123]
	v_mfma_f32_16x16x32_bf16 v[116:119], v[140:143], v[176:179], v[116:119]
	v_mfma_f32_16x16x32_bf16 v[112:115], v[148:151], v[176:179], v[112:115]
	v_mfma_f32_16x16x32_bf16 v[108:111], v[140:143], v[184:187], v[108:111]
	v_mfma_f32_16x16x32_bf16 v[104:107], v[148:151], v[184:187], v[104:107]
	v_mfma_f32_16x16x32_bf16 v[100:103], v[140:143], v[192:195], v[100:103]
	v_mfma_f32_16x16x32_bf16 v[96:99], v[148:151], v[192:195], v[96:99]
	v_mfma_f32_16x16x32_bf16 v[124:127], v[144:147], v[172:175], v[124:127]
	v_mfma_f32_16x16x32_bf16 v[120:123], v[164:167], v[172:175], v[120:123]
	v_mfma_f32_16x16x32_bf16 v[116:119], v[144:147], v[180:183], v[116:119]
	v_mfma_f32_16x16x32_bf16 v[112:115], v[164:167], v[180:183], v[112:115]
	v_mfma_f32_16x16x32_bf16 v[108:111], v[144:147], v[188:191], v[108:111]
	v_mfma_f32_16x16x32_bf16 v[104:107], v[164:167], v[188:191], v[104:107]
	v_mfma_f32_16x16x32_bf16 v[100:103], v[144:147], v[196:199], v[100:103]
	v_mfma_f32_16x16x32_bf16 v[96:99], v[164:167], v[196:199], v[96:99]
	s_barrier
	ds_read_b128 v[200:203], v163
	ds_read_b128 v[218:221], v163 offset:1024
	ds_read_b128 v[222:225], v163 offset:2048
	ds_read_b128 v[226:229], v163 offset:3072
	s_waitcnt vmcnt(0)
	s_barrier
	s_waitcnt lgkmcnt(0)
	s_waitcnt lgkmcnt(0)
	v_mfma_f32_16x16x32_bf16 v[92:95], v[200:203], v[168:171], v[92:95]
	v_mfma_f32_16x16x32_bf16 v[88:91], v[222:225], v[168:171], v[88:91]
	v_mfma_f32_16x16x32_bf16 v[84:87], v[200:203], v[176:179], v[84:87]
	v_mfma_f32_16x16x32_bf16 v[80:83], v[222:225], v[176:179], v[80:83]
	v_mfma_f32_16x16x32_bf16 v[76:79], v[200:203], v[184:187], v[76:79]
	v_mfma_f32_16x16x32_bf16 v[72:75], v[222:225], v[184:187], v[72:75]
	v_mfma_f32_16x16x32_bf16 v[68:71], v[200:203], v[192:195], v[68:71]
	v_mfma_f32_16x16x32_bf16 v[64:67], v[222:225], v[192:195], v[64:67]
	v_mfma_f32_16x16x32_bf16 v[92:95], v[218:221], v[172:175], v[92:95]
	v_mfma_f32_16x16x32_bf16 v[88:91], v[226:229], v[172:175], v[88:91]
	v_mfma_f32_16x16x32_bf16 v[84:87], v[218:221], v[180:183], v[84:87]
	v_mfma_f32_16x16x32_bf16 v[80:83], v[226:229], v[180:183], v[80:83]
	v_mfma_f32_16x16x32_bf16 v[76:79], v[218:221], v[188:191], v[76:79]
	v_mfma_f32_16x16x32_bf16 v[72:75], v[226:229], v[188:191], v[72:75]
	v_mfma_f32_16x16x32_bf16 v[68:71], v[218:221], v[196:199], v[68:71]
	v_mfma_f32_16x16x32_bf16 v[64:67], v[226:229], v[196:199], v[64:67]
	s_barrier
	ds_read_b128 v[168:171], v162 offset:49152
	ds_read_b128 v[172:175], v162 offset:50176
	ds_read_b128 v[176:179], v161 offset:49152
	ds_read_b128 v[180:183], v161 offset:50176
	ds_read_b128 v[184:187], v160 offset:49152
	ds_read_b128 v[160:163], v160 offset:50176
	ds_read_b128 v[188:191], v159 offset:49152
	ds_read_b128 v[156:159], v159 offset:50176
	s_barrier
	s_waitcnt lgkmcnt(0)
	s_waitcnt lgkmcnt(0)
	v_mfma_f32_16x16x32_bf16 v[60:63], v[140:143], v[168:171], v[60:63]
	v_mfma_f32_16x16x32_bf16 v[56:59], v[148:151], v[168:171], v[56:59]
	v_mfma_f32_16x16x32_bf16 v[52:55], v[140:143], v[176:179], v[52:55]
	v_mfma_f32_16x16x32_bf16 v[48:51], v[148:151], v[176:179], v[48:51]
	v_mfma_f32_16x16x32_bf16 v[44:47], v[140:143], v[184:187], v[44:47]
	v_mfma_f32_16x16x32_bf16 v[40:43], v[148:151], v[184:187], v[40:43]
	v_mfma_f32_16x16x32_bf16 v[36:39], v[140:143], v[188:191], v[36:39]
	v_mfma_f32_16x16x32_bf16 v[32:35], v[148:151], v[188:191], v[32:35]
	v_mfma_f32_16x16x32_bf16 v[60:63], v[144:147], v[172:175], v[60:63]
	v_mfma_f32_16x16x32_bf16 v[56:59], v[164:167], v[172:175], v[56:59]
	v_mfma_f32_16x16x32_bf16 v[52:55], v[144:147], v[180:183], v[52:55]
	v_mfma_f32_16x16x32_bf16 v[48:51], v[164:167], v[180:183], v[48:51]
	v_mfma_f32_16x16x32_bf16 v[44:47], v[144:147], v[160:163], v[44:47]
	v_mfma_f32_16x16x32_bf16 v[40:43], v[164:167], v[160:163], v[40:43]
	v_mfma_f32_16x16x32_bf16 v[36:39], v[144:147], v[156:159], v[36:39]
	v_mfma_f32_16x16x32_bf16 v[32:35], v[164:167], v[156:159], v[32:35]
	v_mfma_f32_16x16x32_bf16 v[28:31], v[200:203], v[168:171], v[28:31]
	v_mfma_f32_16x16x32_bf16 v[24:27], v[222:225], v[168:171], v[24:27]
	v_mfma_f32_16x16x32_bf16 v[20:23], v[200:203], v[176:179], v[20:23]
	v_mfma_f32_16x16x32_bf16 v[16:19], v[222:225], v[176:179], v[16:19]
	v_mfma_f32_16x16x32_bf16 v[12:15], v[200:203], v[184:187], v[12:15]
	v_mfma_f32_16x16x32_bf16 v[8:11], v[222:225], v[184:187], v[8:11]
	v_mfma_f32_16x16x32_bf16 v[4:7], v[200:203], v[188:191], v[4:7]
	v_mfma_f32_16x16x32_bf16 v[0:3], v[222:225], v[188:191], v[0:3]
	v_mfma_f32_16x16x32_bf16 v[28:31], v[218:221], v[172:175], v[28:31]
	v_mfma_f32_16x16x32_bf16 v[24:27], v[226:229], v[172:175], v[24:27]
	v_mfma_f32_16x16x32_bf16 v[20:23], v[218:221], v[180:183], v[20:23]
	v_mfma_f32_16x16x32_bf16 v[16:19], v[226:229], v[180:183], v[16:19]
	v_mfma_f32_16x16x32_bf16 v[12:15], v[218:221], v[160:163], v[12:15]
	v_mfma_f32_16x16x32_bf16 v[8:11], v[226:229], v[160:163], v[8:11]
	v_mfma_f32_16x16x32_bf16 v[4:7], v[218:221], v[156:159], v[4:7]
	v_mfma_f32_16x16x32_bf16 v[0:3], v[226:229], v[156:159], v[0:3]
	s_movk_i32 s15, 0x100
	v_cmp_gt_u32_e32 vcc, s15, v129
	s_barrier
	s_and_saveexec_b64 s[50:51], vcc
	s_cbranch_execz .LBB0_239
	s_barrier

; #define STAGE(P, BASE, br, kt) STAGET(tid_, P, BASE, br, kt)
; #define LDA(dst, b, h) UFOR(m, 4) UFOR(k, 2) \
;     dst[m][k] = *reinterpret_cast<const bf16x8*>((char*)SA(b, h) + lds_byte(wr * 64 + m * 16 + fr, k * 32 + fq * 8))
; #define LDB(dst, b, h) UFOR(n, 2) UFOR(k, 2) \
;     dst[n][k] = *reinterpret_cast<const bf16x8*>((char*)SB(b, h) + lds_byte(wc * 32 + n * 16 + fr, k * 32 + fq * 8))
; #define MMA(ai, bj, At, Bq) do { __builtin_amdgcn_s_setprio(1); \
;     UFOR(m, 4) UFOR(n, 2) UFOR(k, 2) \
;       acc[ai][bj][m][n] = __builtin_amdgcn_mfma_f32_16x16x32_bf16(Bq[n][k], At[m][k], acc[ai][bj][m][n], 0, 0, 0); \
;     __builtin_amdgcn_s_setprio(0); } while (0)
; #define WAIT_L(n) asm volatile("s_waitcnt lgkmcnt(" #n ")" ::: "memory")
; #define BAR __builtin_amdgcn_s_barrier()
; #define SCHED __builtin_amdgcn_sched_barrier(0)
; template <int EPI, int K, int KL> ...
;     ...
;     LDB(B0, 0, 0); SCHED; LDA(At, 0, 0); STAGE(SA(1, 1), A, brow + HALF, t + 1);
;     WAIT_L(8); BAR; WAIT_L(0); MMA(0, 0, At, B0); BAR; SCHED;
;     LDB(B1, 0, 1); STAGE(SB(0, 0), Bt, bcol, t + 2);
;     BAR; WAIT_L(0); MMA(0, 1, At, B1); BAR;
;     LDA(At, 0, 1); STAGE(SA(0, 0), A, brow, t + 2);
;     BAR; WAIT_L(0); MMA(1, 0, At, B0); BAR; SCHED;
.LBB0_940:
	ds_read_b128 v[174:177], v170
	ds_read_b128 v[178:181], v170 offset:1024
	ds_read_b128 v[182:185], v170 offset:2048
	ds_read_b128 v[186:189], v170 offset:3072
	v_add_u32_e32 v171, 0xc000, v157
	v_lshl_add_u64 v[136:137], s[92:93], 0, v[148:149]
	v_readfirstlane_b32 s60, v171
	v_lshl_add_u64 v[138:139], v[136:137], 0, s[88:89]
	s_mov_b32 m0, s60
	v_add_u32_e32 v172, 0xe000, v157
	ds_read_b128 v[190:193], v162
	ds_read_b128 v[194:197], v162 offset:1024
	ds_read_b128 v[198:201], v161
	ds_read_b128 v[202:205], v161 offset:1024
	ds_read_b128 v[218:221], v160
	ds_read_b128 v[222:225], v160 offset:1024
	ds_read_b128 v[226:229], v159
	ds_read_b128 v[230:233], v159 offset:1024
	global_load_lds_dwordx4 v[138:139], off
	v_lshl_add_u64 v[138:139], s[92:93], 0, v[150:151]
	v_readfirstlane_b32 s60, v172
	v_lshl_add_u64 v[208:209], v[138:139], 0, s[88:89]
	s_mov_b32 m0, s60
	s_nop 0
	global_load_lds_dwordx4 v[208:209], off
	s_waitcnt lgkmcnt(8)
	s_barrier
	s_waitcnt lgkmcnt(0)
	s_waitcnt lgkmcnt(0)
	v_mfma_f32_16x16x32_bf16 v[124:127], v[174:177], v[190:193], v[124:127]
	v_mfma_f32_16x16x32_bf16 v[120:123], v[182:185], v[190:193], v[120:123]
	v_mfma_f32_16x16x32_bf16 v[116:119], v[174:177], v[198:201], v[116:119]
	v_mfma_f32_16x16x32_bf16 v[112:115], v[182:185], v[198:201], v[112:115]
	v_mfma_f32_16x16x32_bf16 v[108:111], v[174:177], v[218:221], v[108:111]
	v_mfma_f32_16x16x32_bf16 v[104:107], v[182:185], v[218:221], v[104:107]
	v_mfma_f32_16x16x32_bf16 v[100:103], v[174:177], v[226:229], v[100:103]
	v_mfma_f32_16x16x32_bf16 v[96:99], v[182:185], v[226:229], v[96:99]
	v_mfma_f32_16x16x32_bf16 v[124:127], v[178:181], v[194:197], v[124:127]
	v_mfma_f32_16x16x32_bf16 v[120:123], v[186:189], v[194:197], v[120:123]
	v_mfma_f32_16x16x32_bf16 v[116:119], v[178:181], v[202:205], v[116:119]
	v_mfma_f32_16x16x32_bf16 v[112:115], v[186:189], v[202:205], v[112:115]
	v_mfma_f32_16x16x32_bf16 v[108:111], v[178:181], v[222:225], v[108:111]
	v_mfma_f32_16x16x32_bf16 v[104:107], v[186:189], v[222:225], v[104:107]
	v_mfma_f32_16x16x32_bf16 v[100:103], v[178:181], v[230:233], v[100:103]
	v_mfma_f32_16x16x32_bf16 v[96:99], v[186:189], v[230:233], v[96:99]
	s_barrier
	v_lshl_add_u64 v[208:209], s[92:93], 0, v[144:145]
	v_readfirstlane_b32 s60, v156
	v_lshl_add_u64 v[210:211], v[208:209], 0, s[62:63]
	s_mov_b32 m0, s60
	v_add_u32_e32 v134, 0x2000, v156
	ds_read_b128 v[234:237], v168
	ds_read_b128 v[238:241], v168 offset:1024
	ds_read_b128 v[242:245], v168 offset:2048
	ds_read_b128 v[246:249], v168 offset:3072
	global_load_lds_dwordx4 v[210:211], off
	v_lshl_add_u64 v[210:211], s[92:93], 0, v[146:147]
	v_readfirstlane_b32 s60, v134
	v_lshl_add_u64 v[214:215], v[210:211], 0, s[62:63]
	s_mov_b32 m0, s60
	s_nop 0
	global_load_lds_dwordx4 v[214:215], off
	s_barrier
	s_waitcnt lgkmcnt(0)
	s_waitcnt lgkmcnt(0)
	v_mfma_f32_16x16x32_bf16 v[92:95], v[234:237], v[190:193], v[92:95]
	v_mfma_f32_16x16x32_bf16 v[88:91], v[242:245], v[190:193], v[88:91]
	v_mfma_f32_16x16x32_bf16 v[84:87], v[234:237], v[198:201], v[84:87]
	v_mfma_f32_16x16x32_bf16 v[80:83], v[242:245], v[198:201], v[80:83]
	v_mfma_f32_16x16x32_bf16 v[76:79], v[234:237], v[218:221], v[76:79]
	v_mfma_f32_16x16x32_bf16 v[72:75], v[242:245], v[218:221], v[72:75]
	v_mfma_f32_16x16x32_bf16 v[68:71], v[234:237], v[226:229], v[68:71]
	v_mfma_f32_16x16x32_bf16 v[64:67], v[242:245], v[226:229], v[64:67]
	v_mfma_f32_16x16x32_bf16 v[92:95], v[238:241], v[194:197], v[92:95]
	v_mfma_f32_16x16x32_bf16 v[88:91], v[246:249], v[194:197], v[88:91]
	v_mfma_f32_16x16x32_bf16 v[84:87], v[238:241], v[202:205], v[84:87]
	v_mfma_f32_16x16x32_bf16 v[80:83], v[246:249], v[202:205], v[80:83]
	v_mfma_f32_16x16x32_bf16 v[76:79], v[238:241], v[222:225], v[76:79]
	v_mfma_f32_16x16x32_bf16 v[72:75], v[246:249], v[222:225], v[72:75]
	v_mfma_f32_16x16x32_bf16 v[68:71], v[238:241], v[230:233], v[68:71]
	v_mfma_f32_16x16x32_bf16 v[64:67], v[246:249], v[230:233], v[64:67]
	v_readfirstlane_b32 s60, v157
	v_add_u32_e32 v134, 0x2000, v157
	v_lshl_add_u64 v[214:215], v[136:137], 0, s[8:9]
	s_mov_b32 m0, s60
	v_readfirstlane_b32 s60, v134
	s_barrier
	ds_read_b128 v[190:193], v162 offset:16384
	ds_read_b128 v[194:197], v162 offset:17408
	ds_read_b128 v[198:201], v161 offset:16384
	ds_read_b128 v[202:205], v161 offset:17408
	ds_read_b128 v[218:221], v160 offset:16384
	ds_read_b128 v[222:225], v160 offset:17408
	ds_read_b128 v[226:229], v159 offset:16384
	ds_read_b128 v[230:233], v159 offset:17408
	global_load_lds_dwordx4 v[214:215], off
	v_lshl_add_u64 v[214:215], v[138:139], 0, s[8:9]
	s_mov_b32 m0, s60
	s_nop 0
	global_load_lds_dwordx4 v[214:215], off
	s_barrier
	s_waitcnt lgkmcnt(0)
	s_waitcnt lgkmcnt(0)
	v_mfma_f32_16x16x32_bf16 v[60:63], v[174:177], v[190:193], v[60:63]
	v_mfma_f32_16x16x32_bf16 v[56:59], v[182:185], v[190:193], v[56:59]
	v_mfma_f32_16x16x32_bf16 v[52:55], v[174:177], v[198:201], v[52:55]
	v_mfma_f32_16x16x32_bf16 v[48:51], v[182:185], v[198:201], v[48:51]
	v_mfma_f32_16x16x32_bf16 v[44:47], v[174:177], v[218:221], v[44:47]
	v_mfma_f32_16x16x32_bf16 v[40:43], v[182:185], v[218:221], v[40:43]
	v_mfma_f32_16x16x32_bf16 v[36:39], v[174:177], v[226:229], v[36:39]
	v_mfma_f32_16x16x32_bf16 v[32:35], v[182:185], v[226:229], v[32:35]
	v_mfma_f32_16x16x32_bf16 v[60:63], v[178:181], v[194:197], v[60:63]
	v_mfma_f32_16x16x32_bf16 v[56:59], v[186:189], v[194:197], v[56:59]
	v_mfma_f32_16x16x32_bf16 v[52:55], v[178:181], v[202:205], v[52:55]
	v_mfma_f32_16x16x32_bf16 v[48:51], v[186:189], v[202:205], v[48:51]
	v_mfma_f32_16x16x32_bf16 v[44:47], v[178:181], v[222:225], v[44:47]
	v_mfma_f32_16x16x32_bf16 v[40:43], v[186:189], v[222:225], v[40:43]
	v_mfma_f32_16x16x32_bf16 v[36:39], v[178:181], v[230:233], v[36:39]
	v_mfma_f32_16x16x32_bf16 v[32:35], v[186:189], v[230:233], v[32:35]
	s_barrier
; #define STAGE(P, BASE, br, kt) STAGET(tid_, P, BASE, br, kt)
; #define LDA(dst, b, h) UFOR(m, 4) UFOR(k, 2) \
;     dst[m][k] = *reinterpret_cast<const bf16x8*>((char*)SA(b, h) + lds_byte(wr * 64 + m * 16 + fr, k * 32 + fq * 8))
; #define LDB(dst, b, h) UFOR(n, 2) UFOR(k, 2) \
;     dst[n][k] = *reinterpret_cast<const bf16x8*>((char*)SB(b, h) + lds_byte(wc * 32 + n * 16 + fr, k * 32 + fq * 8))
; #define MMA(ai, bj, At, Bq) do { __builtin_amdgcn_s_setprio(1); \
;     UFOR(m, 4) UFOR(n, 2) UFOR(k, 2) \
;       acc[ai][bj][m][n] = __builtin_amdgcn_mfma_f32_16x16x32_bf16(Bq[n][k], At[m][k], acc[ai][bj][m][n], 0, 0, 0); \
;     __builtin_amdgcn_s_setprio(0); } while (0)
; #define WAIT_V(n) asm volatile("s_waitcnt vmcnt(" #n ")" ::: "memory")
; #define WAIT_L(n) asm volatile("s_waitcnt lgkmcnt(" #n ")" ::: "memory")
; #define BAR __builtin_amdgcn_s_barrier()
; #define SCHED __builtin_amdgcn_sched_barrier(0)
; template <int EPI, int K, int KL> ...
;     ...
;     STAGE(SB(0, 1), Bt, bcol + HALF, t + 2);
;     WAIT_V(6); BAR; MMA(1, 1, At, B1); BAR;
;     LDB(B0, 1, 0); SCHED; LDA(At, 1, 0); STAGE(SA(0, 1), A, brow + HALF, t + 2);
;     WAIT_L(8); BAR; WAIT_L(0); MMA(0, 0, At, B0); BAR; SCHED;
;     LDB(B1, 1, 1); STAGE(SB(1, 0), Bt, bcol, t + 3);
;     BAR; WAIT_L(0); MMA(0, 1, At, B1); BAR;
;     LDA(At, 1, 1); STAGE(SA(1, 0), A, brow, t + 3);
	v_readfirstlane_b32 s60, v158
	v_add_u32_e32 v134, 0x2000, v158
	v_lshl_add_u64 v[174:175], v[208:209], 0, s[66:67]
	s_mov_b32 m0, s60
	v_readfirstlane_b32 s60, v134
	global_load_lds_dwordx4 v[174:175], off
	v_lshl_add_u64 v[174:175], v[210:211], 0, s[66:67]
	s_mov_b32 m0, s60
	s_nop 0
	global_load_lds_dwordx4 v[174:175], off
	s_waitcnt vmcnt(6)
	s_barrier
	v_mfma_f32_16x16x32_bf16 v[28:31], v[234:237], v[190:193], v[28:31]
	v_mfma_f32_16x16x32_bf16 v[24:27], v[242:245], v[190:193], v[24:27]
	v_mfma_f32_16x16x32_bf16 v[20:23], v[234:237], v[198:201], v[20:23]
	v_mfma_f32_16x16x32_bf16 v[16:19], v[242:245], v[198:201], v[16:19]
	v_mfma_f32_16x16x32_bf16 v[12:15], v[234:237], v[218:221], v[12:15]
	v_mfma_f32_16x16x32_bf16 v[8:11], v[242:245], v[218:221], v[8:11]
	v_mfma_f32_16x16x32_bf16 v[4:7], v[234:237], v[226:229], v[4:7]
	v_mfma_f32_16x16x32_bf16 v[0:3], v[242:245], v[226:229], v[0:3]
	v_mfma_f32_16x16x32_bf16 v[28:31], v[238:241], v[194:197], v[28:31]
	v_mfma_f32_16x16x32_bf16 v[24:27], v[246:249], v[194:197], v[24:27]
	v_mfma_f32_16x16x32_bf16 v[20:23], v[238:241], v[202:205], v[20:23]
	v_mfma_f32_16x16x32_bf16 v[16:19], v[246:249], v[202:205], v[16:19]
	v_mfma_f32_16x16x32_bf16 v[12:15], v[238:241], v[222:225], v[12:15]
	v_mfma_f32_16x16x32_bf16 v[8:11], v[246:249], v[222:225], v[8:11]
	v_mfma_f32_16x16x32_bf16 v[4:7], v[238:241], v[230:233], v[4:7]
	v_mfma_f32_16x16x32_bf16 v[0:3], v[246:249], v[230:233], v[0:3]
	s_barrier
	ds_read_b128 v[174:177], v165
	ds_read_b128 v[178:181], v165 offset:1024
	ds_read_b128 v[182:185], v165 offset:2048
	ds_read_b128 v[186:189], v165 offset:3072
	v_add_u32_e32 v134, 0x4000, v157
	v_lshl_add_u64 v[214:215], v[136:137], 0, s[12:13]
	v_readfirstlane_b32 s60, v134
	v_add_u32_e32 v134, 0x6000, v157
	s_mov_b32 m0, s60
	v_readfirstlane_b32 s60, v134
	ds_read_b128 v[190:193], v162 offset:32768
	ds_read_b128 v[194:197], v162 offset:33792
	ds_read_b128 v[198:201], v161 offset:32768
	ds_read_b128 v[202:205], v161 offset:33792
	ds_read_b128 v[218:221], v160 offset:32768
	ds_read_b128 v[222:225], v160 offset:33792
	ds_read_b128 v[226:229], v159 offset:32768
	ds_read_b128 v[230:233], v159 offset:33792
	global_load_lds_dwordx4 v[214:215], off
	v_lshl_add_u64 v[214:215], v[138:139], 0, s[12:13]
	s_mov_b32 m0, s60
	s_nop 0
	global_load_lds_dwordx4 v[214:215], off
	s_waitcnt lgkmcnt(8)
	s_barrier
	s_waitcnt lgkmcnt(0)
	s_waitcnt lgkmcnt(0)
	v_mfma_f32_16x16x32_bf16 v[124:127], v[174:177], v[190:193], v[124:127]
	v_mfma_f32_16x16x32_bf16 v[120:123], v[182:185], v[190:193], v[120:123]
	v_mfma_f32_16x16x32_bf16 v[116:119], v[174:177], v[198:201], v[116:119]
	v_mfma_f32_16x16x32_bf16 v[112:115], v[182:185], v[198:201], v[112:115]
	v_mfma_f32_16x16x32_bf16 v[108:111], v[174:177], v[218:221], v[108:111]
	v_mfma_f32_16x16x32_bf16 v[104:107], v[182:185], v[218:221], v[104:107]
	v_mfma_f32_16x16x32_bf16 v[100:103], v[174:177], v[226:229], v[100:103]
	v_mfma_f32_16x16x32_bf16 v[96:99], v[182:185], v[226:229], v[96:99]
	v_mfma_f32_16x16x32_bf16 v[124:127], v[178:181], v[194:197], v[124:127]
	v_mfma_f32_16x16x32_bf16 v[120:123], v[186:189], v[194:197], v[120:123]
	v_mfma_f32_16x16x32_bf16 v[116:119], v[178:181], v[202:205], v[116:119]
	v_mfma_f32_16x16x32_bf16 v[112:115], v[186:189], v[202:205], v[112:115]
	v_mfma_f32_16x16x32_bf16 v[108:111], v[178:181], v[222:225], v[108:111]
	v_mfma_f32_16x16x32_bf16 v[104:107], v[186:189], v[222:225], v[104:107]
	v_mfma_f32_16x16x32_bf16 v[100:103], v[178:181], v[230:233], v[100:103]
	v_mfma_f32_16x16x32_bf16 v[96:99], v[186:189], v[230:233], v[96:99]
	s_barrier
	v_readfirstlane_b32 s60, v164
	v_add_u32_e32 v134, 0x2000, v164
	v_lshl_add_u64 v[214:215], v[208:209], 0, s[70:71]
	s_mov_b32 m0, s60
	v_readfirstlane_b32 s60, v134
	ds_read_b128 v[234:237], v163
	ds_read_b128 v[238:241], v163 offset:1024
	ds_read_b128 v[242:245], v163 offset:2048
	ds_read_b128 v[246:249], v163 offset:3072
	global_load_lds_dwordx4 v[214:215], off
	v_lshl_add_u64 v[214:215], v[210:211], 0, s[70:71]
	s_mov_b32 m0, s60
	s_nop 0
	global_load_lds_dwordx4 v[214:215], off
	s_barrier
	s_waitcnt lgkmcnt(0)
	s_waitcnt lgkmcnt(0)
	v_mfma_f32_16x16x32_bf16 v[92:95], v[234:237], v[190:193], v[92:95]
	v_mfma_f32_16x16x32_bf16 v[88:91], v[242:245], v[190:193], v[88:91]
	v_mfma_f32_16x16x32_bf16 v[84:87], v[234:237], v[198:201], v[84:87]
	v_mfma_f32_16x16x32_bf16 v[80:83], v[242:245], v[198:201], v[80:83]
	v_mfma_f32_16x16x32_bf16 v[76:79], v[234:237], v[218:221], v[76:79]
	v_mfma_f32_16x16x32_bf16 v[72:75], v[242:245], v[218:221], v[72:75]
	v_mfma_f32_16x16x32_bf16 v[68:71], v[234:237], v[226:229], v[68:71]
	v_mfma_f32_16x16x32_bf16 v[64:67], v[242:245], v[226:229], v[64:67]
	v_mfma_f32_16x16x32_bf16 v[92:95], v[238:241], v[194:197], v[92:95]
	v_mfma_f32_16x16x32_bf16 v[88:91], v[246:249], v[194:197], v[88:91]
	v_mfma_f32_16x16x32_bf16 v[84:87], v[238:241], v[202:205], v[84:87]
	v_mfma_f32_16x16x32_bf16 v[80:83], v[246:249], v[202:205], v[80:83]
	v_mfma_f32_16x16x32_bf16 v[76:79], v[238:241], v[222:225], v[76:79]
	v_mfma_f32_16x16x32_bf16 v[72:75], v[246:249], v[222:225], v[72:75]
	v_mfma_f32_16x16x32_bf16 v[68:71], v[238:241], v[230:233], v[68:71]
	v_mfma_f32_16x16x32_bf16 v[64:67], v[246:249], v[230:233], v[64:67]
	v_readfirstlane_b32 s60, v166
	v_lshl_add_u64 v[136:137], v[136:137], 0, s[16:17]
	s_mov_b32 m0, s60
	v_readfirstlane_b32 s60, v167
	s_barrier
	ds_read_b128 v[190:193], v162 offset:49152
	ds_read_b128 v[194:197], v162 offset:50176
	ds_read_b128 v[198:201], v161 offset:49152
	ds_read_b128 v[202:205], v161 offset:50176
	ds_read_b128 v[218:221], v160 offset:49152
	ds_read_b128 v[222:225], v160 offset:50176
	ds_read_b128 v[226:229], v159 offset:49152
	ds_read_b128 v[230:233], v159 offset:50176
	global_load_lds_dwordx4 v[136:137], off
	v_lshl_add_u64 v[136:137], v[138:139], 0, s[16:17]
	s_mov_b32 m0, s60
	s_nop 0
	global_load_lds_dwordx4 v[136:137], off
	s_barrier
; #define STAGE(P, BASE, br, kt) STAGET(tid_, P, BASE, br, kt)
; #define LDA(dst, b, h) UFOR(m, 4) UFOR(k, 2) \
;     dst[m][k] = *reinterpret_cast<const bf16x8*>((char*)SA(b, h) + lds_byte(wr * 64 + m * 16 + fr, k * 32 + fq * 8))
; #define LDB(dst, b, h) UFOR(n, 2) UFOR(k, 2) \
;     dst[n][k] = *reinterpret_cast<const bf16x8*>((char*)SB(b, h) + lds_byte(wc * 32 + n * 16 + fr, k * 32 + fq * 8))
; #define MMA(ai, bj, At, Bq) do { __builtin_amdgcn_s_setprio(1); \
;     UFOR(m, 4) UFOR(n, 2) UFOR(k, 2) \
;       acc[ai][bj][m][n] = __builtin_amdgcn_mfma_f32_16x16x32_bf16(Bq[n][k], At[m][k], acc[ai][bj][m][n], 0, 0, 0); \
;     __builtin_amdgcn_s_setprio(0); } while (0)
; #define WAIT_V(n) asm volatile("s_waitcnt vmcnt(" #n ")" ::: "memory")
; #define WAIT_L(n) asm volatile("s_waitcnt lgkmcnt(" #n ")" ::: "memory")
; #define BAR __builtin_amdgcn_s_barrier()
; #define SCHED __builtin_amdgcn_sched_barrier(0)
; template <int EPI, int K, int KL> ...
;     ...
;     BAR; WAIT_L(0); MMA(1, 0, At, B0); BAR; SCHED;
;     STAGE(SB(1, 1), Bt, bcol + HALF, t + 3);
;     WAIT_V(6); BAR; MMA(1, 1, At, B1); BAR;
;   }
;   { LDB(B0, 0, 0); LDA(At, 0, 0); STAGE(SA(1, 1), A, brow + HALF, nt - 1);
;     BAR; WAIT_L(0); MMA(0, 0, At, B0); BAR;
	s_waitcnt lgkmcnt(0)
	s_waitcnt lgkmcnt(0)
	v_mfma_f32_16x16x32_bf16 v[60:63], v[174:177], v[190:193], v[60:63]
	v_mfma_f32_16x16x32_bf16 v[56:59], v[182:185], v[190:193], v[56:59]
	v_mfma_f32_16x16x32_bf16 v[52:55], v[174:177], v[198:201], v[52:55]
	v_mfma_f32_16x16x32_bf16 v[48:51], v[182:185], v[198:201], v[48:51]
	v_mfma_f32_16x16x32_bf16 v[44:47], v[174:177], v[218:221], v[44:47]
	v_mfma_f32_16x16x32_bf16 v[40:43], v[182:185], v[218:221], v[40:43]
	v_mfma_f32_16x16x32_bf16 v[36:39], v[174:177], v[226:229], v[36:39]
	v_mfma_f32_16x16x32_bf16 v[32:35], v[182:185], v[226:229], v[32:35]
	v_mfma_f32_16x16x32_bf16 v[60:63], v[178:181], v[194:197], v[60:63]
	v_mfma_f32_16x16x32_bf16 v[56:59], v[186:189], v[194:197], v[56:59]
	v_mfma_f32_16x16x32_bf16 v[52:55], v[178:181], v[202:205], v[52:55]
	v_mfma_f32_16x16x32_bf16 v[48:51], v[186:189], v[202:205], v[48:51]
	v_mfma_f32_16x16x32_bf16 v[44:47], v[178:181], v[222:225], v[44:47]
	v_mfma_f32_16x16x32_bf16 v[40:43], v[186:189], v[222:225], v[40:43]
	v_mfma_f32_16x16x32_bf16 v[36:39], v[178:181], v[230:233], v[36:39]
	v_mfma_f32_16x16x32_bf16 v[32:35], v[186:189], v[230:233], v[32:35]
	s_barrier
	v_readfirstlane_b32 s60, v169
	v_add_u32_e32 v134, 0x2000, v169
	v_lshl_add_u64 v[136:137], v[208:209], 0, s[74:75]
	s_mov_b32 m0, s60
	v_readfirstlane_b32 s60, v134
	global_load_lds_dwordx4 v[136:137], off
	v_lshl_add_u64 v[136:137], v[210:211], 0, s[74:75]
	s_mov_b32 m0, s60
	s_nop 0
	global_load_lds_dwordx4 v[136:137], off
	s_waitcnt vmcnt(6)
	s_barrier
	v_mfma_f32_16x16x32_bf16 v[28:31], v[234:237], v[190:193], v[28:31]
	v_mfma_f32_16x16x32_bf16 v[24:27], v[242:245], v[190:193], v[24:27]
	v_mfma_f32_16x16x32_bf16 v[20:23], v[234:237], v[198:201], v[20:23]
	v_mfma_f32_16x16x32_bf16 v[16:19], v[242:245], v[198:201], v[16:19]
	v_mfma_f32_16x16x32_bf16 v[12:15], v[234:237], v[218:221], v[12:15]
	v_mfma_f32_16x16x32_bf16 v[8:11], v[242:245], v[218:221], v[8:11]
	v_mfma_f32_16x16x32_bf16 v[4:7], v[234:237], v[226:229], v[4:7]
	v_mfma_f32_16x16x32_bf16 v[0:3], v[242:245], v[226:229], v[0:3]
	v_mfma_f32_16x16x32_bf16 v[28:31], v[238:241], v[194:197], v[28:31]
	v_mfma_f32_16x16x32_bf16 v[24:27], v[246:249], v[194:197], v[24:27]
	v_mfma_f32_16x16x32_bf16 v[20:23], v[238:241], v[202:205], v[20:23]
	v_mfma_f32_16x16x32_bf16 v[16:19], v[246:249], v[202:205], v[16:19]
	v_mfma_f32_16x16x32_bf16 v[12:15], v[238:241], v[222:225], v[12:15]
	v_mfma_f32_16x16x32_bf16 v[8:11], v[246:249], v[222:225], v[8:11]
	v_mfma_f32_16x16x32_bf16 v[4:7], v[238:241], v[230:233], v[4:7]
	v_mfma_f32_16x16x32_bf16 v[0:3], v[246:249], v[230:233], v[0:3]
	s_add_i32 s55, s55, 2
	v_lshl_add_u64 v[144:145], v[144:145], 0, s[20:21]
	v_lshl_add_u64 v[146:147], v[146:147], 0, s[20:21]
	v_lshl_add_u64 v[148:149], v[148:149], 0, s[20:21]
	s_cmp_lt_u32 s55, 28
	v_lshl_add_u64 v[150:151], v[150:151], 0, s[20:21]
	s_barrier
	s_cbranch_scc1 .LBB0_940
	s_add_u32 s58, s58, 0x80f80
	s_addc_u32 s59, s59, 0
	v_lshl_add_u64 v[130:131], s[58:59], 0, v[130:131]
	v_readfirstlane_b32 s55, v171
	v_lshl_add_u64 v[128:129], v[128:129], 1, v[130:131]
	s_mov_b32 m0, s55
	ds_read_b128 v[144:147], v170
	ds_read_b128 v[148:151], v170 offset:1024
	ds_read_b128 v[174:177], v170 offset:2048
	ds_read_b128 v[178:181], v170 offset:3072
	ds_read_b128 v[182:185], v162
	ds_read_b128 v[186:189], v162 offset:1024
	ds_read_b128 v[190:193], v161
	ds_read_b128 v[194:197], v161 offset:1024
	ds_read_b128 v[198:201], v160
	ds_read_b128 v[202:205], v160 offset:1024
	ds_read_b128 v[218:221], v159
	ds_read_b128 v[222:225], v159 offset:1024
	global_load_lds_dwordx4 v[128:129], off
	v_lshl_add_u64 v[128:129], s[58:59], 0, v[142:143]
	v_readfirstlane_b32 s55, v172
	v_lshl_add_u64 v[128:129], v[140:141], 1, v[128:129]
	s_mov_b32 m0, s55
	s_nop 0
	global_load_lds_dwordx4 v[128:129], off
	s_barrier
	s_waitcnt lgkmcnt(0)
	s_waitcnt lgkmcnt(0)
	v_mfma_f32_16x16x32_bf16 v[124:127], v[144:147], v[182:185], v[124:127]
	v_mfma_f32_16x16x32_bf16 v[120:123], v[174:177], v[182:185], v[120:123]
	v_mfma_f32_16x16x32_bf16 v[116:119], v[144:147], v[190:193], v[116:119]
	v_mfma_f32_16x16x32_bf16 v[112:115], v[174:177], v[190:193], v[112:115]
	v_mfma_f32_16x16x32_bf16 v[108:111], v[144:147], v[198:201], v[108:111]
	v_mfma_f32_16x16x32_bf16 v[104:107], v[174:177], v[198:201], v[104:107]
	v_mfma_f32_16x16x32_bf16 v[100:103], v[144:147], v[218:221], v[100:103]
	v_mfma_f32_16x16x32_bf16 v[96:99], v[174:177], v[218:221], v[96:99]
	v_mfma_f32_16x16x32_bf16 v[124:127], v[148:151], v[186:189], v[124:127]
	v_mfma_f32_16x16x32_bf16 v[120:123], v[178:181], v[186:189], v[120:123]
	v_mfma_f32_16x16x32_bf16 v[116:119], v[148:151], v[194:197], v[116:119]
	v_mfma_f32_16x16x32_bf16 v[112:115], v[178:181], v[194:197], v[112:115]
	v_mfma_f32_16x16x32_bf16 v[108:111], v[148:151], v[202:205], v[108:111]
	v_mfma_f32_16x16x32_bf16 v[104:107], v[178:181], v[202:205], v[104:107]
	v_mfma_f32_16x16x32_bf16 v[100:103], v[148:151], v[222:225], v[100:103]
	v_mfma_f32_16x16x32_bf16 v[96:99], v[178:181], v[222:225], v[96:99]
	s_barrier
	ds_read_b128 v[128:131], v168
	ds_read_b128 v[140:143], v168 offset:1024
	ds_read_b128 v[170:173], v168 offset:2048
	ds_read_b128 v[166:169], v168 offset:3072
	s_barrier
; #define LDA(dst, b, h) UFOR(m, 4) UFOR(k, 2) \
;     dst[m][k] = *reinterpret_cast<const bf16x8*>((char*)SA(b, h) + lds_byte(wr * 64 + m * 16 + fr, k * 32 + fq * 8))
; #define LDB(dst, b, h) UFOR(n, 2) UFOR(k, 2) \
;     dst[n][k] = *reinterpret_cast<const bf16x8*>((char*)SB(b, h) + lds_byte(wc * 32 + n * 16 + fr, k * 32 + fq * 8))
; #define MMA(ai, bj, At, Bq) do { __builtin_amdgcn_s_setprio(1); \
;     UFOR(m, 4) UFOR(n, 2) UFOR(k, 2) \
;       acc[ai][bj][m][n] = __builtin_amdgcn_mfma_f32_16x16x32_bf16(Bq[n][k], At[m][k], acc[ai][bj][m][n], 0, 0, 0); \
;     __builtin_amdgcn_s_setprio(0); } while (0)
; #define WAIT_V(n) asm volatile("s_waitcnt vmcnt(" #n ")" ::: "memory")
; #define WAIT_L(n) asm volatile("s_waitcnt lgkmcnt(" #n ")" ::: "memory")
; #define BAR __builtin_amdgcn_s_barrier()
; template <int EPI, int K, int KL> ...
;     ...
;     BAR; WAIT_L(0); MMA(0, 0, At, B0); BAR;
;     LDB(B1, 0, 1); BAR; WAIT_L(0); MMA(0, 1, At, B1); BAR;
;     LDA(At, 0, 1); WAIT_V(4); BAR; WAIT_L(0); MMA(1, 0, At, B0); MMA(1, 1, At, B1); BAR; }
;   { LDB(B0, 1, 0); LDA(At, 1, 0); WAIT_V(2); BAR; WAIT_L(0); MMA(0, 0, At, B0); BAR;
;     LDB(B1, 1, 1); WAIT_V(0); BAR; WAIT_L(0); MMA(0, 1, At, B1); BAR;
	s_waitcnt lgkmcnt(0)
	s_waitcnt lgkmcnt(0)
	v_mfma_f32_16x16x32_bf16 v[80:83], v[170:173], v[190:193], v[80:83]
	v_mfma_f32_16x16x32_bf16 v[72:75], v[170:173], v[198:201], v[72:75]
	v_mfma_f32_16x16x32_bf16 v[68:71], v[128:131], v[218:221], v[68:71]
	v_mfma_f32_16x16x32_bf16 v[64:67], v[170:173], v[218:221], v[64:67]
	v_mfma_f32_16x16x32_bf16 v[92:95], v[128:131], v[182:185], v[92:95]
	v_mfma_f32_16x16x32_bf16 v[88:91], v[170:173], v[182:185], v[88:91]
	v_mfma_f32_16x16x32_bf16 v[84:87], v[128:131], v[190:193], v[84:87]
	v_mfma_f32_16x16x32_bf16 v[80:83], v[166:169], v[194:197], v[80:83]
	v_mfma_f32_16x16x32_bf16 v[76:79], v[128:131], v[198:201], v[76:79]
	v_mfma_f32_16x16x32_bf16 v[72:75], v[166:169], v[202:205], v[72:75]
	v_mfma_f32_16x16x32_bf16 v[68:71], v[140:143], v[222:225], v[68:71]
	v_mfma_f32_16x16x32_bf16 v[64:67], v[166:169], v[222:225], v[64:67]
	v_mfma_f32_16x16x32_bf16 v[226:229], v[140:143], v[186:189], v[92:95]
	v_mfma_f32_16x16x32_bf16 v[182:185], v[166:169], v[186:189], v[88:91]
	v_mfma_f32_16x16x32_bf16 v[186:189], v[140:143], v[194:197], v[84:87]
	v_mfma_f32_16x16x32_bf16 v[190:193], v[140:143], v[202:205], v[76:79]
	s_barrier
	s_nop 0
	ds_read_b128 v[76:79], v162 offset:16384
	ds_read_b128 v[84:87], v162 offset:17408
	ds_read_b128 v[88:91], v161 offset:16384
	ds_read_b128 v[92:95], v161 offset:17408
	ds_read_b128 v[194:197], v160 offset:16384
	ds_read_b128 v[198:201], v160 offset:17408
	ds_read_b128 v[202:205], v159 offset:16384
	ds_read_b128 v[218:221], v159 offset:17408
	s_waitcnt vmcnt(4)
	s_barrier
	s_waitcnt lgkmcnt(0)
	s_waitcnt lgkmcnt(0)
	v_mfma_f32_16x16x32_bf16 v[48:51], v[174:177], v[88:91], v[48:51]
	v_mfma_f32_16x16x32_bf16 v[40:43], v[174:177], v[194:197], v[40:43]
	v_mfma_f32_16x16x32_bf16 v[36:39], v[144:147], v[202:205], v[36:39]
	v_mfma_f32_16x16x32_bf16 v[32:35], v[174:177], v[202:205], v[32:35]
	v_mfma_f32_16x16x32_bf16 v[60:63], v[144:147], v[76:79], v[60:63]
	v_mfma_f32_16x16x32_bf16 v[56:59], v[174:177], v[76:79], v[56:59]
	v_mfma_f32_16x16x32_bf16 v[52:55], v[144:147], v[88:91], v[52:55]
	v_mfma_f32_16x16x32_bf16 v[48:51], v[178:181], v[92:95], v[48:51]
	v_mfma_f32_16x16x32_bf16 v[44:47], v[144:147], v[194:197], v[44:47]
	v_mfma_f32_16x16x32_bf16 v[40:43], v[178:181], v[198:201], v[40:43]
	v_mfma_f32_16x16x32_bf16 v[36:39], v[148:151], v[218:221], v[36:39]
	v_mfma_f32_16x16x32_bf16 v[32:35], v[178:181], v[218:221], v[32:35]
	v_mfma_f32_16x16x32_bf16 v[222:225], v[148:151], v[84:87], v[60:63]
	v_mfma_f32_16x16x32_bf16 v[230:233], v[178:181], v[84:87], v[56:59]
	v_mfma_f32_16x16x32_bf16 v[234:237], v[148:151], v[92:95], v[52:55]
	v_mfma_f32_16x16x32_bf16 v[238:241], v[148:151], v[198:201], v[44:47]
	v_mfma_f32_16x16x32_bf16 v[0:3], v[170:173], v[202:205], v[0:3]
	v_mfma_f32_16x16x32_bf16 v[28:31], v[128:131], v[76:79], v[28:31]
	v_mfma_f32_16x16x32_bf16 v[24:27], v[170:173], v[76:79], v[24:27]
	v_mfma_f32_16x16x32_bf16 v[20:23], v[128:131], v[88:91], v[20:23]
	v_mfma_f32_16x16x32_bf16 v[16:19], v[170:173], v[88:91], v[16:19]
	v_mfma_f32_16x16x32_bf16 v[12:15], v[128:131], v[194:197], v[12:15]
	v_mfma_f32_16x16x32_bf16 v[8:11], v[170:173], v[194:197], v[8:11]
	v_mfma_f32_16x16x32_bf16 v[4:7], v[128:131], v[202:205], v[4:7]
	v_mfma_f32_16x16x32_bf16 v[0:3], v[166:169], v[218:221], v[0:3]
	v_mfma_f32_16x16x32_bf16 v[144:147], v[140:143], v[84:87], v[28:31]
	v_mfma_f32_16x16x32_bf16 v[148:151], v[166:169], v[84:87], v[24:27]
	v_mfma_f32_16x16x32_bf16 v[174:177], v[140:143], v[92:95], v[20:23]
	v_mfma_f32_16x16x32_bf16 v[178:181], v[166:169], v[92:95], v[16:19]
	v_mfma_f32_16x16x32_bf16 v[242:245], v[140:143], v[198:201], v[12:15]
	v_mfma_f32_16x16x32_bf16 v[194:197], v[166:169], v[198:201], v[8:11]
	v_mfma_f32_16x16x32_bf16 v[128:131], v[140:143], v[218:221], v[4:7]
	s_barrier
	s_nop 0
	ds_read_b128 v[4:7], v165
	ds_read_b128 v[8:11], v165 offset:1024
	ds_read_b128 v[16:19], v165 offset:2048
	ds_read_b128 v[140:143], v165 offset:3072
	ds_read_b128 v[12:15], v162 offset:32768
	ds_read_b128 v[20:23], v162 offset:33792
	ds_read_b128 v[24:27], v161 offset:32768
	ds_read_b128 v[44:47], v161 offset:33792
	ds_read_b128 v[164:167], v160 offset:32768
	ds_read_b128 v[168:171], v160 offset:33792
	ds_read_b128 v[198:201], v159 offset:32768
	ds_read_b128 v[202:205], v159 offset:33792
	s_waitcnt vmcnt(2)
	s_barrier
; #define LDA(dst, b, h) UFOR(m, 4) UFOR(k, 2) \
;     dst[m][k] = *reinterpret_cast<const bf16x8*>((char*)SA(b, h) + lds_byte(wr * 64 + m * 16 + fr, k * 32 + fq * 8))
; #define LDB(dst, b, h) UFOR(n, 2) UFOR(k, 2) \
;     dst[n][k] = *reinterpret_cast<const bf16x8*>((char*)SB(b, h) + lds_byte(wc * 32 + n * 16 + fr, k * 32 + fq * 8))
; #define MMA(ai, bj, At, Bq) do { __builtin_amdgcn_s_setprio(1); \
;     UFOR(m, 4) UFOR(n, 2) UFOR(k, 2) \
;       acc[ai][bj][m][n] = __builtin_amdgcn_mfma_f32_16x16x32_bf16(Bq[n][k], At[m][k], acc[ai][bj][m][n], 0, 0, 0); \
;     __builtin_amdgcn_s_setprio(0); } while (0)
; #define WAIT_V(n) asm volatile("s_waitcnt vmcnt(" #n ")" ::: "memory")
; #define WAIT_L(n) asm volatile("s_waitcnt lgkmcnt(" #n ")" ::: "memory")
; #define BAR __builtin_amdgcn_s_barrier()
; template <int EPI, int K, int KL> ...
;     ...
;   { LDB(B0, 1, 0); LDA(At, 1, 0); WAIT_V(2); BAR; WAIT_L(0); MMA(0, 0, At, B0); BAR;
;     LDB(B1, 1, 1); WAIT_V(0); BAR; WAIT_L(0); MMA(0, 1, At, B1); BAR;
;     LDA(At, 1, 1); BAR; WAIT_L(0); MMA(1, 0, At, B0); MMA(1, 1, At, B1); BAR; }
;   if (wr == 0) BAR;
	s_waitcnt lgkmcnt(0)
	s_waitcnt lgkmcnt(0)
	v_mfma_f32_16x16x32_bf16 v[28:31], v[4:7], v[12:15], v[124:127]
	v_mfma_f32_16x16x32_bf16 v[124:127], v[8:11], v[20:23], v[28:31]
	v_mfma_f32_16x16x32_bf16 v[28:31], v[16:19], v[12:15], v[120:123]
	v_mfma_f32_16x16x32_bf16 v[92:95], v[140:143], v[20:23], v[28:31]
	v_mfma_f32_16x16x32_bf16 v[28:31], v[4:7], v[24:27], v[116:119]
	v_mfma_f32_16x16x32_bf16 v[120:123], v[8:11], v[44:47], v[28:31]
	v_mfma_f32_16x16x32_bf16 v[28:31], v[16:19], v[24:27], v[112:115]
	v_mfma_f32_16x16x32_bf16 v[88:91], v[140:143], v[44:47], v[28:31]
	v_mfma_f32_16x16x32_bf16 v[28:31], v[4:7], v[164:167], v[108:111]
	v_mfma_f32_16x16x32_bf16 v[116:119], v[8:11], v[168:171], v[28:31]
	v_mfma_f32_16x16x32_bf16 v[28:31], v[16:19], v[164:167], v[104:107]
	v_mfma_f32_16x16x32_bf16 v[84:87], v[140:143], v[168:171], v[28:31]
	v_mfma_f32_16x16x32_bf16 v[28:31], v[4:7], v[198:201], v[100:103]
	v_mfma_f32_16x16x32_bf16 v[108:111], v[8:11], v[202:205], v[28:31]
	v_mfma_f32_16x16x32_bf16 v[28:31], v[16:19], v[198:201], v[96:99]
	v_mfma_f32_16x16x32_bf16 v[76:79], v[140:143], v[202:205], v[28:31]
	s_barrier
	ds_read_b128 v[218:221], v163
	ds_read_b128 v[246:249], v163 offset:1024
	ds_read_b128 v[136:139], v163 offset:2048
	ds_read_b128 v[208:211], v163 offset:3072
	s_waitcnt vmcnt(0)
	s_barrier
	s_waitcnt lgkmcnt(0)
	s_waitcnt lgkmcnt(0)
	v_mfma_f32_16x16x32_bf16 v[28:31], v[218:221], v[12:15], v[226:229]
	v_mfma_f32_16x16x32_bf16 v[12:15], v[136:139], v[12:15], v[182:185]
	v_mfma_f32_16x16x32_bf16 v[60:63], v[246:249], v[20:23], v[28:31]
	v_mfma_f32_16x16x32_bf16 v[28:31], v[208:211], v[20:23], v[12:15]
	v_mfma_f32_16x16x32_bf16 v[12:15], v[218:221], v[24:27], v[186:189]
	v_mfma_f32_16x16x32_bf16 v[56:59], v[246:249], v[44:47], v[12:15]
	v_mfma_f32_16x16x32_bf16 v[12:15], v[136:139], v[24:27], v[80:83]
	v_mfma_f32_16x16x32_bf16 v[24:27], v[208:211], v[44:47], v[12:15]
	v_mfma_f32_16x16x32_bf16 v[12:15], v[218:221], v[164:167], v[190:193]
	v_mfma_f32_16x16x32_bf16 v[52:55], v[246:249], v[168:171], v[12:15]
	v_mfma_f32_16x16x32_bf16 v[12:15], v[136:139], v[164:167], v[72:75]
	v_mfma_f32_16x16x32_bf16 v[20:23], v[208:211], v[168:171], v[12:15]
	v_mfma_f32_16x16x32_bf16 v[12:15], v[218:221], v[198:201], v[68:71]
	v_mfma_f32_16x16x32_bf16 v[44:47], v[246:249], v[202:205], v[12:15]
	v_mfma_f32_16x16x32_bf16 v[12:15], v[136:139], v[198:201], v[64:67]
	v_mfma_f32_16x16x32_bf16 v[12:15], v[208:211], v[202:205], v[12:15]
	s_barrier
	ds_read_b128 v[164:167], v162 offset:49152
	ds_read_b128 v[168:171], v162 offset:50176
	ds_read_b128 v[182:185], v161 offset:49152
	ds_read_b128 v[186:189], v161 offset:50176
	ds_read_b128 v[190:193], v160 offset:49152
	ds_read_b128 v[160:163], v160 offset:50176
	ds_read_b128 v[198:201], v159 offset:49152
	ds_read_b128 v[156:159], v159 offset:50176
	s_barrier
	s_waitcnt lgkmcnt(0)
	s_waitcnt lgkmcnt(0)
	v_mfma_f32_16x16x32_bf16 v[64:67], v[4:7], v[164:167], v[222:225]
	v_mfma_f32_16x16x32_bf16 v[112:115], v[8:11], v[168:171], v[64:67]
	v_mfma_f32_16x16x32_bf16 v[64:67], v[16:19], v[164:167], v[230:233]
	v_mfma_f32_16x16x32_bf16 v[48:51], v[16:19], v[182:185], v[48:51]
	v_mfma_f32_16x16x32_bf16 v[80:83], v[140:143], v[168:171], v[64:67]
	v_mfma_f32_16x16x32_bf16 v[64:67], v[4:7], v[182:185], v[234:237]
	v_mfma_f32_16x16x32_bf16 v[72:75], v[140:143], v[186:189], v[48:51]
	v_mfma_f32_16x16x32_bf16 v[48:51], v[4:7], v[190:193], v[238:241]
	v_mfma_f32_16x16x32_bf16 v[4:7], v[4:7], v[198:201], v[36:39]
	v_mfma_f32_16x16x32_bf16 v[40:43], v[16:19], v[190:193], v[40:43]
	v_mfma_f32_16x16x32_bf16 v[96:99], v[8:11], v[156:159], v[4:7]
	v_mfma_f32_16x16x32_bf16 v[4:7], v[16:19], v[198:201], v[32:35]
	v_mfma_f32_16x16x32_bf16 v[104:107], v[8:11], v[186:189], v[64:67]
	v_mfma_f32_16x16x32_bf16 v[100:103], v[8:11], v[160:163], v[48:51]
	v_mfma_f32_16x16x32_bf16 v[68:71], v[140:143], v[160:163], v[40:43]
	v_mfma_f32_16x16x32_bf16 v[64:67], v[140:143], v[156:159], v[4:7]
	v_mfma_f32_16x16x32_bf16 v[4:7], v[218:221], v[164:167], v[144:147]
	v_mfma_f32_16x16x32_bf16 v[48:51], v[246:249], v[168:171], v[4:7]
	v_mfma_f32_16x16x32_bf16 v[4:7], v[136:139], v[164:167], v[148:151]
	v_mfma_f32_16x16x32_bf16 v[16:19], v[208:211], v[168:171], v[4:7]
	v_mfma_f32_16x16x32_bf16 v[4:7], v[218:221], v[182:185], v[174:177]
	v_mfma_f32_16x16x32_bf16 v[40:43], v[246:249], v[186:189], v[4:7]
	v_mfma_f32_16x16x32_bf16 v[4:7], v[136:139], v[182:185], v[178:181]
	v_mfma_f32_16x16x32_bf16 v[8:11], v[208:211], v[186:189], v[4:7]
	v_mfma_f32_16x16x32_bf16 v[4:7], v[218:221], v[190:193], v[242:245]
	v_mfma_f32_16x16x32_bf16 v[36:39], v[246:249], v[160:163], v[4:7]
	v_mfma_f32_16x16x32_bf16 v[4:7], v[136:139], v[190:193], v[194:197]
	v_mfma_f32_16x16x32_bf16 v[32:35], v[218:221], v[198:201], v[128:131]
	v_mfma_f32_16x16x32_bf16 v[0:3], v[136:139], v[198:201], v[0:3]
	v_mfma_f32_16x16x32_bf16 v[4:7], v[208:211], v[160:163], v[4:7]
	v_mfma_f32_16x16x32_bf16 v[32:35], v[246:249], v[156:159], v[32:35]
	v_mfma_f32_16x16x32_bf16 v[0:3], v[208:211], v[156:159], v[0:3]
	s_movk_i32 s55, 0x100
	v_cmp_gt_u32_e32 vcc, s55, v154
	s_barrier
	s_and_saveexec_b64 s[58:59], vcc
	s_cbranch_execz .LBB0_943
	s_barrier

; #define STAGE(P, BASE, br, kt) STAGET(tid_, P, BASE, br, kt)
; #define LDA(dst, b, h) UFOR(m, 4) UFOR(k, 2) \
;     dst[m][k] = *reinterpret_cast<const bf16x8*>((char*)SA(b, h) + lds_byte(wr * 64 + m * 16 + fr, k * 32 + fq * 8))
; #define LDB(dst, b, h) UFOR(n, 2) UFOR(k, 2) \
;     dst[n][k] = *reinterpret_cast<const bf16x8*>((char*)SB(b, h) + lds_byte(wc * 32 + n * 16 + fr, k * 32 + fq * 8))
; #define MMA(ai, bj, At, Bq) do { __builtin_amdgcn_s_setprio(1); \
;     UFOR(m, 4) UFOR(n, 2) UFOR(k, 2) \
;       acc[ai][bj][m][n] = __builtin_amdgcn_mfma_f32_16x16x32_bf16(Bq[n][k], At[m][k], acc[ai][bj][m][n], 0, 0, 0); \
;     __builtin_amdgcn_s_setprio(0); } while (0)
; #define WAIT_L(n) asm volatile("s_waitcnt lgkmcnt(" #n ")" ::: "memory")
; #define BAR __builtin_amdgcn_s_barrier()
; #define SCHED __builtin_amdgcn_sched_barrier(0)
; template <int EPI, int K, int KL> ...
;     ...
;     LDB(B0, 0, 0); SCHED; LDA(At, 0, 0); STAGE(SA(1, 1), A, brow + HALF, t + 1);
;     WAIT_L(8); BAR; WAIT_L(0); MMA(0, 0, At, B0); BAR; SCHED;
;     LDB(B1, 0, 1); STAGE(SB(0, 0), Bt, bcol, t + 2);
;     BAR; WAIT_L(0); MMA(0, 1, At, B1); BAR;
;     LDA(At, 0, 1); STAGE(SA(0, 0), A, brow, t + 2);
;     BAR; WAIT_L(0); MMA(1, 0, At, B0); BAR; SCHED;
.LBB0_1107:
	ds_read_b128 v[136:139], v171
	ds_read_b128 v[174:177], v171 offset:1024
	ds_read_b128 v[178:181], v171 offset:2048
	ds_read_b128 v[182:185], v171 offset:3072
	v_add_u32_e32 v172, 0xc000, v158
	v_lshl_add_u64 v[214:215], s[92:93], 0, v[148:149]
	v_readfirstlane_b32 s56, v172
	v_lshl_add_u64 v[216:217], v[214:215], 0, s[88:89]
	s_mov_b32 m0, s56
	v_add_u32_e32 v173, 0xe000, v158
	ds_read_b128 v[186:189], v163
	ds_read_b128 v[190:193], v163 offset:1024
	ds_read_b128 v[194:197], v162
	ds_read_b128 v[198:201], v162 offset:1024
	ds_read_b128 v[202:205], v161
	ds_read_b128 v[208:211], v161 offset:1024
	ds_read_b128 v[218:221], v160
	ds_read_b128 v[222:225], v160 offset:1024
	global_load_lds_dwordx4 v[216:217], off
	v_lshl_add_u64 v[216:217], s[92:93], 0, v[150:151]
	v_readfirstlane_b32 s56, v173
	v_lshl_add_u64 v[226:227], v[216:217], 0, s[88:89]
	s_mov_b32 m0, s56
	s_nop 0
	global_load_lds_dwordx4 v[226:227], off
	s_waitcnt lgkmcnt(8)
	s_barrier
	s_waitcnt lgkmcnt(0)
	s_waitcnt lgkmcnt(0)
	v_mfma_f32_16x16x32_bf16 v[0:3], v[136:139], v[186:189], v[0:3]
	v_mfma_f32_16x16x32_bf16 v[4:7], v[178:181], v[186:189], v[4:7]
	v_mfma_f32_16x16x32_bf16 v[8:11], v[136:139], v[194:197], v[8:11]
	v_mfma_f32_16x16x32_bf16 v[16:19], v[178:181], v[194:197], v[16:19]
	v_mfma_f32_16x16x32_bf16 v[28:31], v[136:139], v[202:205], v[28:31]
	v_mfma_f32_16x16x32_bf16 v[40:43], v[178:181], v[202:205], v[40:43]
	v_mfma_f32_16x16x32_bf16 v[52:55], v[136:139], v[218:221], v[52:55]
	v_mfma_f32_16x16x32_bf16 v[64:67], v[178:181], v[218:221], v[64:67]
	v_mfma_f32_16x16x32_bf16 v[0:3], v[174:177], v[190:193], v[0:3]
	v_mfma_f32_16x16x32_bf16 v[4:7], v[182:185], v[190:193], v[4:7]
	v_mfma_f32_16x16x32_bf16 v[8:11], v[174:177], v[198:201], v[8:11]
	v_mfma_f32_16x16x32_bf16 v[16:19], v[182:185], v[198:201], v[16:19]
	v_mfma_f32_16x16x32_bf16 v[28:31], v[174:177], v[208:211], v[28:31]
	v_mfma_f32_16x16x32_bf16 v[40:43], v[182:185], v[208:211], v[40:43]
	v_mfma_f32_16x16x32_bf16 v[52:55], v[174:177], v[222:225], v[52:55]
	v_mfma_f32_16x16x32_bf16 v[64:67], v[182:185], v[222:225], v[64:67]
	s_barrier
	v_lshl_add_u64 v[242:243], s[92:93], 0, v[144:145]
	v_readfirstlane_b32 s56, v157
	v_lshl_add_u64 v[244:245], v[242:243], 0, s[2:3]
	s_mov_b32 m0, s56
	v_add_u32_e32 v134, 0x2000, v157
	ds_read_b128 v[226:229], v169
	ds_read_b128 v[230:233], v169 offset:1024
	ds_read_b128 v[234:237], v169 offset:2048
	ds_read_b128 v[238:241], v169 offset:3072
	global_load_lds_dwordx4 v[244:245], off
	v_lshl_add_u64 v[244:245], s[92:93], 0, v[146:147]
	v_readfirstlane_b32 s56, v134
	v_lshl_add_u64 v[246:247], v[244:245], 0, s[2:3]
	s_mov_b32 m0, s56
	s_nop 0
	global_load_lds_dwordx4 v[246:247], off
	s_barrier
	s_waitcnt lgkmcnt(0)
	s_waitcnt lgkmcnt(0)
	v_mfma_f32_16x16x32_bf16 v[12:15], v[226:229], v[186:189], v[12:15]
	v_mfma_f32_16x16x32_bf16 v[24:27], v[234:237], v[186:189], v[24:27]
	v_mfma_f32_16x16x32_bf16 v[36:39], v[226:229], v[194:197], v[36:39]
	v_mfma_f32_16x16x32_bf16 v[48:51], v[234:237], v[194:197], v[48:51]
	v_mfma_f32_16x16x32_bf16 v[60:63], v[226:229], v[202:205], v[60:63]
	v_mfma_f32_16x16x32_bf16 v[72:75], v[234:237], v[202:205], v[72:75]
	v_mfma_f32_16x16x32_bf16 v[80:83], v[226:229], v[218:221], v[80:83]
	v_mfma_f32_16x16x32_bf16 v[88:91], v[234:237], v[218:221], v[88:91]
	v_mfma_f32_16x16x32_bf16 v[12:15], v[230:233], v[190:193], v[12:15]
	v_mfma_f32_16x16x32_bf16 v[24:27], v[238:241], v[190:193], v[24:27]
	v_mfma_f32_16x16x32_bf16 v[36:39], v[230:233], v[198:201], v[36:39]
	v_mfma_f32_16x16x32_bf16 v[48:51], v[238:241], v[198:201], v[48:51]
	v_mfma_f32_16x16x32_bf16 v[60:63], v[230:233], v[208:211], v[60:63]
	v_mfma_f32_16x16x32_bf16 v[72:75], v[238:241], v[208:211], v[72:75]
	v_mfma_f32_16x16x32_bf16 v[80:83], v[230:233], v[222:225], v[80:83]
	v_mfma_f32_16x16x32_bf16 v[88:91], v[238:241], v[222:225], v[88:91]
	v_readfirstlane_b32 s56, v158
	v_add_u32_e32 v134, 0x2000, v158
	v_lshl_add_u64 v[246:247], v[214:215], 0, s[8:9]
	s_mov_b32 m0, s56
	v_readfirstlane_b32 s56, v134
	s_barrier
	ds_read_b128 v[186:189], v163 offset:16384
	ds_read_b128 v[190:193], v163 offset:17408
	ds_read_b128 v[194:197], v162 offset:16384
	ds_read_b128 v[198:201], v162 offset:17408
	ds_read_b128 v[202:205], v161 offset:16384
	ds_read_b128 v[208:211], v161 offset:17408
	ds_read_b128 v[218:221], v160 offset:16384
	ds_read_b128 v[222:225], v160 offset:17408
	global_load_lds_dwordx4 v[246:247], off
	v_lshl_add_u64 v[246:247], v[216:217], 0, s[8:9]
	s_mov_b32 m0, s56
	s_nop 0
	global_load_lds_dwordx4 v[246:247], off
	s_barrier
	s_waitcnt lgkmcnt(0)
	s_waitcnt lgkmcnt(0)
	v_mfma_f32_16x16x32_bf16 v[20:23], v[136:139], v[186:189], v[20:23]
	v_mfma_f32_16x16x32_bf16 v[32:35], v[178:181], v[186:189], v[32:35]
	v_mfma_f32_16x16x32_bf16 v[44:47], v[136:139], v[194:197], v[44:47]
	v_mfma_f32_16x16x32_bf16 v[56:59], v[178:181], v[194:197], v[56:59]
	v_mfma_f32_16x16x32_bf16 v[68:71], v[136:139], v[202:205], v[68:71]
	v_mfma_f32_16x16x32_bf16 v[76:79], v[178:181], v[202:205], v[76:79]
	v_mfma_f32_16x16x32_bf16 v[84:87], v[136:139], v[218:221], v[84:87]
	v_mfma_f32_16x16x32_bf16 v[92:95], v[178:181], v[218:221], v[92:95]
	v_mfma_f32_16x16x32_bf16 v[20:23], v[174:177], v[190:193], v[20:23]
	v_mfma_f32_16x16x32_bf16 v[32:35], v[182:185], v[190:193], v[32:35]
	v_mfma_f32_16x16x32_bf16 v[44:47], v[174:177], v[198:201], v[44:47]
	v_mfma_f32_16x16x32_bf16 v[56:59], v[182:185], v[198:201], v[56:59]
	v_mfma_f32_16x16x32_bf16 v[68:71], v[174:177], v[208:211], v[68:71]
	v_mfma_f32_16x16x32_bf16 v[76:79], v[182:185], v[208:211], v[76:79]
	v_mfma_f32_16x16x32_bf16 v[84:87], v[174:177], v[222:225], v[84:87]
	v_mfma_f32_16x16x32_bf16 v[92:95], v[182:185], v[222:225], v[92:95]
	s_barrier
; #define STAGE(P, BASE, br, kt) STAGET(tid_, P, BASE, br, kt)
; #define LDA(dst, b, h) UFOR(m, 4) UFOR(k, 2) \
;     dst[m][k] = *reinterpret_cast<const bf16x8*>((char*)SA(b, h) + lds_byte(wr * 64 + m * 16 + fr, k * 32 + fq * 8))
; #define LDB(dst, b, h) UFOR(n, 2) UFOR(k, 2) \
;     dst[n][k] = *reinterpret_cast<const bf16x8*>((char*)SB(b, h) + lds_byte(wc * 32 + n * 16 + fr, k * 32 + fq * 8))
; #define MMA(ai, bj, At, Bq) do { __builtin_amdgcn_s_setprio(1); \
;     UFOR(m, 4) UFOR(n, 2) UFOR(k, 2) \
;       acc[ai][bj][m][n] = __builtin_amdgcn_mfma_f32_16x16x32_bf16(Bq[n][k], At[m][k], acc[ai][bj][m][n], 0, 0, 0); \
;     __builtin_amdgcn_s_setprio(0); } while (0)
; #define WAIT_V(n) asm volatile("s_waitcnt vmcnt(" #n ")" ::: "memory")
; #define WAIT_L(n) asm volatile("s_waitcnt lgkmcnt(" #n ")" ::: "memory")
; #define BAR __builtin_amdgcn_s_barrier()
; #define SCHED __builtin_amdgcn_sched_barrier(0)
; template <int EPI, int K, int KL> ...
;     ...
;     STAGE(SB(0, 1), Bt, bcol + HALF, t + 2);
;     WAIT_V(6); BAR; MMA(1, 1, At, B1); BAR;
;     LDB(B0, 1, 0); SCHED; LDA(At, 1, 0); STAGE(SA(0, 1), A, brow + HALF, t + 2);
;     WAIT_L(8); BAR; WAIT_L(0); MMA(0, 0, At, B0); BAR; SCHED;
;     LDB(B1, 1, 1); STAGE(SB(1, 0), Bt, bcol, t + 3);
;     BAR; WAIT_L(0); MMA(0, 1, At, B1); BAR;
;     LDA(At, 1, 1); STAGE(SA(1, 0), A, brow, t + 3);
	v_readfirstlane_b32 s56, v159
	v_add_u32_e32 v134, 0x2000, v159
	v_lshl_add_u64 v[136:137], v[242:243], 0, s[96:97]
	s_mov_b32 m0, s56
	v_readfirstlane_b32 s56, v134
	global_load_lds_dwordx4 v[136:137], off
	v_lshl_add_u64 v[136:137], v[244:245], 0, s[96:97]
	s_mov_b32 m0, s56
	s_nop 0
	global_load_lds_dwordx4 v[136:137], off
	s_waitcnt vmcnt(6)
	s_barrier
	v_mfma_f32_16x16x32_bf16 v[96:99], v[226:229], v[186:189], v[96:99]
	v_mfma_f32_16x16x32_bf16 v[100:103], v[234:237], v[186:189], v[100:103]
	v_mfma_f32_16x16x32_bf16 v[104:107], v[226:229], v[194:197], v[104:107]
	v_mfma_f32_16x16x32_bf16 v[108:111], v[234:237], v[194:197], v[108:111]
	v_mfma_f32_16x16x32_bf16 v[112:115], v[226:229], v[202:205], v[112:115]
	v_mfma_f32_16x16x32_bf16 v[116:119], v[234:237], v[202:205], v[116:119]
	v_mfma_f32_16x16x32_bf16 v[120:123], v[226:229], v[218:221], v[120:123]
	v_mfma_f32_16x16x32_bf16 v[124:127], v[234:237], v[218:221], v[124:127]
	v_mfma_f32_16x16x32_bf16 v[96:99], v[230:233], v[190:193], v[96:99]
	v_mfma_f32_16x16x32_bf16 v[100:103], v[238:241], v[190:193], v[100:103]
	v_mfma_f32_16x16x32_bf16 v[104:107], v[230:233], v[198:201], v[104:107]
	v_mfma_f32_16x16x32_bf16 v[108:111], v[238:241], v[198:201], v[108:111]
	v_mfma_f32_16x16x32_bf16 v[112:115], v[230:233], v[208:211], v[112:115]
	v_mfma_f32_16x16x32_bf16 v[116:119], v[238:241], v[208:211], v[116:119]
	v_mfma_f32_16x16x32_bf16 v[120:123], v[230:233], v[222:225], v[120:123]
	v_mfma_f32_16x16x32_bf16 v[124:127], v[238:241], v[222:225], v[124:127]
	s_barrier
	ds_read_b128 v[136:139], v166
	ds_read_b128 v[174:177], v166 offset:1024
	ds_read_b128 v[178:181], v166 offset:2048
	ds_read_b128 v[182:185], v166 offset:3072
	v_add_u32_e32 v134, 0x4000, v158
	v_lshl_add_u64 v[226:227], v[214:215], 0, s[12:13]
	v_readfirstlane_b32 s56, v134
	v_add_u32_e32 v134, 0x6000, v158
	s_mov_b32 m0, s56
	v_readfirstlane_b32 s56, v134
	ds_read_b128 v[186:189], v163 offset:32768
	ds_read_b128 v[190:193], v163 offset:33792
	ds_read_b128 v[194:197], v162 offset:32768
	ds_read_b128 v[198:201], v162 offset:33792
	ds_read_b128 v[202:205], v161 offset:32768
	ds_read_b128 v[208:211], v161 offset:33792
	ds_read_b128 v[218:221], v160 offset:32768
	ds_read_b128 v[222:225], v160 offset:33792
	global_load_lds_dwordx4 v[226:227], off
	v_lshl_add_u64 v[226:227], v[216:217], 0, s[12:13]
	s_mov_b32 m0, s56
	s_nop 0
	global_load_lds_dwordx4 v[226:227], off
	s_waitcnt lgkmcnt(8)
	s_barrier
	s_waitcnt lgkmcnt(0)
	s_waitcnt lgkmcnt(0)
	v_mfma_f32_16x16x32_bf16 v[0:3], v[136:139], v[186:189], v[0:3]
	v_mfma_f32_16x16x32_bf16 v[4:7], v[178:181], v[186:189], v[4:7]
	v_mfma_f32_16x16x32_bf16 v[8:11], v[136:139], v[194:197], v[8:11]
	v_mfma_f32_16x16x32_bf16 v[16:19], v[178:181], v[194:197], v[16:19]
	v_mfma_f32_16x16x32_bf16 v[28:31], v[136:139], v[202:205], v[28:31]
	v_mfma_f32_16x16x32_bf16 v[40:43], v[178:181], v[202:205], v[40:43]
	v_mfma_f32_16x16x32_bf16 v[52:55], v[136:139], v[218:221], v[52:55]
	v_mfma_f32_16x16x32_bf16 v[64:67], v[178:181], v[218:221], v[64:67]
	v_mfma_f32_16x16x32_bf16 v[0:3], v[174:177], v[190:193], v[0:3]
	v_mfma_f32_16x16x32_bf16 v[4:7], v[182:185], v[190:193], v[4:7]
	v_mfma_f32_16x16x32_bf16 v[8:11], v[174:177], v[198:201], v[8:11]
	v_mfma_f32_16x16x32_bf16 v[16:19], v[182:185], v[198:201], v[16:19]
	v_mfma_f32_16x16x32_bf16 v[28:31], v[174:177], v[208:211], v[28:31]
	v_mfma_f32_16x16x32_bf16 v[40:43], v[182:185], v[208:211], v[40:43]
	v_mfma_f32_16x16x32_bf16 v[52:55], v[174:177], v[222:225], v[52:55]
	v_mfma_f32_16x16x32_bf16 v[64:67], v[182:185], v[222:225], v[64:67]
	s_barrier
	v_readfirstlane_b32 s56, v165
	v_add_u32_e32 v134, 0x2000, v165
	v_lshl_add_u64 v[246:247], v[242:243], 0, s[80:81]
	s_mov_b32 m0, s56
	v_readfirstlane_b32 s56, v134
	ds_read_b128 v[226:229], v164
	ds_read_b128 v[230:233], v164 offset:1024
	ds_read_b128 v[234:237], v164 offset:2048
	ds_read_b128 v[238:241], v164 offset:3072
	global_load_lds_dwordx4 v[246:247], off
	v_lshl_add_u64 v[246:247], v[244:245], 0, s[80:81]
	s_mov_b32 m0, s56
	s_nop 0
	global_load_lds_dwordx4 v[246:247], off
	s_barrier
	s_waitcnt lgkmcnt(0)
	s_waitcnt lgkmcnt(0)
	v_mfma_f32_16x16x32_bf16 v[12:15], v[226:229], v[186:189], v[12:15]
	v_mfma_f32_16x16x32_bf16 v[24:27], v[234:237], v[186:189], v[24:27]
	v_mfma_f32_16x16x32_bf16 v[36:39], v[226:229], v[194:197], v[36:39]
	v_mfma_f32_16x16x32_bf16 v[48:51], v[234:237], v[194:197], v[48:51]
	v_mfma_f32_16x16x32_bf16 v[60:63], v[226:229], v[202:205], v[60:63]
	v_mfma_f32_16x16x32_bf16 v[72:75], v[234:237], v[202:205], v[72:75]
	v_mfma_f32_16x16x32_bf16 v[80:83], v[226:229], v[218:221], v[80:83]
	v_mfma_f32_16x16x32_bf16 v[88:91], v[234:237], v[218:221], v[88:91]
	v_mfma_f32_16x16x32_bf16 v[12:15], v[230:233], v[190:193], v[12:15]
	v_mfma_f32_16x16x32_bf16 v[24:27], v[238:241], v[190:193], v[24:27]
	v_mfma_f32_16x16x32_bf16 v[36:39], v[230:233], v[198:201], v[36:39]
	v_mfma_f32_16x16x32_bf16 v[48:51], v[238:241], v[198:201], v[48:51]
	v_mfma_f32_16x16x32_bf16 v[60:63], v[230:233], v[208:211], v[60:63]
	v_mfma_f32_16x16x32_bf16 v[72:75], v[238:241], v[208:211], v[72:75]
	v_mfma_f32_16x16x32_bf16 v[80:83], v[230:233], v[222:225], v[80:83]
	v_mfma_f32_16x16x32_bf16 v[88:91], v[238:241], v[222:225], v[88:91]
	v_readfirstlane_b32 s56, v167
	v_lshl_add_u64 v[214:215], v[214:215], 0, s[16:17]
	s_mov_b32 m0, s56
	v_readfirstlane_b32 s56, v168
	s_barrier
	ds_read_b128 v[186:189], v163 offset:49152
	ds_read_b128 v[190:193], v163 offset:50176
	ds_read_b128 v[194:197], v162 offset:49152
	ds_read_b128 v[198:201], v162 offset:50176
	ds_read_b128 v[202:205], v161 offset:49152
	ds_read_b128 v[208:211], v161 offset:50176
	ds_read_b128 v[218:221], v160 offset:49152
	ds_read_b128 v[222:225], v160 offset:50176
	global_load_lds_dwordx4 v[214:215], off
	v_lshl_add_u64 v[214:215], v[216:217], 0, s[16:17]
	s_mov_b32 m0, s56
	s_nop 0
	global_load_lds_dwordx4 v[214:215], off
	s_barrier
; #define STAGE(P, BASE, br, kt) STAGET(tid_, P, BASE, br, kt)
; #define LDA(dst, b, h) UFOR(m, 4) UFOR(k, 2) \
;     dst[m][k] = *reinterpret_cast<const bf16x8*>((char*)SA(b, h) + lds_byte(wr * 64 + m * 16 + fr, k * 32 + fq * 8))
; #define LDB(dst, b, h) UFOR(n, 2) UFOR(k, 2) \
;     dst[n][k] = *reinterpret_cast<const bf16x8*>((char*)SB(b, h) + lds_byte(wc * 32 + n * 16 + fr, k * 32 + fq * 8))
; #define MMA(ai, bj, At, Bq) do { __builtin_amdgcn_s_setprio(1); \
;     UFOR(m, 4) UFOR(n, 2) UFOR(k, 2) \
;       acc[ai][bj][m][n] = __builtin_amdgcn_mfma_f32_16x16x32_bf16(Bq[n][k], At[m][k], acc[ai][bj][m][n], 0, 0, 0); \
;     __builtin_amdgcn_s_setprio(0); } while (0)
; #define WAIT_V(n) asm volatile("s_waitcnt vmcnt(" #n ")" ::: "memory")
; #define WAIT_L(n) asm volatile("s_waitcnt lgkmcnt(" #n ")" ::: "memory")
; #define BAR __builtin_amdgcn_s_barrier()
; #define SCHED __builtin_amdgcn_sched_barrier(0)
; template <int EPI, int K, int KL> ...
;     ...
;     BAR; WAIT_L(0); MMA(1, 0, At, B0); BAR; SCHED;
;     STAGE(SB(1, 1), Bt, bcol + HALF, t + 3);
;     WAIT_V(6); BAR; MMA(1, 1, At, B1); BAR;
;   }
;   { LDB(B0, 0, 0); LDA(At, 0, 0); STAGE(SA(1, 1), A, brow + HALF, nt - 1);
;     BAR; WAIT_L(0); MMA(0, 0, At, B0); BAR;
	s_waitcnt lgkmcnt(0)
	s_waitcnt lgkmcnt(0)
	v_mfma_f32_16x16x32_bf16 v[20:23], v[136:139], v[186:189], v[20:23]
	v_mfma_f32_16x16x32_bf16 v[32:35], v[178:181], v[186:189], v[32:35]
	v_mfma_f32_16x16x32_bf16 v[44:47], v[136:139], v[194:197], v[44:47]
	v_mfma_f32_16x16x32_bf16 v[56:59], v[178:181], v[194:197], v[56:59]
	v_mfma_f32_16x16x32_bf16 v[68:71], v[136:139], v[202:205], v[68:71]
	v_mfma_f32_16x16x32_bf16 v[76:79], v[178:181], v[202:205], v[76:79]
	v_mfma_f32_16x16x32_bf16 v[84:87], v[136:139], v[218:221], v[84:87]
	v_mfma_f32_16x16x32_bf16 v[92:95], v[178:181], v[218:221], v[92:95]
	v_mfma_f32_16x16x32_bf16 v[20:23], v[174:177], v[190:193], v[20:23]
	v_mfma_f32_16x16x32_bf16 v[32:35], v[182:185], v[190:193], v[32:35]
	v_mfma_f32_16x16x32_bf16 v[44:47], v[174:177], v[198:201], v[44:47]
	v_mfma_f32_16x16x32_bf16 v[56:59], v[182:185], v[198:201], v[56:59]
	v_mfma_f32_16x16x32_bf16 v[68:71], v[174:177], v[208:211], v[68:71]
	v_mfma_f32_16x16x32_bf16 v[76:79], v[182:185], v[208:211], v[76:79]
	v_mfma_f32_16x16x32_bf16 v[84:87], v[174:177], v[222:225], v[84:87]
	v_mfma_f32_16x16x32_bf16 v[92:95], v[182:185], v[222:225], v[92:95]
	s_barrier
	v_readfirstlane_b32 s56, v170
	v_add_u32_e32 v134, 0x2000, v170
	v_lshl_add_u64 v[136:137], v[242:243], 0, s[90:91]
	s_mov_b32 m0, s56
	v_readfirstlane_b32 s56, v134
	global_load_lds_dwordx4 v[136:137], off
	v_lshl_add_u64 v[136:137], v[244:245], 0, s[90:91]
	s_mov_b32 m0, s56
	s_nop 0
	global_load_lds_dwordx4 v[136:137], off
	s_waitcnt vmcnt(6)
	s_barrier
	v_mfma_f32_16x16x32_bf16 v[96:99], v[226:229], v[186:189], v[96:99]
	v_mfma_f32_16x16x32_bf16 v[100:103], v[234:237], v[186:189], v[100:103]
	v_mfma_f32_16x16x32_bf16 v[104:107], v[226:229], v[194:197], v[104:107]
	v_mfma_f32_16x16x32_bf16 v[108:111], v[234:237], v[194:197], v[108:111]
	v_mfma_f32_16x16x32_bf16 v[112:115], v[226:229], v[202:205], v[112:115]
	v_mfma_f32_16x16x32_bf16 v[116:119], v[234:237], v[202:205], v[116:119]
	v_mfma_f32_16x16x32_bf16 v[120:123], v[226:229], v[218:221], v[120:123]
	v_mfma_f32_16x16x32_bf16 v[124:127], v[234:237], v[218:221], v[124:127]
	v_mfma_f32_16x16x32_bf16 v[96:99], v[230:233], v[190:193], v[96:99]
	v_mfma_f32_16x16x32_bf16 v[100:103], v[238:241], v[190:193], v[100:103]
	v_mfma_f32_16x16x32_bf16 v[104:107], v[230:233], v[198:201], v[104:107]
	v_mfma_f32_16x16x32_bf16 v[108:111], v[238:241], v[198:201], v[108:111]
	v_mfma_f32_16x16x32_bf16 v[112:115], v[230:233], v[208:211], v[112:115]
	v_mfma_f32_16x16x32_bf16 v[116:119], v[238:241], v[208:211], v[116:119]
	v_mfma_f32_16x16x32_bf16 v[120:123], v[230:233], v[222:225], v[120:123]
	v_mfma_f32_16x16x32_bf16 v[124:127], v[238:241], v[222:225], v[124:127]
	s_add_i32 s53, s53, 2
	v_lshl_add_u64 v[144:145], v[144:145], 0, s[20:21]
	v_lshl_add_u64 v[146:147], v[146:147], 0, s[20:21]
	v_lshl_add_u64 v[148:149], v[148:149], 0, s[20:21]
	s_cmp_lt_u32 s53, 28
	v_lshl_add_u64 v[150:151], v[150:151], 0, s[20:21]
	s_barrier
	s_cbranch_scc1 .LBB0_1107
	s_add_u32 s40, s40, 0x80f80
	s_addc_u32 s41, s41, 0
	v_lshl_add_u64 v[130:131], s[40:41], 0, v[130:131]
	v_readfirstlane_b32 s53, v172
	v_lshl_add_u64 v[128:129], v[128:129], 1, v[130:131]
	s_mov_b32 m0, s53
	ds_read_b128 v[136:139], v171
	ds_read_b128 v[144:147], v171 offset:1024
	ds_read_b128 v[148:151], v171 offset:2048
	ds_read_b128 v[174:177], v171 offset:3072
	ds_read_b128 v[178:181], v163
	ds_read_b128 v[182:185], v163 offset:1024
	ds_read_b128 v[186:189], v162
	ds_read_b128 v[190:193], v162 offset:1024
	ds_read_b128 v[194:197], v161
	ds_read_b128 v[198:201], v161 offset:1024
	ds_read_b128 v[202:205], v160
	ds_read_b128 v[208:211], v160 offset:1024
	global_load_lds_dwordx4 v[128:129], off
	v_lshl_add_u64 v[128:129], s[40:41], 0, v[142:143]
	v_readfirstlane_b32 s40, v173
	v_lshl_add_u64 v[128:129], v[140:141], 1, v[128:129]
	s_mov_b32 m0, s40
	s_nop 0
	global_load_lds_dwordx4 v[128:129], off
	s_barrier
	s_waitcnt lgkmcnt(0)
	s_waitcnt lgkmcnt(0)
	v_mfma_f32_16x16x32_bf16 v[0:3], v[136:139], v[178:181], v[0:3]
	v_mfma_f32_16x16x32_bf16 v[4:7], v[148:151], v[178:181], v[4:7]
	v_mfma_f32_16x16x32_bf16 v[8:11], v[136:139], v[186:189], v[8:11]
	v_mfma_f32_16x16x32_bf16 v[16:19], v[148:151], v[186:189], v[16:19]
	v_mfma_f32_16x16x32_bf16 v[28:31], v[136:139], v[194:197], v[28:31]
	v_mfma_f32_16x16x32_bf16 v[40:43], v[148:151], v[194:197], v[40:43]
	v_mfma_f32_16x16x32_bf16 v[52:55], v[136:139], v[202:205], v[52:55]
	v_mfma_f32_16x16x32_bf16 v[64:67], v[148:151], v[202:205], v[64:67]
	v_mfma_f32_16x16x32_bf16 v[0:3], v[144:147], v[182:185], v[0:3]
	v_mfma_f32_16x16x32_bf16 v[4:7], v[174:177], v[182:185], v[4:7]
	v_mfma_f32_16x16x32_bf16 v[8:11], v[144:147], v[190:193], v[8:11]
	v_mfma_f32_16x16x32_bf16 v[16:19], v[174:177], v[190:193], v[16:19]
	v_mfma_f32_16x16x32_bf16 v[28:31], v[144:147], v[198:201], v[28:31]
	v_mfma_f32_16x16x32_bf16 v[40:43], v[174:177], v[198:201], v[40:43]
	v_mfma_f32_16x16x32_bf16 v[52:55], v[144:147], v[208:211], v[52:55]
	v_mfma_f32_16x16x32_bf16 v[64:67], v[174:177], v[208:211], v[64:67]
	s_barrier
	ds_read_b128 v[128:131], v169
	ds_read_b128 v[140:143], v169 offset:1024
	ds_read_b128 v[170:173], v169 offset:2048
	ds_read_b128 v[218:221], v169 offset:3072
	s_barrier
; #define LDA(dst, b, h) UFOR(m, 4) UFOR(k, 2) \
;     dst[m][k] = *reinterpret_cast<const bf16x8*>((char*)SA(b, h) + lds_byte(wr * 64 + m * 16 + fr, k * 32 + fq * 8))
; #define LDB(dst, b, h) UFOR(n, 2) UFOR(k, 2) \
;     dst[n][k] = *reinterpret_cast<const bf16x8*>((char*)SB(b, h) + lds_byte(wc * 32 + n * 16 + fr, k * 32 + fq * 8))
; #define MMA(ai, bj, At, Bq) do { __builtin_amdgcn_s_setprio(1); \
;     UFOR(m, 4) UFOR(n, 2) UFOR(k, 2) \
;       acc[ai][bj][m][n] = __builtin_amdgcn_mfma_f32_16x16x32_bf16(Bq[n][k], At[m][k], acc[ai][bj][m][n], 0, 0, 0); \
;     __builtin_amdgcn_s_setprio(0); } while (0)
; #define WAIT_V(n) asm volatile("s_waitcnt vmcnt(" #n ")" ::: "memory")
; #define WAIT_L(n) asm volatile("s_waitcnt lgkmcnt(" #n ")" ::: "memory")
; #define BAR __builtin_amdgcn_s_barrier()
; template <int EPI, int K, int KL> ...
;     ...
;     LDB(B1, 0, 1); BAR; WAIT_L(0); MMA(0, 1, At, B1); BAR;
;     LDA(At, 0, 1); WAIT_V(4); BAR; WAIT_L(0); MMA(1, 0, At, B0); MMA(1, 1, At, B1); BAR; }
;   { LDB(B0, 1, 0); LDA(At, 1, 0); WAIT_V(2); BAR; WAIT_L(0); MMA(0, 0, At, B0); BAR;
	s_waitcnt lgkmcnt(0)
	s_waitcnt lgkmcnt(0)
	v_mfma_f32_16x16x32_bf16 v[12:15], v[128:131], v[178:181], v[12:15]
	v_mfma_f32_16x16x32_bf16 v[24:27], v[170:173], v[178:181], v[24:27]
	v_mfma_f32_16x16x32_bf16 v[36:39], v[128:131], v[186:189], v[36:39]
	v_mfma_f32_16x16x32_bf16 v[48:51], v[170:173], v[186:189], v[48:51]
	v_mfma_f32_16x16x32_bf16 v[60:63], v[128:131], v[194:197], v[60:63]
	v_mfma_f32_16x16x32_bf16 v[72:75], v[170:173], v[194:197], v[72:75]
	v_mfma_f32_16x16x32_bf16 v[80:83], v[128:131], v[202:205], v[80:83]
	v_mfma_f32_16x16x32_bf16 v[12:15], v[140:143], v[182:185], v[12:15]
	v_mfma_f32_16x16x32_bf16 v[24:27], v[218:221], v[182:185], v[24:27]
	v_mfma_f32_16x16x32_bf16 v[36:39], v[140:143], v[190:193], v[36:39]
	v_mfma_f32_16x16x32_bf16 v[48:51], v[218:221], v[190:193], v[48:51]
	v_mfma_f32_16x16x32_bf16 v[60:63], v[140:143], v[198:201], v[60:63]
	v_mfma_f32_16x16x32_bf16 v[72:75], v[218:221], v[198:201], v[72:75]
	v_mfma_f32_16x16x32_bf16 v[178:181], v[140:143], v[208:211], v[80:83]
	v_mfma_f32_16x16x32_bf16 v[80:83], v[170:173], v[202:205], v[88:91]
	v_mfma_f32_16x16x32_bf16 v[182:185], v[218:221], v[208:211], v[80:83]
	s_barrier
	s_nop 4
	ds_read_b128 v[80:83], v163 offset:16384
	ds_read_b128 v[88:91], v163 offset:17408
	ds_read_b128 v[186:189], v162 offset:16384
	ds_read_b128 v[190:193], v162 offset:17408
	ds_read_b128 v[194:197], v161 offset:16384
	ds_read_b128 v[198:201], v161 offset:17408
	ds_read_b128 v[202:205], v160 offset:16384
	ds_read_b128 v[208:211], v160 offset:17408
	s_waitcnt vmcnt(4)
	s_barrier
	s_waitcnt lgkmcnt(0)
	s_waitcnt lgkmcnt(0)
	v_mfma_f32_16x16x32_bf16 v[56:59], v[148:151], v[186:189], v[56:59]
	v_mfma_f32_16x16x32_bf16 v[222:225], v[174:177], v[190:193], v[56:59]
	v_mfma_f32_16x16x32_bf16 v[56:59], v[136:139], v[194:197], v[68:71]
	v_mfma_f32_16x16x32_bf16 v[226:229], v[144:147], v[198:201], v[56:59]
	v_mfma_f32_16x16x32_bf16 v[56:59], v[148:151], v[194:197], v[76:79]
	v_mfma_f32_16x16x32_bf16 v[20:23], v[136:139], v[80:83], v[20:23]
	v_mfma_f32_16x16x32_bf16 v[32:35], v[148:151], v[80:83], v[32:35]
	v_mfma_f32_16x16x32_bf16 v[44:47], v[136:139], v[186:189], v[44:47]
	v_mfma_f32_16x16x32_bf16 v[230:233], v[174:177], v[198:201], v[56:59]
	v_mfma_f32_16x16x32_bf16 v[56:59], v[136:139], v[202:205], v[84:87]
	v_mfma_f32_16x16x32_bf16 v[20:23], v[144:147], v[88:91], v[20:23]
	v_mfma_f32_16x16x32_bf16 v[32:35], v[174:177], v[88:91], v[32:35]
	v_mfma_f32_16x16x32_bf16 v[44:47], v[144:147], v[190:193], v[44:47]
	v_mfma_f32_16x16x32_bf16 v[136:139], v[144:147], v[208:211], v[56:59]
	v_mfma_f32_16x16x32_bf16 v[56:59], v[148:151], v[202:205], v[92:95]
	v_mfma_f32_16x16x32_bf16 v[144:147], v[174:177], v[208:211], v[56:59]
	v_mfma_f32_16x16x32_bf16 v[56:59], v[128:131], v[80:83], v[96:99]
	v_mfma_f32_16x16x32_bf16 v[148:151], v[140:143], v[88:91], v[56:59]
	v_mfma_f32_16x16x32_bf16 v[56:59], v[170:173], v[80:83], v[100:103]
	v_mfma_f32_16x16x32_bf16 v[174:177], v[218:221], v[88:91], v[56:59]
	v_mfma_f32_16x16x32_bf16 v[56:59], v[128:131], v[186:189], v[104:107]
	v_mfma_f32_16x16x32_bf16 v[234:237], v[140:143], v[190:193], v[56:59]
	v_mfma_f32_16x16x32_bf16 v[56:59], v[170:173], v[186:189], v[108:111]
	v_mfma_f32_16x16x32_bf16 v[186:189], v[218:221], v[190:193], v[56:59]
	v_mfma_f32_16x16x32_bf16 v[56:59], v[128:131], v[194:197], v[112:115]
	v_mfma_f32_16x16x32_bf16 v[190:193], v[140:143], v[198:201], v[56:59]
	v_mfma_f32_16x16x32_bf16 v[56:59], v[170:173], v[194:197], v[116:119]
	v_mfma_f32_16x16x32_bf16 v[194:197], v[218:221], v[198:201], v[56:59]
	v_mfma_f32_16x16x32_bf16 v[56:59], v[128:131], v[202:205], v[120:123]
	v_mfma_f32_16x16x32_bf16 v[128:131], v[140:143], v[208:211], v[56:59]
	v_mfma_f32_16x16x32_bf16 v[56:59], v[170:173], v[202:205], v[124:127]
	v_mfma_f32_16x16x32_bf16 v[140:143], v[218:221], v[208:211], v[56:59]
	s_barrier
	ds_read_b128 v[168:171], v166
	ds_read_b128 v[198:201], v166 offset:1024
	ds_read_b128 v[202:205], v166 offset:2048
	ds_read_b128 v[208:211], v166 offset:3072
	s_nop 0
	ds_read_b128 v[56:59], v163 offset:32768
	ds_read_b128 v[68:71], v163 offset:33792
	ds_read_b128 v[76:79], v162 offset:32768
	ds_read_b128 v[80:83], v162 offset:33792
	ds_read_b128 v[218:221], v161 offset:32768
	ds_read_b128 v[238:241], v161 offset:33792
	ds_read_b128 v[242:245], v160 offset:32768
	ds_read_b128 v[246:249], v160 offset:33792
	s_waitcnt vmcnt(2)
	s_barrier
; #define LDA(dst, b, h) UFOR(m, 4) UFOR(k, 2) \
;     dst[m][k] = *reinterpret_cast<const bf16x8*>((char*)SA(b, h) + lds_byte(wr * 64 + m * 16 + fr, k * 32 + fq * 8))
; #define LDB(dst, b, h) UFOR(n, 2) UFOR(k, 2) \
;     dst[n][k] = *reinterpret_cast<const bf16x8*>((char*)SB(b, h) + lds_byte(wc * 32 + n * 16 + fr, k * 32 + fq * 8))
; #define MMA(ai, bj, At, Bq) do { __builtin_amdgcn_s_setprio(1); \
;     UFOR(m, 4) UFOR(n, 2) UFOR(k, 2) \
;       acc[ai][bj][m][n] = __builtin_amdgcn_mfma_f32_16x16x32_bf16(Bq[n][k], At[m][k], acc[ai][bj][m][n], 0, 0, 0); \
;     __builtin_amdgcn_s_setprio(0); } while (0)
; #define WAIT_V(n) asm volatile("s_waitcnt vmcnt(" #n ")" ::: "memory")
; #define WAIT_L(n) asm volatile("s_waitcnt lgkmcnt(" #n ")" ::: "memory")
; #define BAR __builtin_amdgcn_s_barrier()
; template <int EPI, int K, int KL> ...
;     ...
;   { LDB(B0, 1, 0); LDA(At, 1, 0); WAIT_V(2); BAR; WAIT_L(0); MMA(0, 0, At, B0); BAR;
;     LDB(B1, 1, 1); WAIT_V(0); BAR; WAIT_L(0); MMA(0, 1, At, B1); BAR;
;     LDA(At, 1, 1); BAR; WAIT_L(0); MMA(1, 0, At, B0); MMA(1, 1, At, B1); BAR; }
;   if (wr == 0) BAR;
	s_waitcnt lgkmcnt(0)
	s_waitcnt lgkmcnt(0)
	v_mfma_f32_16x16x32_bf16 v[0:3], v[168:171], v[56:59], v[0:3]
	v_mfma_f32_16x16x32_bf16 v[124:127], v[198:201], v[68:71], v[0:3]
	v_mfma_f32_16x16x32_bf16 v[0:3], v[202:205], v[56:59], v[4:7]
	v_mfma_f32_16x16x32_bf16 v[120:123], v[208:211], v[68:71], v[0:3]
	v_mfma_f32_16x16x32_bf16 v[0:3], v[168:171], v[76:79], v[8:11]
	v_mfma_f32_16x16x32_bf16 v[116:119], v[198:201], v[80:83], v[0:3]
	v_mfma_f32_16x16x32_bf16 v[0:3], v[202:205], v[76:79], v[16:19]
	v_mfma_f32_16x16x32_bf16 v[112:115], v[208:211], v[80:83], v[0:3]
	v_mfma_f32_16x16x32_bf16 v[0:3], v[168:171], v[218:221], v[28:31]
	v_mfma_f32_16x16x32_bf16 v[108:111], v[198:201], v[238:241], v[0:3]
	v_mfma_f32_16x16x32_bf16 v[0:3], v[202:205], v[218:221], v[40:43]
	v_mfma_f32_16x16x32_bf16 v[104:107], v[208:211], v[238:241], v[0:3]
	v_mfma_f32_16x16x32_bf16 v[0:3], v[168:171], v[242:245], v[52:55]
	v_mfma_f32_16x16x32_bf16 v[100:103], v[198:201], v[246:249], v[0:3]
	v_mfma_f32_16x16x32_bf16 v[0:3], v[202:205], v[242:245], v[64:67]
	v_mfma_f32_16x16x32_bf16 v[96:99], v[208:211], v[246:249], v[0:3]
	s_barrier
	s_nop 4
	ds_read_b128 v[0:3], v164
	ds_read_b128 v[4:7], v164 offset:1024
	ds_read_b128 v[214:217], v164 offset:2048
	ds_read_b128 v[164:167], v164 offset:3072
	s_waitcnt vmcnt(0)
	s_barrier
	s_waitcnt lgkmcnt(0)
	s_waitcnt lgkmcnt(0)
	v_mfma_f32_16x16x32_bf16 v[8:11], v[0:3], v[56:59], v[12:15]
	v_mfma_f32_16x16x32_bf16 v[92:95], v[4:7], v[68:71], v[8:11]
	v_mfma_f32_16x16x32_bf16 v[8:11], v[214:217], v[56:59], v[24:27]
	v_mfma_f32_16x16x32_bf16 v[88:91], v[164:167], v[68:71], v[8:11]
	v_mfma_f32_16x16x32_bf16 v[8:11], v[0:3], v[76:79], v[36:39]
	v_mfma_f32_16x16x32_bf16 v[84:87], v[4:7], v[80:83], v[8:11]
	v_mfma_f32_16x16x32_bf16 v[8:11], v[214:217], v[76:79], v[48:51]
	v_mfma_f32_16x16x32_bf16 v[80:83], v[164:167], v[80:83], v[8:11]
	v_mfma_f32_16x16x32_bf16 v[8:11], v[0:3], v[218:221], v[60:63]
	v_mfma_f32_16x16x32_bf16 v[76:79], v[4:7], v[238:241], v[8:11]
	v_mfma_f32_16x16x32_bf16 v[8:11], v[214:217], v[218:221], v[72:75]
	v_mfma_f32_16x16x32_bf16 v[72:75], v[164:167], v[238:241], v[8:11]
	v_mfma_f32_16x16x32_bf16 v[8:11], v[0:3], v[242:245], v[178:181]
	v_mfma_f32_16x16x32_bf16 v[68:71], v[4:7], v[246:249], v[8:11]
	v_mfma_f32_16x16x32_bf16 v[8:11], v[214:217], v[242:245], v[182:185]
	v_mfma_f32_16x16x32_bf16 v[64:67], v[164:167], v[246:249], v[8:11]
	s_barrier
	s_nop 4
	ds_read_b128 v[8:11], v163 offset:49152
	ds_read_b128 v[12:15], v163 offset:50176
	ds_read_b128 v[16:19], v162 offset:49152
	ds_read_b128 v[178:181], v162 offset:50176
	ds_read_b128 v[182:185], v161 offset:49152
	ds_read_b128 v[218:221], v161 offset:50176
	ds_read_b128 v[238:241], v160 offset:49152
	ds_read_b128 v[158:161], v160 offset:50176
	s_barrier
	s_waitcnt lgkmcnt(0)
	s_waitcnt lgkmcnt(0)
	v_mfma_f32_16x16x32_bf16 v[20:23], v[168:171], v[8:11], v[20:23]
	v_mfma_f32_16x16x32_bf16 v[60:63], v[198:201], v[12:15], v[20:23]
	v_mfma_f32_16x16x32_bf16 v[20:23], v[202:205], v[8:11], v[32:35]
	v_mfma_f32_16x16x32_bf16 v[56:59], v[208:211], v[12:15], v[20:23]
	v_mfma_f32_16x16x32_bf16 v[20:23], v[168:171], v[16:19], v[44:47]
	v_mfma_f32_16x16x32_bf16 v[52:55], v[198:201], v[178:181], v[20:23]
	v_mfma_f32_16x16x32_bf16 v[20:23], v[202:205], v[16:19], v[222:225]
	v_mfma_f32_16x16x32_bf16 v[48:51], v[208:211], v[178:181], v[20:23]
	v_mfma_f32_16x16x32_bf16 v[20:23], v[168:171], v[182:185], v[226:229]
	v_mfma_f32_16x16x32_bf16 v[44:47], v[198:201], v[218:221], v[20:23]
	v_mfma_f32_16x16x32_bf16 v[20:23], v[202:205], v[182:185], v[230:233]
	v_mfma_f32_16x16x32_bf16 v[40:43], v[208:211], v[218:221], v[20:23]
	v_mfma_f32_16x16x32_bf16 v[20:23], v[168:171], v[238:241], v[136:139]
	v_mfma_f32_16x16x32_bf16 v[36:39], v[198:201], v[158:161], v[20:23]
	v_mfma_f32_16x16x32_bf16 v[20:23], v[202:205], v[238:241], v[144:147]
	v_mfma_f32_16x16x32_bf16 v[32:35], v[208:211], v[158:161], v[20:23]
	v_mfma_f32_16x16x32_bf16 v[20:23], v[0:3], v[8:11], v[148:151]
	v_mfma_f32_16x16x32_bf16 v[8:11], v[214:217], v[8:11], v[174:177]
	v_mfma_f32_16x16x32_bf16 v[24:27], v[164:167], v[12:15], v[8:11]
	v_mfma_f32_16x16x32_bf16 v[8:11], v[0:3], v[16:19], v[234:237]
	v_mfma_f32_16x16x32_bf16 v[28:31], v[4:7], v[12:15], v[20:23]
	v_mfma_f32_16x16x32_bf16 v[20:23], v[4:7], v[178:181], v[8:11]
	v_mfma_f32_16x16x32_bf16 v[8:11], v[214:217], v[16:19], v[186:189]
	v_mfma_f32_16x16x32_bf16 v[16:19], v[164:167], v[178:181], v[8:11]
	v_mfma_f32_16x16x32_bf16 v[8:11], v[0:3], v[182:185], v[190:193]
	v_mfma_f32_16x16x32_bf16 v[0:3], v[0:3], v[238:241], v[128:131]
	v_mfma_f32_16x16x32_bf16 v[12:15], v[4:7], v[218:221], v[8:11]
	v_mfma_f32_16x16x32_bf16 v[8:11], v[214:217], v[182:185], v[194:197]
	v_mfma_f32_16x16x32_bf16 v[4:7], v[4:7], v[158:161], v[0:3]
	v_mfma_f32_16x16x32_bf16 v[0:3], v[214:217], v[238:241], v[140:143]
	v_mfma_f32_16x16x32_bf16 v[8:11], v[164:167], v[218:221], v[8:11]
	v_mfma_f32_16x16x32_bf16 v[0:3], v[164:167], v[158:161], v[0:3]
	s_movk_i32 s40, 0x100
	v_cmp_gt_u32_e32 vcc, s40, v152
	s_barrier
	s_and_saveexec_b64 s[40:41], vcc
	s_cbranch_execz .LBB0_1110
	s_barrier

; #define STAGE(P, BASE, br, kt) STAGET(tid_, P, BASE, br, kt)
; #define LDA(dst, b, h) UFOR(m, 4) UFOR(k, 2) \
;     dst[m][k] = *reinterpret_cast<const bf16x8*>((char*)SA(b, h) + lds_byte(wr * 64 + m * 16 + fr, k * 32 + fq * 8))
; #define LDB(dst, b, h) UFOR(n, 2) UFOR(k, 2) \
;     dst[n][k] = *reinterpret_cast<const bf16x8*>((char*)SB(b, h) + lds_byte(wc * 32 + n * 16 + fr, k * 32 + fq * 8))
; #define MMA(ai, bj, At, Bq) do { __builtin_amdgcn_s_setprio(1); \
;     UFOR(m, 4) UFOR(n, 2) UFOR(k, 2) \
;       acc[ai][bj][m][n] = __builtin_amdgcn_mfma_f32_16x16x32_bf16(Bq[n][k], At[m][k], acc[ai][bj][m][n], 0, 0, 0); \
;     __builtin_amdgcn_s_setprio(0); } while (0)
; #define WAIT_L(n) asm volatile("s_waitcnt lgkmcnt(" #n ")" ::: "memory")
; #define BAR __builtin_amdgcn_s_barrier()
; #define SCHED __builtin_amdgcn_sched_barrier(0)
; template <int EPI, int K, int KL> ...
;     ...
;     LDB(B0, 0, 0); SCHED; LDA(At, 0, 0); STAGE(SA(1, 1), A, brow + HALF, t + 1);
;     WAIT_L(8); BAR; WAIT_L(0); MMA(0, 0, At, B0); BAR; SCHED;
;     LDB(B1, 0, 1); STAGE(SB(0, 0), Bt, bcol, t + 2);
;     BAR; WAIT_L(0); MMA(0, 1, At, B1); BAR;
;     LDA(At, 0, 1); STAGE(SA(0, 0), A, brow, t + 2);
;     BAR; WAIT_L(0); MMA(1, 0, At, B0); BAR; SCHED;
.LBB0_1184:
	ds_read_b128 v[136:139], v170
	ds_read_b128 v[174:177], v170 offset:1024
	ds_read_b128 v[178:181], v170 offset:2048
	ds_read_b128 v[182:185], v170 offset:3072
	v_add_u32_e32 v171, 0xc000, v157
	v_lshl_add_u64 v[238:239], s[92:93], 0, v[148:149]
	v_readfirstlane_b32 s54, v171
	v_lshl_add_u64 v[172:173], v[238:239], 0, s[86:87]
	s_mov_b32 m0, s54
	ds_read_b128 v[186:189], v162
	ds_read_b128 v[190:193], v162 offset:1024
	ds_read_b128 v[194:197], v161
	ds_read_b128 v[198:201], v161 offset:1024
	ds_read_b128 v[202:205], v160
	ds_read_b128 v[208:211], v160 offset:1024
	ds_read_b128 v[214:217], v159
	ds_read_b128 v[218:221], v159 offset:1024
	global_load_lds_dwordx4 v[172:173], off
	v_add_u32_e32 v172, 0xe000, v157
	v_lshl_add_u64 v[240:241], s[92:93], 0, v[150:151]
	v_readfirstlane_b32 s54, v172
	v_lshl_add_u64 v[222:223], v[240:241], 0, s[86:87]
	s_mov_b32 m0, s54
	s_nop 0
	global_load_lds_dwordx4 v[222:223], off
	s_waitcnt lgkmcnt(8)
	s_barrier
	s_waitcnt lgkmcnt(0)
	s_waitcnt lgkmcnt(0)
	v_mfma_f32_16x16x32_bf16 v[124:127], v[136:139], v[186:189], v[124:127]
	v_mfma_f32_16x16x32_bf16 v[120:123], v[178:181], v[186:189], v[120:123]
	v_mfma_f32_16x16x32_bf16 v[116:119], v[136:139], v[194:197], v[116:119]
	v_mfma_f32_16x16x32_bf16 v[112:115], v[178:181], v[194:197], v[112:115]
	v_mfma_f32_16x16x32_bf16 v[108:111], v[136:139], v[202:205], v[108:111]
	v_mfma_f32_16x16x32_bf16 v[104:107], v[178:181], v[202:205], v[104:107]
	v_mfma_f32_16x16x32_bf16 v[100:103], v[136:139], v[214:217], v[100:103]
	v_mfma_f32_16x16x32_bf16 v[96:99], v[178:181], v[214:217], v[96:99]
	v_mfma_f32_16x16x32_bf16 v[124:127], v[174:177], v[190:193], v[124:127]
	v_mfma_f32_16x16x32_bf16 v[120:123], v[182:185], v[190:193], v[120:123]
	v_mfma_f32_16x16x32_bf16 v[116:119], v[174:177], v[198:201], v[116:119]
	v_mfma_f32_16x16x32_bf16 v[112:115], v[182:185], v[198:201], v[112:115]
	v_mfma_f32_16x16x32_bf16 v[108:111], v[174:177], v[208:211], v[108:111]
	v_mfma_f32_16x16x32_bf16 v[104:107], v[182:185], v[208:211], v[104:107]
	v_mfma_f32_16x16x32_bf16 v[100:103], v[174:177], v[218:221], v[100:103]
	v_mfma_f32_16x16x32_bf16 v[96:99], v[182:185], v[218:221], v[96:99]
	s_barrier
	v_lshl_add_u64 v[242:243], s[92:93], 0, v[144:145]
	v_readfirstlane_b32 s54, v156
	v_lshl_add_u64 v[244:245], v[242:243], 0, s[22:23]
	s_mov_b32 m0, s54
	v_add_u32_e32 v134, 0x2000, v156
	ds_read_b128 v[222:225], v169
	ds_read_b128 v[226:229], v169 offset:1024
	ds_read_b128 v[230:233], v169 offset:2048
	ds_read_b128 v[234:237], v169 offset:3072
	global_load_lds_dwordx4 v[244:245], off
	v_lshl_add_u64 v[244:245], s[92:93], 0, v[146:147]
	v_readfirstlane_b32 s54, v134
	v_lshl_add_u64 v[246:247], v[244:245], 0, s[22:23]
	s_mov_b32 m0, s54
	s_nop 0
	global_load_lds_dwordx4 v[246:247], off
	s_barrier
	s_waitcnt lgkmcnt(0)
	s_waitcnt lgkmcnt(0)
	v_mfma_f32_16x16x32_bf16 v[92:95], v[222:225], v[186:189], v[92:95]
	v_mfma_f32_16x16x32_bf16 v[88:91], v[230:233], v[186:189], v[88:91]
	v_mfma_f32_16x16x32_bf16 v[84:87], v[222:225], v[194:197], v[84:87]
	v_mfma_f32_16x16x32_bf16 v[80:83], v[230:233], v[194:197], v[80:83]
	v_mfma_f32_16x16x32_bf16 v[76:79], v[222:225], v[202:205], v[76:79]
	v_mfma_f32_16x16x32_bf16 v[72:75], v[230:233], v[202:205], v[72:75]
	v_mfma_f32_16x16x32_bf16 v[68:71], v[222:225], v[214:217], v[68:71]
	v_mfma_f32_16x16x32_bf16 v[64:67], v[230:233], v[214:217], v[64:67]
	v_mfma_f32_16x16x32_bf16 v[92:95], v[226:229], v[190:193], v[92:95]
	v_mfma_f32_16x16x32_bf16 v[88:91], v[234:237], v[190:193], v[88:91]
	v_mfma_f32_16x16x32_bf16 v[84:87], v[226:229], v[198:201], v[84:87]
	v_mfma_f32_16x16x32_bf16 v[80:83], v[234:237], v[198:201], v[80:83]
	v_mfma_f32_16x16x32_bf16 v[76:79], v[226:229], v[208:211], v[76:79]
	v_mfma_f32_16x16x32_bf16 v[72:75], v[234:237], v[208:211], v[72:75]
	v_mfma_f32_16x16x32_bf16 v[68:71], v[226:229], v[218:221], v[68:71]
	v_mfma_f32_16x16x32_bf16 v[64:67], v[234:237], v[218:221], v[64:67]
	v_readfirstlane_b32 s54, v157
	v_add_u32_e32 v134, 0x2000, v157
	v_lshl_add_u64 v[246:247], v[238:239], 0, s[34:35]
	s_mov_b32 m0, s54
	v_readfirstlane_b32 s54, v134
	s_barrier
	ds_read_b128 v[186:189], v162 offset:16384
	ds_read_b128 v[190:193], v162 offset:17408
	ds_read_b128 v[194:197], v161 offset:16384
	ds_read_b128 v[198:201], v161 offset:17408
	ds_read_b128 v[202:205], v160 offset:16384
	ds_read_b128 v[208:211], v160 offset:17408
	ds_read_b128 v[214:217], v159 offset:16384
	ds_read_b128 v[218:221], v159 offset:17408
	global_load_lds_dwordx4 v[246:247], off
	v_lshl_add_u64 v[246:247], v[240:241], 0, s[34:35]
	s_mov_b32 m0, s54
	s_nop 0
	global_load_lds_dwordx4 v[246:247], off
	s_barrier
	s_waitcnt lgkmcnt(0)
	s_waitcnt lgkmcnt(0)
	v_mfma_f32_16x16x32_bf16 v[60:63], v[136:139], v[186:189], v[60:63]
	v_mfma_f32_16x16x32_bf16 v[56:59], v[178:181], v[186:189], v[56:59]
	v_mfma_f32_16x16x32_bf16 v[52:55], v[136:139], v[194:197], v[52:55]
	v_mfma_f32_16x16x32_bf16 v[48:51], v[178:181], v[194:197], v[48:51]
	v_mfma_f32_16x16x32_bf16 v[44:47], v[136:139], v[202:205], v[44:47]
	v_mfma_f32_16x16x32_bf16 v[40:43], v[178:181], v[202:205], v[40:43]
	v_mfma_f32_16x16x32_bf16 v[36:39], v[136:139], v[214:217], v[36:39]
	v_mfma_f32_16x16x32_bf16 v[32:35], v[178:181], v[214:217], v[32:35]
	v_mfma_f32_16x16x32_bf16 v[60:63], v[174:177], v[190:193], v[60:63]
	v_mfma_f32_16x16x32_bf16 v[56:59], v[182:185], v[190:193], v[56:59]
	v_mfma_f32_16x16x32_bf16 v[52:55], v[174:177], v[198:201], v[52:55]
	v_mfma_f32_16x16x32_bf16 v[48:51], v[182:185], v[198:201], v[48:51]
	v_mfma_f32_16x16x32_bf16 v[44:47], v[174:177], v[208:211], v[44:47]
	v_mfma_f32_16x16x32_bf16 v[40:43], v[182:185], v[208:211], v[40:43]
	v_mfma_f32_16x16x32_bf16 v[36:39], v[174:177], v[218:221], v[36:39]
	v_mfma_f32_16x16x32_bf16 v[32:35], v[182:185], v[218:221], v[32:35]
	s_barrier
; #define STAGE(P, BASE, br, kt) STAGET(tid_, P, BASE, br, kt)
; #define LDA(dst, b, h) UFOR(m, 4) UFOR(k, 2) \
;     dst[m][k] = *reinterpret_cast<const bf16x8*>((char*)SA(b, h) + lds_byte(wr * 64 + m * 16 + fr, k * 32 + fq * 8))
; #define LDB(dst, b, h) UFOR(n, 2) UFOR(k, 2) \
;     dst[n][k] = *reinterpret_cast<const bf16x8*>((char*)SB(b, h) + lds_byte(wc * 32 + n * 16 + fr, k * 32 + fq * 8))
; #define MMA(ai, bj, At, Bq) do { __builtin_amdgcn_s_setprio(1); \
;     UFOR(m, 4) UFOR(n, 2) UFOR(k, 2) \
;       acc[ai][bj][m][n] = __builtin_amdgcn_mfma_f32_16x16x32_bf16(Bq[n][k], At[m][k], acc[ai][bj][m][n], 0, 0, 0); \
;     __builtin_amdgcn_s_setprio(0); } while (0)
; #define WAIT_V(n) asm volatile("s_waitcnt vmcnt(" #n ")" ::: "memory")
; #define WAIT_L(n) asm volatile("s_waitcnt lgkmcnt(" #n ")" ::: "memory")
; #define BAR __builtin_amdgcn_s_barrier()
; #define SCHED __builtin_amdgcn_sched_barrier(0)
; template <int EPI, int K, int KL> ...
;     ...
;     STAGE(SB(0, 1), Bt, bcol + HALF, t + 2);
;     WAIT_V(6); BAR; MMA(1, 1, At, B1); BAR;
;     LDB(B0, 1, 0); SCHED; LDA(At, 1, 0); STAGE(SA(0, 1), A, brow + HALF, t + 2);
;     WAIT_L(8); BAR; WAIT_L(0); MMA(0, 0, At, B0); BAR; SCHED;
;     LDB(B1, 1, 1); STAGE(SB(1, 0), Bt, bcol, t + 3);
;     BAR; WAIT_L(0); MMA(0, 1, At, B1); BAR;
;     LDA(At, 1, 1); STAGE(SA(1, 0), A, brow, t + 3);
	v_readfirstlane_b32 s54, v158
	v_add_u32_e32 v134, 0x2000, v158
	v_lshl_add_u64 v[136:137], v[242:243], 0, s[24:25]
	s_mov_b32 m0, s54
	v_readfirstlane_b32 s54, v134
	global_load_lds_dwordx4 v[136:137], off
	v_lshl_add_u64 v[136:137], v[244:245], 0, s[24:25]
	s_mov_b32 m0, s54
	s_nop 0
	global_load_lds_dwordx4 v[136:137], off
	s_waitcnt vmcnt(6)
	s_barrier
	v_mfma_f32_16x16x32_bf16 v[28:31], v[222:225], v[186:189], v[28:31]
	v_mfma_f32_16x16x32_bf16 v[24:27], v[230:233], v[186:189], v[24:27]
	v_mfma_f32_16x16x32_bf16 v[20:23], v[222:225], v[194:197], v[20:23]
	v_mfma_f32_16x16x32_bf16 v[16:19], v[230:233], v[194:197], v[16:19]
	v_mfma_f32_16x16x32_bf16 v[12:15], v[222:225], v[202:205], v[12:15]
	v_mfma_f32_16x16x32_bf16 v[8:11], v[230:233], v[202:205], v[8:11]
	v_mfma_f32_16x16x32_bf16 v[4:7], v[222:225], v[214:217], v[4:7]
	v_mfma_f32_16x16x32_bf16 v[0:3], v[230:233], v[214:217], v[0:3]
	v_mfma_f32_16x16x32_bf16 v[28:31], v[226:229], v[190:193], v[28:31]
	v_mfma_f32_16x16x32_bf16 v[24:27], v[234:237], v[190:193], v[24:27]
	v_mfma_f32_16x16x32_bf16 v[20:23], v[226:229], v[198:201], v[20:23]
	v_mfma_f32_16x16x32_bf16 v[16:19], v[234:237], v[198:201], v[16:19]
	v_mfma_f32_16x16x32_bf16 v[12:15], v[226:229], v[208:211], v[12:15]
	v_mfma_f32_16x16x32_bf16 v[8:11], v[234:237], v[208:211], v[8:11]
	v_mfma_f32_16x16x32_bf16 v[4:7], v[226:229], v[218:221], v[4:7]
	v_mfma_f32_16x16x32_bf16 v[0:3], v[234:237], v[218:221], v[0:3]
	s_barrier
	ds_read_b128 v[136:139], v165
	ds_read_b128 v[174:177], v165 offset:1024
	ds_read_b128 v[178:181], v165 offset:2048
	ds_read_b128 v[182:185], v165 offset:3072
	v_add_u32_e32 v134, 0x4000, v157
	v_lshl_add_u64 v[222:223], v[238:239], 0, s[28:29]
	v_readfirstlane_b32 s54, v134
	v_add_u32_e32 v134, 0x6000, v157
	s_mov_b32 m0, s54
	v_readfirstlane_b32 s54, v134
	ds_read_b128 v[186:189], v162 offset:32768
	ds_read_b128 v[190:193], v162 offset:33792
	ds_read_b128 v[194:197], v161 offset:32768
	ds_read_b128 v[198:201], v161 offset:33792
	ds_read_b128 v[202:205], v160 offset:32768
	ds_read_b128 v[208:211], v160 offset:33792
	ds_read_b128 v[214:217], v159 offset:32768
	ds_read_b128 v[218:221], v159 offset:33792
	global_load_lds_dwordx4 v[222:223], off
	v_lshl_add_u64 v[222:223], v[240:241], 0, s[28:29]
	s_mov_b32 m0, s54
	s_nop 0
	global_load_lds_dwordx4 v[222:223], off
	s_waitcnt lgkmcnt(8)
	s_barrier
	s_waitcnt lgkmcnt(0)
	s_waitcnt lgkmcnt(0)
	v_mfma_f32_16x16x32_bf16 v[124:127], v[136:139], v[186:189], v[124:127]
	v_mfma_f32_16x16x32_bf16 v[120:123], v[178:181], v[186:189], v[120:123]
	v_mfma_f32_16x16x32_bf16 v[116:119], v[136:139], v[194:197], v[116:119]
	v_mfma_f32_16x16x32_bf16 v[112:115], v[178:181], v[194:197], v[112:115]
	v_mfma_f32_16x16x32_bf16 v[108:111], v[136:139], v[202:205], v[108:111]
	v_mfma_f32_16x16x32_bf16 v[104:107], v[178:181], v[202:205], v[104:107]
	v_mfma_f32_16x16x32_bf16 v[100:103], v[136:139], v[214:217], v[100:103]
	v_mfma_f32_16x16x32_bf16 v[96:99], v[178:181], v[214:217], v[96:99]
	v_mfma_f32_16x16x32_bf16 v[124:127], v[174:177], v[190:193], v[124:127]
	v_mfma_f32_16x16x32_bf16 v[120:123], v[182:185], v[190:193], v[120:123]
	v_mfma_f32_16x16x32_bf16 v[116:119], v[174:177], v[198:201], v[116:119]
	v_mfma_f32_16x16x32_bf16 v[112:115], v[182:185], v[198:201], v[112:115]
	v_mfma_f32_16x16x32_bf16 v[108:111], v[174:177], v[208:211], v[108:111]
	v_mfma_f32_16x16x32_bf16 v[104:107], v[182:185], v[208:211], v[104:107]
	v_mfma_f32_16x16x32_bf16 v[100:103], v[174:177], v[218:221], v[100:103]
	v_mfma_f32_16x16x32_bf16 v[96:99], v[182:185], v[218:221], v[96:99]
	s_barrier
	v_readfirstlane_b32 s54, v164
	v_add_u32_e32 v134, 0x2000, v164
	v_lshl_add_u64 v[246:247], v[242:243], 0, s[94:95]
	s_mov_b32 m0, s54
	v_readfirstlane_b32 s54, v134
	ds_read_b128 v[222:225], v163
	ds_read_b128 v[226:229], v163 offset:1024
	ds_read_b128 v[230:233], v163 offset:2048
	ds_read_b128 v[234:237], v163 offset:3072
	global_load_lds_dwordx4 v[246:247], off
	v_lshl_add_u64 v[246:247], v[244:245], 0, s[94:95]
	s_mov_b32 m0, s54
	s_nop 0
	global_load_lds_dwordx4 v[246:247], off
	s_barrier
	s_waitcnt lgkmcnt(0)
	s_waitcnt lgkmcnt(0)
	v_mfma_f32_16x16x32_bf16 v[92:95], v[222:225], v[186:189], v[92:95]
	v_mfma_f32_16x16x32_bf16 v[88:91], v[230:233], v[186:189], v[88:91]
	v_mfma_f32_16x16x32_bf16 v[84:87], v[222:225], v[194:197], v[84:87]
	v_mfma_f32_16x16x32_bf16 v[80:83], v[230:233], v[194:197], v[80:83]
	v_mfma_f32_16x16x32_bf16 v[76:79], v[222:225], v[202:205], v[76:79]
	v_mfma_f32_16x16x32_bf16 v[72:75], v[230:233], v[202:205], v[72:75]
	v_mfma_f32_16x16x32_bf16 v[68:71], v[222:225], v[214:217], v[68:71]
	v_mfma_f32_16x16x32_bf16 v[64:67], v[230:233], v[214:217], v[64:67]
	v_mfma_f32_16x16x32_bf16 v[92:95], v[226:229], v[190:193], v[92:95]
	v_mfma_f32_16x16x32_bf16 v[88:91], v[234:237], v[190:193], v[88:91]
	v_mfma_f32_16x16x32_bf16 v[84:87], v[226:229], v[198:201], v[84:87]
	v_mfma_f32_16x16x32_bf16 v[80:83], v[234:237], v[198:201], v[80:83]
	v_mfma_f32_16x16x32_bf16 v[76:79], v[226:229], v[208:211], v[76:79]
	v_mfma_f32_16x16x32_bf16 v[72:75], v[234:237], v[208:211], v[72:75]
	v_mfma_f32_16x16x32_bf16 v[68:71], v[226:229], v[218:221], v[68:71]
	v_mfma_f32_16x16x32_bf16 v[64:67], v[234:237], v[218:221], v[64:67]
	v_readfirstlane_b32 s54, v166
	v_lshl_add_u64 v[238:239], v[238:239], 0, s[4:5]
	s_mov_b32 m0, s54
	v_readfirstlane_b32 s54, v167
	s_barrier
	ds_read_b128 v[186:189], v162 offset:49152
	ds_read_b128 v[190:193], v162 offset:50176
	ds_read_b128 v[194:197], v161 offset:49152
	ds_read_b128 v[198:201], v161 offset:50176
	ds_read_b128 v[202:205], v160 offset:49152
	ds_read_b128 v[208:211], v160 offset:50176
	ds_read_b128 v[214:217], v159 offset:49152
	ds_read_b128 v[218:221], v159 offset:50176
	global_load_lds_dwordx4 v[238:239], off
	v_lshl_add_u64 v[238:239], v[240:241], 0, s[4:5]
	s_mov_b32 m0, s54
	s_nop 0
	global_load_lds_dwordx4 v[238:239], off
	s_barrier
; #define STAGE(P, BASE, br, kt) STAGET(tid_, P, BASE, br, kt)
; #define LDA(dst, b, h) UFOR(m, 4) UFOR(k, 2) \
;     dst[m][k] = *reinterpret_cast<const bf16x8*>((char*)SA(b, h) + lds_byte(wr * 64 + m * 16 + fr, k * 32 + fq * 8))
; #define LDB(dst, b, h) UFOR(n, 2) UFOR(k, 2) \
;     dst[n][k] = *reinterpret_cast<const bf16x8*>((char*)SB(b, h) + lds_byte(wc * 32 + n * 16 + fr, k * 32 + fq * 8))
; #define MMA(ai, bj, At, Bq) do { __builtin_amdgcn_s_setprio(1); \
;     UFOR(m, 4) UFOR(n, 2) UFOR(k, 2) \
;       acc[ai][bj][m][n] = __builtin_amdgcn_mfma_f32_16x16x32_bf16(Bq[n][k], At[m][k], acc[ai][bj][m][n], 0, 0, 0); \
;     __builtin_amdgcn_s_setprio(0); } while (0)
; #define WAIT_V(n) asm volatile("s_waitcnt vmcnt(" #n ")" ::: "memory")
; #define WAIT_L(n) asm volatile("s_waitcnt lgkmcnt(" #n ")" ::: "memory")
; #define BAR __builtin_amdgcn_s_barrier()
; #define SCHED __builtin_amdgcn_sched_barrier(0)
; template <int EPI, int K, int KL> ...
;     ...
;     BAR; WAIT_L(0); MMA(1, 0, At, B0); BAR; SCHED;
;     STAGE(SB(1, 1), Bt, bcol + HALF, t + 3);
;     WAIT_V(6); BAR; MMA(1, 1, At, B1); BAR;
;   }
;   { LDB(B0, 0, 0); LDA(At, 0, 0); STAGE(SA(1, 1), A, brow + HALF, nt - 1);
;     BAR; WAIT_L(0); MMA(0, 0, At, B0); BAR;
;     LDB(B1, 0, 1); BAR; WAIT_L(0); MMA(0, 1, At, B1); BAR;
	s_waitcnt lgkmcnt(0)
	s_waitcnt lgkmcnt(0)
	v_mfma_f32_16x16x32_bf16 v[60:63], v[136:139], v[186:189], v[60:63]
	v_mfma_f32_16x16x32_bf16 v[56:59], v[178:181], v[186:189], v[56:59]
	v_mfma_f32_16x16x32_bf16 v[52:55], v[136:139], v[194:197], v[52:55]
	v_mfma_f32_16x16x32_bf16 v[48:51], v[178:181], v[194:197], v[48:51]
	v_mfma_f32_16x16x32_bf16 v[44:47], v[136:139], v[202:205], v[44:47]
	v_mfma_f32_16x16x32_bf16 v[40:43], v[178:181], v[202:205], v[40:43]
	v_mfma_f32_16x16x32_bf16 v[36:39], v[136:139], v[214:217], v[36:39]
	v_mfma_f32_16x16x32_bf16 v[32:35], v[178:181], v[214:217], v[32:35]
	v_mfma_f32_16x16x32_bf16 v[60:63], v[174:177], v[190:193], v[60:63]
	v_mfma_f32_16x16x32_bf16 v[56:59], v[182:185], v[190:193], v[56:59]
	v_mfma_f32_16x16x32_bf16 v[52:55], v[174:177], v[198:201], v[52:55]
	v_mfma_f32_16x16x32_bf16 v[48:51], v[182:185], v[198:201], v[48:51]
	v_mfma_f32_16x16x32_bf16 v[44:47], v[174:177], v[208:211], v[44:47]
	v_mfma_f32_16x16x32_bf16 v[40:43], v[182:185], v[208:211], v[40:43]
	v_mfma_f32_16x16x32_bf16 v[36:39], v[174:177], v[218:221], v[36:39]
	v_mfma_f32_16x16x32_bf16 v[32:35], v[182:185], v[218:221], v[32:35]
	s_barrier
	v_readfirstlane_b32 s54, v168
	v_add_u32_e32 v134, 0x2000, v168
	v_lshl_add_u64 v[136:137], v[242:243], 0, s[10:11]
	s_mov_b32 m0, s54
	v_readfirstlane_b32 s54, v134
	global_load_lds_dwordx4 v[136:137], off
	v_lshl_add_u64 v[136:137], v[244:245], 0, s[10:11]
	s_mov_b32 m0, s54
	s_nop 0
	global_load_lds_dwordx4 v[136:137], off
	s_waitcnt vmcnt(6)
	s_barrier
	v_mfma_f32_16x16x32_bf16 v[28:31], v[222:225], v[186:189], v[28:31]
	v_mfma_f32_16x16x32_bf16 v[24:27], v[230:233], v[186:189], v[24:27]
	v_mfma_f32_16x16x32_bf16 v[20:23], v[222:225], v[194:197], v[20:23]
	v_mfma_f32_16x16x32_bf16 v[16:19], v[230:233], v[194:197], v[16:19]
	v_mfma_f32_16x16x32_bf16 v[12:15], v[222:225], v[202:205], v[12:15]
	v_mfma_f32_16x16x32_bf16 v[8:11], v[230:233], v[202:205], v[8:11]
	v_mfma_f32_16x16x32_bf16 v[4:7], v[222:225], v[214:217], v[4:7]
	v_mfma_f32_16x16x32_bf16 v[0:3], v[230:233], v[214:217], v[0:3]
	v_mfma_f32_16x16x32_bf16 v[28:31], v[226:229], v[190:193], v[28:31]
	v_mfma_f32_16x16x32_bf16 v[24:27], v[234:237], v[190:193], v[24:27]
	v_mfma_f32_16x16x32_bf16 v[20:23], v[226:229], v[198:201], v[20:23]
	v_mfma_f32_16x16x32_bf16 v[16:19], v[234:237], v[198:201], v[16:19]
	v_mfma_f32_16x16x32_bf16 v[12:15], v[226:229], v[208:211], v[12:15]
	v_mfma_f32_16x16x32_bf16 v[8:11], v[234:237], v[208:211], v[8:11]
	v_mfma_f32_16x16x32_bf16 v[4:7], v[226:229], v[218:221], v[4:7]
	v_mfma_f32_16x16x32_bf16 v[0:3], v[234:237], v[218:221], v[0:3]
	s_add_i32 s19, s19, 2
	v_lshl_add_u64 v[144:145], v[144:145], 0, s[20:21]
	v_lshl_add_u64 v[146:147], v[146:147], 0, s[20:21]
	v_lshl_add_u64 v[148:149], v[148:149], 0, s[20:21]
	s_cmpk_lt_u32 s19, 0x54
	v_lshl_add_u64 v[150:151], v[150:151], 0, s[20:21]
	s_barrier
	s_cbranch_scc1 .LBB0_1184
	s_add_u32 s52, s52, 0x162b80
	s_addc_u32 s53, s53, 0
	v_lshl_add_u64 v[130:131], s[52:53], 0, v[130:131]
	v_readfirstlane_b32 s19, v171
	v_lshl_add_u64 v[128:129], v[128:129], 1, v[130:131]
	s_mov_b32 m0, s19
	ds_read_b128 v[136:139], v170
	ds_read_b128 v[144:147], v170 offset:1024
	ds_read_b128 v[148:151], v170 offset:2048
	ds_read_b128 v[174:177], v170 offset:3072
	ds_read_b128 v[178:181], v162
	ds_read_b128 v[182:185], v162 offset:1024
	ds_read_b128 v[186:189], v161
	ds_read_b128 v[190:193], v161 offset:1024
	ds_read_b128 v[194:197], v160
	ds_read_b128 v[198:201], v160 offset:1024
	ds_read_b128 v[202:205], v159
	ds_read_b128 v[208:211], v159 offset:1024
	global_load_lds_dwordx4 v[128:129], off
	v_lshl_add_u64 v[128:129], s[52:53], 0, v[142:143]
	v_readfirstlane_b32 s19, v172
	v_lshl_add_u64 v[128:129], v[140:141], 1, v[128:129]
	s_mov_b32 m0, s19
	s_nop 0
	global_load_lds_dwordx4 v[128:129], off
	s_barrier
	s_waitcnt lgkmcnt(0)
	s_waitcnt lgkmcnt(0)
	v_mfma_f32_16x16x32_bf16 v[120:123], v[148:151], v[178:181], v[120:123]
	v_mfma_f32_16x16x32_bf16 v[116:119], v[136:139], v[186:189], v[116:119]
	v_mfma_f32_16x16x32_bf16 v[112:115], v[148:151], v[186:189], v[112:115]
	v_mfma_f32_16x16x32_bf16 v[108:111], v[136:139], v[194:197], v[108:111]
	v_mfma_f32_16x16x32_bf16 v[104:107], v[148:151], v[194:197], v[104:107]
	v_mfma_f32_16x16x32_bf16 v[100:103], v[136:139], v[202:205], v[100:103]
	v_mfma_f32_16x16x32_bf16 v[96:99], v[148:151], v[202:205], v[96:99]
	v_mfma_f32_16x16x32_bf16 v[124:127], v[136:139], v[178:181], v[124:127]
	v_mfma_f32_16x16x32_bf16 v[120:123], v[174:177], v[182:185], v[120:123]
	v_mfma_f32_16x16x32_bf16 v[116:119], v[144:147], v[190:193], v[116:119]
	v_mfma_f32_16x16x32_bf16 v[112:115], v[174:177], v[190:193], v[112:115]
	v_mfma_f32_16x16x32_bf16 v[108:111], v[144:147], v[198:201], v[108:111]
	v_mfma_f32_16x16x32_bf16 v[104:107], v[174:177], v[198:201], v[104:107]
	v_mfma_f32_16x16x32_bf16 v[100:103], v[144:147], v[208:211], v[100:103]
	v_mfma_f32_16x16x32_bf16 v[96:99], v[174:177], v[208:211], v[96:99]
	v_mfma_f32_16x16x32_bf16 v[124:127], v[144:147], v[182:185], v[124:127]
	s_barrier
	ds_read_b128 v[128:131], v169
	ds_read_b128 v[140:143], v169 offset:1024
	ds_read_b128 v[170:173], v169 offset:2048
	ds_read_b128 v[166:169], v169 offset:3072
	s_barrier
; #define LDA(dst, b, h) UFOR(m, 4) UFOR(k, 2) \
;     dst[m][k] = *reinterpret_cast<const bf16x8*>((char*)SA(b, h) + lds_byte(wr * 64 + m * 16 + fr, k * 32 + fq * 8))
; #define LDB(dst, b, h) UFOR(n, 2) UFOR(k, 2) \
;     dst[n][k] = *reinterpret_cast<const bf16x8*>((char*)SB(b, h) + lds_byte(wc * 32 + n * 16 + fr, k * 32 + fq * 8))
; #define MMA(ai, bj, At, Bq) do { __builtin_amdgcn_s_setprio(1); \
;     UFOR(m, 4) UFOR(n, 2) UFOR(k, 2) \
;       acc[ai][bj][m][n] = __builtin_amdgcn_mfma_f32_16x16x32_bf16(Bq[n][k], At[m][k], acc[ai][bj][m][n], 0, 0, 0); \
;     __builtin_amdgcn_s_setprio(0); } while (0)
; #define WAIT_V(n) asm volatile("s_waitcnt vmcnt(" #n ")" ::: "memory")
; #define WAIT_L(n) asm volatile("s_waitcnt lgkmcnt(" #n ")" ::: "memory")
; #define BAR __builtin_amdgcn_s_barrier()
; template <int EPI, int K, int KL> ...
;     ...
;     LDB(B1, 0, 1); BAR; WAIT_L(0); MMA(0, 1, At, B1); BAR;
;     LDA(At, 0, 1); WAIT_V(4); BAR; WAIT_L(0); MMA(1, 0, At, B0); MMA(1, 1, At, B1); BAR; }
;   { LDB(B0, 1, 0); LDA(At, 1, 0); WAIT_V(2); BAR; WAIT_L(0); MMA(0, 0, At, B0); BAR;
	s_waitcnt lgkmcnt(0)
	s_waitcnt lgkmcnt(0)
	v_mfma_f32_16x16x32_bf16 v[80:83], v[170:173], v[186:189], v[80:83]
	v_mfma_f32_16x16x32_bf16 v[76:79], v[128:131], v[194:197], v[76:79]
	v_mfma_f32_16x16x32_bf16 v[68:71], v[128:131], v[202:205], v[68:71]
	v_mfma_f32_16x16x32_bf16 v[64:67], v[170:173], v[202:205], v[64:67]
	v_mfma_f32_16x16x32_bf16 v[92:95], v[128:131], v[178:181], v[92:95]
	v_mfma_f32_16x16x32_bf16 v[88:91], v[170:173], v[178:181], v[88:91]
	v_mfma_f32_16x16x32_bf16 v[84:87], v[128:131], v[186:189], v[84:87]
	v_mfma_f32_16x16x32_bf16 v[80:83], v[166:169], v[190:193], v[80:83]
	v_mfma_f32_16x16x32_bf16 v[76:79], v[140:143], v[198:201], v[76:79]
	v_mfma_f32_16x16x32_bf16 v[72:75], v[170:173], v[194:197], v[72:75]
	v_mfma_f32_16x16x32_bf16 v[68:71], v[140:143], v[208:211], v[68:71]
	v_mfma_f32_16x16x32_bf16 v[64:67], v[166:169], v[208:211], v[64:67]
	v_mfma_f32_16x16x32_bf16 v[214:217], v[140:143], v[182:185], v[92:95]
	v_mfma_f32_16x16x32_bf16 v[178:181], v[166:169], v[182:185], v[88:91]
	v_mfma_f32_16x16x32_bf16 v[182:185], v[140:143], v[190:193], v[84:87]
	v_mfma_f32_16x16x32_bf16 v[186:189], v[166:169], v[198:201], v[72:75]
	s_barrier
	s_nop 0
	ds_read_b128 v[72:75], v162 offset:16384
	ds_read_b128 v[84:87], v162 offset:17408
	ds_read_b128 v[88:91], v161 offset:16384
	ds_read_b128 v[92:95], v161 offset:17408
	ds_read_b128 v[190:193], v160 offset:16384
	ds_read_b128 v[194:197], v160 offset:17408
	ds_read_b128 v[198:201], v159 offset:16384
	ds_read_b128 v[202:205], v159 offset:17408
	s_waitcnt vmcnt(4)
	s_barrier
	s_waitcnt lgkmcnt(0)
	s_waitcnt lgkmcnt(0)
	v_mfma_f32_16x16x32_bf16 v[48:51], v[148:151], v[88:91], v[48:51]
	v_mfma_f32_16x16x32_bf16 v[40:43], v[148:151], v[190:193], v[40:43]
	v_mfma_f32_16x16x32_bf16 v[36:39], v[136:139], v[198:201], v[36:39]
	v_mfma_f32_16x16x32_bf16 v[32:35], v[148:151], v[198:201], v[32:35]
	v_mfma_f32_16x16x32_bf16 v[60:63], v[136:139], v[72:75], v[60:63]
	v_mfma_f32_16x16x32_bf16 v[56:59], v[148:151], v[72:75], v[56:59]
	v_mfma_f32_16x16x32_bf16 v[52:55], v[136:139], v[88:91], v[52:55]
	v_mfma_f32_16x16x32_bf16 v[48:51], v[174:177], v[92:95], v[48:51]
	v_mfma_f32_16x16x32_bf16 v[44:47], v[136:139], v[190:193], v[44:47]
	v_mfma_f32_16x16x32_bf16 v[40:43], v[174:177], v[194:197], v[40:43]
	v_mfma_f32_16x16x32_bf16 v[36:39], v[144:147], v[202:205], v[36:39]
	v_mfma_f32_16x16x32_bf16 v[32:35], v[174:177], v[202:205], v[32:35]
	v_mfma_f32_16x16x32_bf16 v[208:211], v[144:147], v[84:87], v[60:63]
	v_mfma_f32_16x16x32_bf16 v[218:221], v[174:177], v[84:87], v[56:59]
	v_mfma_f32_16x16x32_bf16 v[222:225], v[144:147], v[92:95], v[52:55]
	v_mfma_f32_16x16x32_bf16 v[226:229], v[144:147], v[194:197], v[44:47]
	v_mfma_f32_16x16x32_bf16 v[0:3], v[170:173], v[198:201], v[0:3]
	v_mfma_f32_16x16x32_bf16 v[28:31], v[128:131], v[72:75], v[28:31]
	v_mfma_f32_16x16x32_bf16 v[24:27], v[170:173], v[72:75], v[24:27]
	v_mfma_f32_16x16x32_bf16 v[20:23], v[128:131], v[88:91], v[20:23]
	v_mfma_f32_16x16x32_bf16 v[16:19], v[170:173], v[88:91], v[16:19]
	v_mfma_f32_16x16x32_bf16 v[12:15], v[128:131], v[190:193], v[12:15]
	v_mfma_f32_16x16x32_bf16 v[8:11], v[170:173], v[190:193], v[8:11]
	v_mfma_f32_16x16x32_bf16 v[4:7], v[128:131], v[198:201], v[4:7]
	v_mfma_f32_16x16x32_bf16 v[0:3], v[166:169], v[202:205], v[0:3]
	v_mfma_f32_16x16x32_bf16 v[136:139], v[140:143], v[84:87], v[28:31]
	v_mfma_f32_16x16x32_bf16 v[144:147], v[166:169], v[84:87], v[24:27]
	v_mfma_f32_16x16x32_bf16 v[148:151], v[140:143], v[92:95], v[20:23]
	v_mfma_f32_16x16x32_bf16 v[174:177], v[166:169], v[92:95], v[16:19]
	v_mfma_f32_16x16x32_bf16 v[230:233], v[140:143], v[194:197], v[12:15]
	v_mfma_f32_16x16x32_bf16 v[190:193], v[166:169], v[194:197], v[8:11]
	v_mfma_f32_16x16x32_bf16 v[140:143], v[140:143], v[202:205], v[4:7]
	s_barrier
	s_nop 0
	ds_read_b128 v[4:7], v165
	ds_read_b128 v[8:11], v165 offset:1024
	ds_read_b128 v[16:19], v165 offset:2048
	ds_read_b128 v[164:167], v165 offset:3072
	ds_read_b128 v[12:15], v162 offset:32768
	ds_read_b128 v[20:23], v162 offset:33792
	ds_read_b128 v[24:27], v161 offset:32768
	ds_read_b128 v[44:47], v161 offset:33792
	ds_read_b128 v[168:171], v160 offset:32768
	ds_read_b128 v[194:197], v160 offset:33792
	ds_read_b128 v[198:201], v159 offset:32768
	ds_read_b128 v[202:205], v159 offset:33792
	s_waitcnt vmcnt(2)
	s_barrier
; #define LDA(dst, b, h) UFOR(m, 4) UFOR(k, 2) \
;     dst[m][k] = *reinterpret_cast<const bf16x8*>((char*)SA(b, h) + lds_byte(wr * 64 + m * 16 + fr, k * 32 + fq * 8))
; #define LDB(dst, b, h) UFOR(n, 2) UFOR(k, 2) \
;     dst[n][k] = *reinterpret_cast<const bf16x8*>((char*)SB(b, h) + lds_byte(wc * 32 + n * 16 + fr, k * 32 + fq * 8))
; #define MMA(ai, bj, At, Bq) do { __builtin_amdgcn_s_setprio(1); \
;     UFOR(m, 4) UFOR(n, 2) UFOR(k, 2) \
;       acc[ai][bj][m][n] = __builtin_amdgcn_mfma_f32_16x16x32_bf16(Bq[n][k], At[m][k], acc[ai][bj][m][n], 0, 0, 0); \
;     __builtin_amdgcn_s_setprio(0); } while (0)
; #define WAIT_V(n) asm volatile("s_waitcnt vmcnt(" #n ")" ::: "memory")
; #define WAIT_L(n) asm volatile("s_waitcnt lgkmcnt(" #n ")" ::: "memory")
; #define BAR __builtin_amdgcn_s_barrier()
; template <int EPI, int K, int KL> ...
;     ...
;   { LDB(B0, 1, 0); LDA(At, 1, 0); WAIT_V(2); BAR; WAIT_L(0); MMA(0, 0, At, B0); BAR;
;     LDB(B1, 1, 1); WAIT_V(0); BAR; WAIT_L(0); MMA(0, 1, At, B1); BAR;
;     LDA(At, 1, 1); BAR; WAIT_L(0); MMA(1, 0, At, B0); MMA(1, 1, At, B1); BAR; }
;   if (wr == 0) BAR;
;   if (EPI != EPI_UPG && EPI != EPI_PART && has_next) {
	s_waitcnt lgkmcnt(0)
	s_waitcnt lgkmcnt(0)
	v_mfma_f32_16x16x32_bf16 v[28:31], v[4:7], v[12:15], v[124:127]
	v_mfma_f32_16x16x32_bf16 v[128:131], v[8:11], v[20:23], v[28:31]
	v_mfma_f32_16x16x32_bf16 v[28:31], v[16:19], v[12:15], v[120:123]
	v_mfma_f32_16x16x32_bf16 v[92:95], v[164:167], v[20:23], v[28:31]
	v_mfma_f32_16x16x32_bf16 v[28:31], v[4:7], v[24:27], v[116:119]
	v_mfma_f32_16x16x32_bf16 v[120:123], v[8:11], v[44:47], v[28:31]
	v_mfma_f32_16x16x32_bf16 v[28:31], v[16:19], v[24:27], v[112:115]
	v_mfma_f32_16x16x32_bf16 v[88:91], v[164:167], v[44:47], v[28:31]
	v_mfma_f32_16x16x32_bf16 v[28:31], v[4:7], v[168:171], v[108:111]
	v_mfma_f32_16x16x32_bf16 v[116:119], v[8:11], v[194:197], v[28:31]
	v_mfma_f32_16x16x32_bf16 v[28:31], v[16:19], v[168:171], v[104:107]
	v_mfma_f32_16x16x32_bf16 v[84:87], v[164:167], v[194:197], v[28:31]
	v_mfma_f32_16x16x32_bf16 v[28:31], v[4:7], v[198:201], v[100:103]
	v_mfma_f32_16x16x32_bf16 v[108:111], v[8:11], v[202:205], v[28:31]
	v_mfma_f32_16x16x32_bf16 v[28:31], v[16:19], v[198:201], v[96:99]
	v_mfma_f32_16x16x32_bf16 v[72:75], v[164:167], v[202:205], v[28:31]
	s_barrier
	ds_read_b128 v[124:127], v163
	ds_read_b128 v[234:237], v163 offset:1024
	ds_read_b128 v[238:241], v163 offset:2048
	ds_read_b128 v[242:245], v163 offset:3072
	s_waitcnt vmcnt(0)
	s_barrier
	s_waitcnt lgkmcnt(0)
	s_waitcnt lgkmcnt(0)
	v_mfma_f32_16x16x32_bf16 v[28:31], v[124:127], v[12:15], v[214:217]
	v_mfma_f32_16x16x32_bf16 v[12:15], v[238:241], v[12:15], v[178:181]
	v_mfma_f32_16x16x32_bf16 v[60:63], v[234:237], v[20:23], v[28:31]
	v_mfma_f32_16x16x32_bf16 v[28:31], v[242:245], v[20:23], v[12:15]
	v_mfma_f32_16x16x32_bf16 v[12:15], v[124:127], v[24:27], v[182:185]
	v_mfma_f32_16x16x32_bf16 v[56:59], v[234:237], v[44:47], v[12:15]
	v_mfma_f32_16x16x32_bf16 v[12:15], v[238:241], v[24:27], v[80:83]
	v_mfma_f32_16x16x32_bf16 v[24:27], v[242:245], v[44:47], v[12:15]
	v_mfma_f32_16x16x32_bf16 v[12:15], v[124:127], v[168:171], v[76:79]
	v_mfma_f32_16x16x32_bf16 v[52:55], v[234:237], v[194:197], v[12:15]
	v_mfma_f32_16x16x32_bf16 v[12:15], v[238:241], v[168:171], v[186:189]
	v_mfma_f32_16x16x32_bf16 v[20:23], v[242:245], v[194:197], v[12:15]
	v_mfma_f32_16x16x32_bf16 v[12:15], v[124:127], v[198:201], v[68:71]
	v_mfma_f32_16x16x32_bf16 v[44:47], v[234:237], v[202:205], v[12:15]
	v_mfma_f32_16x16x32_bf16 v[12:15], v[238:241], v[198:201], v[64:67]
	v_mfma_f32_16x16x32_bf16 v[12:15], v[242:245], v[202:205], v[12:15]
	s_barrier
	ds_read_b128 v[168:171], v162 offset:49152
	ds_read_b128 v[178:181], v162 offset:50176
	ds_read_b128 v[182:185], v161 offset:49152
	ds_read_b128 v[186:189], v161 offset:50176
	ds_read_b128 v[194:197], v160 offset:49152
	ds_read_b128 v[160:163], v160 offset:50176
	ds_read_b128 v[198:201], v159 offset:49152
	ds_read_b128 v[156:159], v159 offset:50176
	s_barrier
	s_waitcnt lgkmcnt(0)
	s_waitcnt lgkmcnt(0)
	v_mfma_f32_16x16x32_bf16 v[64:67], v[4:7], v[168:171], v[208:211]
	v_mfma_f32_16x16x32_bf16 v[112:115], v[8:11], v[178:181], v[64:67]
	v_mfma_f32_16x16x32_bf16 v[64:67], v[16:19], v[168:171], v[218:221]
	v_mfma_f32_16x16x32_bf16 v[48:51], v[16:19], v[182:185], v[48:51]
	v_mfma_f32_16x16x32_bf16 v[80:83], v[164:167], v[178:181], v[64:67]
	v_mfma_f32_16x16x32_bf16 v[64:67], v[4:7], v[182:185], v[222:225]
	v_mfma_f32_16x16x32_bf16 v[76:79], v[164:167], v[186:189], v[48:51]
	v_mfma_f32_16x16x32_bf16 v[48:51], v[4:7], v[194:197], v[226:229]
	v_mfma_f32_16x16x32_bf16 v[4:7], v[4:7], v[198:201], v[36:39]
	v_mfma_f32_16x16x32_bf16 v[40:43], v[16:19], v[194:197], v[40:43]
	v_mfma_f32_16x16x32_bf16 v[96:99], v[8:11], v[156:159], v[4:7]
	v_mfma_f32_16x16x32_bf16 v[4:7], v[16:19], v[198:201], v[32:35]
	v_mfma_f32_16x16x32_bf16 v[104:107], v[8:11], v[186:189], v[64:67]
	v_mfma_f32_16x16x32_bf16 v[100:103], v[8:11], v[160:163], v[48:51]
	v_mfma_f32_16x16x32_bf16 v[68:71], v[164:167], v[160:163], v[40:43]
	v_mfma_f32_16x16x32_bf16 v[64:67], v[164:167], v[156:159], v[4:7]
	v_mfma_f32_16x16x32_bf16 v[4:7], v[124:127], v[168:171], v[136:139]
	v_mfma_f32_16x16x32_bf16 v[48:51], v[234:237], v[178:181], v[4:7]
	v_mfma_f32_16x16x32_bf16 v[4:7], v[238:241], v[168:171], v[144:147]
	v_mfma_f32_16x16x32_bf16 v[16:19], v[242:245], v[178:181], v[4:7]
	v_mfma_f32_16x16x32_bf16 v[4:7], v[124:127], v[182:185], v[148:151]
	v_mfma_f32_16x16x32_bf16 v[40:43], v[234:237], v[186:189], v[4:7]
	v_mfma_f32_16x16x32_bf16 v[4:7], v[238:241], v[182:185], v[174:177]
	v_mfma_f32_16x16x32_bf16 v[8:11], v[242:245], v[186:189], v[4:7]
	v_mfma_f32_16x16x32_bf16 v[4:7], v[124:127], v[194:197], v[230:233]
	v_mfma_f32_16x16x32_bf16 v[36:39], v[234:237], v[160:163], v[4:7]
	v_mfma_f32_16x16x32_bf16 v[4:7], v[238:241], v[194:197], v[190:193]
	v_mfma_f32_16x16x32_bf16 v[32:35], v[124:127], v[198:201], v[140:143]
	v_mfma_f32_16x16x32_bf16 v[0:3], v[238:241], v[198:201], v[0:3]
	v_mfma_f32_16x16x32_bf16 v[4:7], v[242:245], v[160:163], v[4:7]
	v_mfma_f32_16x16x32_bf16 v[32:35], v[234:237], v[156:159], v[32:35]
	v_mfma_f32_16x16x32_bf16 v[0:3], v[242:245], v[156:159], v[0:3]
	s_movk_i32 s19, 0x100
	v_cmp_gt_u32_e32 vcc, s19, v154
	s_barrier
	s_and_saveexec_b64 s[52:53], vcc
	s_cbranch_execnz .LBB0_1189
	s_or_b64 exec, exec, s[52:53]
	s_andn2_b64 vcc, exec, s[50:51]
	s_cbranch_vccz .LBB0_1190

; #define STAGE(P, BASE, br, kt) STAGET(tid_, P, BASE, br, kt)
; #define LDA(dst, b, h) UFOR(m, 4) UFOR(k, 2) \
;     dst[m][k] = *reinterpret_cast<const bf16x8*>((char*)SA(b, h) + lds_byte(wr * 64 + m * 16 + fr, k * 32 + fq * 8))
; #define LDB(dst, b, h) UFOR(n, 2) UFOR(k, 2) \
;     dst[n][k] = *reinterpret_cast<const bf16x8*>((char*)SB(b, h) + lds_byte(wc * 32 + n * 16 + fr, k * 32 + fq * 8))
; #define MMA(ai, bj, At, Bq) do { __builtin_amdgcn_s_setprio(1); \
;     UFOR(m, 4) UFOR(n, 2) UFOR(k, 2) \
;       acc[ai][bj][m][n] = __builtin_amdgcn_mfma_f32_16x16x32_bf16(Bq[n][k], At[m][k], acc[ai][bj][m][n], 0, 0, 0); \
;     __builtin_amdgcn_s_setprio(0); } while (0)
; #define WAIT_L(n) asm volatile("s_waitcnt lgkmcnt(" #n ")" ::: "memory")
; #define BAR __builtin_amdgcn_s_barrier()
; #define SCHED __builtin_amdgcn_sched_barrier(0)
; template <int EPI, int K, int KL> ...
;     ...
;     LDB(B0, 0, 0); SCHED; LDA(At, 0, 0); STAGE(SA(1, 1), A, brow + HALF, t + 1);
;     WAIT_L(8); BAR; WAIT_L(0); MMA(0, 0, At, B0); BAR; SCHED;
;     LDB(B1, 0, 1); STAGE(SB(0, 0), Bt, bcol, t + 2);
;     BAR; WAIT_L(0); MMA(0, 1, At, B1); BAR;
;     LDA(At, 0, 1); STAGE(SA(0, 0), A, brow, t + 2);
;     BAR; WAIT_L(0); MMA(1, 0, At, B0); BAR; SCHED;
; __device__ __forceinline__ void gemm_ctx_splitk_down(const u16* A, const u16* Bt, float* P2, const EpiArgs& e0) {
;     ...
;     EpiArgs e = e0; e.part = P2 + (size_t)part * 512 * DM;
;     const long koff = (long)part * (DFF / P2_PARTS);
;     gemm_tile<EPI_PART, DFF, DFF / P2_PARTS>(A + koff, Bt + koff, (long)pm * BM, pn * BM, pn, 0, 0, e, true, false, 0, 0);
.LBB0_1204:
	ds_read_b128 v[136:139], v175
	ds_read_b128 v[178:181], v175 offset:1024
	ds_read_b128 v[182:185], v175 offset:2048
	ds_read_b128 v[186:189], v175 offset:3072
	v_add_u32_e32 v176, 0xc000, v161
	v_lshl_add_u64 v[152:153], v[148:149], 0, s[44:45]
	v_readfirstlane_b32 s15, v176
	v_lshl_add_u64 v[154:155], v[152:153], 0, s[58:59]
	s_mov_b32 m0, s15
	v_add_u32_e32 v177, 0xe000, v161
	ds_read_b128 v[190:193], v160
	ds_read_b128 v[194:197], v160 offset:1024
	ds_read_b128 v[198:201], v159
	ds_read_b128 v[202:205], v159 offset:1024
	ds_read_b128 v[208:211], v158
	ds_read_b128 v[214:217], v158 offset:1024
	ds_read_b128 v[218:221], v157
	ds_read_b128 v[222:225], v157 offset:1024
	global_load_lds_dwordx4 v[154:155], off
	v_lshl_add_u64 v[154:155], v[150:151], 0, s[44:45]
	v_readfirstlane_b32 s15, v177
	v_lshl_add_u64 v[226:227], v[154:155], 0, s[58:59]
	s_mov_b32 m0, s15
	s_nop 0
	global_load_lds_dwordx4 v[226:227], off
	s_waitcnt lgkmcnt(8)
	s_barrier
	s_waitcnt lgkmcnt(0)
	s_waitcnt lgkmcnt(0)
	v_mfma_f32_16x16x32_bf16 v[124:127], v[136:139], v[190:193], v[124:127]
	v_mfma_f32_16x16x32_bf16 v[120:123], v[182:185], v[190:193], v[120:123]
	v_mfma_f32_16x16x32_bf16 v[116:119], v[136:139], v[198:201], v[116:119]
	v_mfma_f32_16x16x32_bf16 v[112:115], v[182:185], v[198:201], v[112:115]
	v_mfma_f32_16x16x32_bf16 v[108:111], v[136:139], v[208:211], v[108:111]
	v_mfma_f32_16x16x32_bf16 v[104:107], v[182:185], v[208:211], v[104:107]
	v_mfma_f32_16x16x32_bf16 v[100:103], v[136:139], v[218:221], v[100:103]
	v_mfma_f32_16x16x32_bf16 v[96:99], v[182:185], v[218:221], v[96:99]
	v_mfma_f32_16x16x32_bf16 v[124:127], v[178:181], v[194:197], v[124:127]
	v_mfma_f32_16x16x32_bf16 v[120:123], v[186:189], v[194:197], v[120:123]
	v_mfma_f32_16x16x32_bf16 v[116:119], v[178:181], v[202:205], v[116:119]
	v_mfma_f32_16x16x32_bf16 v[112:115], v[186:189], v[202:205], v[112:115]
	v_mfma_f32_16x16x32_bf16 v[108:111], v[178:181], v[214:217], v[108:111]
	v_mfma_f32_16x16x32_bf16 v[104:107], v[186:189], v[214:217], v[104:107]
	v_mfma_f32_16x16x32_bf16 v[100:103], v[178:181], v[222:225], v[100:103]
	v_mfma_f32_16x16x32_bf16 v[96:99], v[186:189], v[222:225], v[96:99]
	s_barrier
	v_lshl_add_u64 v[242:243], v[144:145], 0, s[44:45]
	v_readfirstlane_b32 s15, v156
	v_lshl_add_u64 v[244:245], v[242:243], 0, s[22:23]
	s_mov_b32 m0, s15
	v_add_u32_e32 v248, 0x2000, v156
	ds_read_b128 v[226:229], v173
	ds_read_b128 v[230:233], v173 offset:1024
	ds_read_b128 v[234:237], v173 offset:2048
	ds_read_b128 v[238:241], v173 offset:3072
	global_load_lds_dwordx4 v[244:245], off
	v_lshl_add_u64 v[244:245], v[146:147], 0, s[44:45]
	v_readfirstlane_b32 s15, v248
	v_lshl_add_u64 v[246:247], v[244:245], 0, s[22:23]
	s_mov_b32 m0, s15
	s_nop 0
	global_load_lds_dwordx4 v[246:247], off
	s_barrier
	s_waitcnt lgkmcnt(0)
	s_waitcnt lgkmcnt(0)
	v_mfma_f32_16x16x32_bf16 v[92:95], v[226:229], v[190:193], v[92:95]
	v_mfma_f32_16x16x32_bf16 v[88:91], v[234:237], v[190:193], v[88:91]
	v_mfma_f32_16x16x32_bf16 v[84:87], v[226:229], v[198:201], v[84:87]
	v_mfma_f32_16x16x32_bf16 v[80:83], v[234:237], v[198:201], v[80:83]
	v_mfma_f32_16x16x32_bf16 v[76:79], v[226:229], v[208:211], v[76:79]
	v_mfma_f32_16x16x32_bf16 v[72:75], v[234:237], v[208:211], v[72:75]
	v_mfma_f32_16x16x32_bf16 v[68:71], v[226:229], v[218:221], v[68:71]
	v_mfma_f32_16x16x32_bf16 v[64:67], v[234:237], v[218:221], v[64:67]
	v_mfma_f32_16x16x32_bf16 v[92:95], v[230:233], v[194:197], v[92:95]
	v_mfma_f32_16x16x32_bf16 v[88:91], v[238:241], v[194:197], v[88:91]
	v_mfma_f32_16x16x32_bf16 v[84:87], v[230:233], v[202:205], v[84:87]
	v_mfma_f32_16x16x32_bf16 v[80:83], v[238:241], v[202:205], v[80:83]
	v_mfma_f32_16x16x32_bf16 v[76:79], v[230:233], v[214:217], v[76:79]
	v_mfma_f32_16x16x32_bf16 v[72:75], v[238:241], v[214:217], v[72:75]
	v_mfma_f32_16x16x32_bf16 v[68:71], v[230:233], v[222:225], v[68:71]
	v_mfma_f32_16x16x32_bf16 v[64:67], v[238:241], v[222:225], v[64:67]
	v_readfirstlane_b32 s15, v161
	v_lshl_add_u64 v[246:247], v[152:153], 0, s[60:61]
	s_mov_b32 m0, s15
	v_readfirstlane_b32 s15, v162
	s_barrier
	ds_read_b128 v[190:193], v160 offset:16384
	ds_read_b128 v[194:197], v160 offset:17408
	ds_read_b128 v[198:201], v159 offset:16384
	ds_read_b128 v[202:205], v159 offset:17408
	ds_read_b128 v[208:211], v158 offset:16384
	ds_read_b128 v[214:217], v158 offset:17408
	ds_read_b128 v[218:221], v157 offset:16384
	ds_read_b128 v[222:225], v157 offset:17408
	global_load_lds_dwordx4 v[246:247], off
	v_lshl_add_u64 v[246:247], v[154:155], 0, s[60:61]
	s_mov_b32 m0, s15
	s_nop 0
	global_load_lds_dwordx4 v[246:247], off
	s_barrier
	s_waitcnt lgkmcnt(0)
	s_waitcnt lgkmcnt(0)
	v_mfma_f32_16x16x32_bf16 v[60:63], v[136:139], v[190:193], v[60:63]
	v_mfma_f32_16x16x32_bf16 v[56:59], v[182:185], v[190:193], v[56:59]
	v_mfma_f32_16x16x32_bf16 v[52:55], v[136:139], v[198:201], v[52:55]
	v_mfma_f32_16x16x32_bf16 v[48:51], v[182:185], v[198:201], v[48:51]
	v_mfma_f32_16x16x32_bf16 v[44:47], v[136:139], v[208:211], v[44:47]
	v_mfma_f32_16x16x32_bf16 v[40:43], v[182:185], v[208:211], v[40:43]
	v_mfma_f32_16x16x32_bf16 v[36:39], v[136:139], v[218:221], v[36:39]
	v_mfma_f32_16x16x32_bf16 v[32:35], v[182:185], v[218:221], v[32:35]
	v_mfma_f32_16x16x32_bf16 v[60:63], v[178:181], v[194:197], v[60:63]
	v_mfma_f32_16x16x32_bf16 v[56:59], v[186:189], v[194:197], v[56:59]
	v_mfma_f32_16x16x32_bf16 v[52:55], v[178:181], v[202:205], v[52:55]
	v_mfma_f32_16x16x32_bf16 v[48:51], v[186:189], v[202:205], v[48:51]
	v_mfma_f32_16x16x32_bf16 v[44:47], v[178:181], v[214:217], v[44:47]
	v_mfma_f32_16x16x32_bf16 v[40:43], v[186:189], v[214:217], v[40:43]
	v_mfma_f32_16x16x32_bf16 v[36:39], v[178:181], v[222:225], v[36:39]
	v_mfma_f32_16x16x32_bf16 v[32:35], v[186:189], v[222:225], v[32:35]
	s_barrier
; #define STAGE(P, BASE, br, kt) STAGET(tid_, P, BASE, br, kt)
; #define LDA(dst, b, h) UFOR(m, 4) UFOR(k, 2) \
;     dst[m][k] = *reinterpret_cast<const bf16x8*>((char*)SA(b, h) + lds_byte(wr * 64 + m * 16 + fr, k * 32 + fq * 8))
; #define LDB(dst, b, h) UFOR(n, 2) UFOR(k, 2) \
;     dst[n][k] = *reinterpret_cast<const bf16x8*>((char*)SB(b, h) + lds_byte(wc * 32 + n * 16 + fr, k * 32 + fq * 8))
; #define MMA(ai, bj, At, Bq) do { __builtin_amdgcn_s_setprio(1); \
;     UFOR(m, 4) UFOR(n, 2) UFOR(k, 2) \
;       acc[ai][bj][m][n] = __builtin_amdgcn_mfma_f32_16x16x32_bf16(Bq[n][k], At[m][k], acc[ai][bj][m][n], 0, 0, 0); \
;     __builtin_amdgcn_s_setprio(0); } while (0)
; #define WAIT_V(n) asm volatile("s_waitcnt vmcnt(" #n ")" ::: "memory")
; #define WAIT_L(n) asm volatile("s_waitcnt lgkmcnt(" #n ")" ::: "memory")
; #define BAR __builtin_amdgcn_s_barrier()
; #define SCHED __builtin_amdgcn_sched_barrier(0)
; template <int EPI, int K, int KL> ...
;     ...
;     STAGE(SB(0, 1), Bt, bcol + HALF, t + 2);
;     WAIT_V(6); BAR; MMA(1, 1, At, B1); BAR;
;     LDB(B0, 1, 0); SCHED; LDA(At, 1, 0); STAGE(SA(0, 1), A, brow + HALF, t + 2);
;     WAIT_L(8); BAR; WAIT_L(0); MMA(0, 0, At, B0); BAR; SCHED;
;     LDB(B1, 1, 1); STAGE(SB(1, 0), Bt, bcol, t + 3);
;     BAR; WAIT_L(0); MMA(0, 1, At, B1); BAR;
;     LDA(At, 1, 1); STAGE(SA(1, 0), A, brow, t + 3);
	v_readfirstlane_b32 s15, v164
	v_add_u32_e32 v138, 0x2000, v164
	v_lshl_add_u64 v[136:137], v[242:243], 0, s[24:25]
	s_mov_b32 m0, s15
	v_readfirstlane_b32 s15, v138
	global_load_lds_dwordx4 v[136:137], off
	v_lshl_add_u64 v[136:137], v[244:245], 0, s[24:25]
	s_mov_b32 m0, s15
	s_nop 0
	global_load_lds_dwordx4 v[136:137], off
	s_waitcnt vmcnt(6)
	s_barrier
	v_mfma_f32_16x16x32_bf16 v[28:31], v[226:229], v[190:193], v[28:31]
	v_mfma_f32_16x16x32_bf16 v[24:27], v[234:237], v[190:193], v[24:27]
	v_mfma_f32_16x16x32_bf16 v[20:23], v[226:229], v[198:201], v[20:23]
	v_mfma_f32_16x16x32_bf16 v[16:19], v[234:237], v[198:201], v[16:19]
	v_mfma_f32_16x16x32_bf16 v[12:15], v[226:229], v[208:211], v[12:15]
	v_mfma_f32_16x16x32_bf16 v[8:11], v[234:237], v[208:211], v[8:11]
	v_mfma_f32_16x16x32_bf16 v[4:7], v[226:229], v[218:221], v[4:7]
	v_mfma_f32_16x16x32_bf16 v[0:3], v[234:237], v[218:221], v[0:3]
	v_mfma_f32_16x16x32_bf16 v[28:31], v[230:233], v[194:197], v[28:31]
	v_mfma_f32_16x16x32_bf16 v[24:27], v[238:241], v[194:197], v[24:27]
	v_mfma_f32_16x16x32_bf16 v[20:23], v[230:233], v[202:205], v[20:23]
	v_mfma_f32_16x16x32_bf16 v[16:19], v[238:241], v[202:205], v[16:19]
	v_mfma_f32_16x16x32_bf16 v[12:15], v[230:233], v[214:217], v[12:15]
	v_mfma_f32_16x16x32_bf16 v[8:11], v[238:241], v[214:217], v[8:11]
	v_mfma_f32_16x16x32_bf16 v[4:7], v[230:233], v[222:225], v[4:7]
	v_mfma_f32_16x16x32_bf16 v[0:3], v[238:241], v[222:225], v[0:3]
	s_barrier
	ds_read_b128 v[136:139], v166
	ds_read_b128 v[178:181], v166 offset:1024
	ds_read_b128 v[182:185], v166 offset:2048
	ds_read_b128 v[186:189], v166 offset:3072
	v_readfirstlane_b32 s15, v165
	v_lshl_add_u64 v[226:227], v[152:153], 0, s[62:63]
	s_mov_b32 m0, s15
	v_readfirstlane_b32 s15, v167
	ds_read_b128 v[190:193], v160 offset:32768
	ds_read_b128 v[194:197], v160 offset:33792
	ds_read_b128 v[198:201], v159 offset:32768
	ds_read_b128 v[202:205], v159 offset:33792
	ds_read_b128 v[208:211], v158 offset:32768
	ds_read_b128 v[214:217], v158 offset:33792
	ds_read_b128 v[218:221], v157 offset:32768
	ds_read_b128 v[222:225], v157 offset:33792
	global_load_lds_dwordx4 v[226:227], off
	v_lshl_add_u64 v[226:227], v[154:155], 0, s[62:63]
	s_mov_b32 m0, s15
	s_nop 0
	global_load_lds_dwordx4 v[226:227], off
	s_waitcnt lgkmcnt(8)
	s_barrier
	s_waitcnt lgkmcnt(0)
	s_waitcnt lgkmcnt(0)
	v_mfma_f32_16x16x32_bf16 v[124:127], v[136:139], v[190:193], v[124:127]
	v_mfma_f32_16x16x32_bf16 v[120:123], v[182:185], v[190:193], v[120:123]
	v_mfma_f32_16x16x32_bf16 v[116:119], v[136:139], v[198:201], v[116:119]
	v_mfma_f32_16x16x32_bf16 v[112:115], v[182:185], v[198:201], v[112:115]
	v_mfma_f32_16x16x32_bf16 v[108:111], v[136:139], v[208:211], v[108:111]
	v_mfma_f32_16x16x32_bf16 v[104:107], v[182:185], v[208:211], v[104:107]
	v_mfma_f32_16x16x32_bf16 v[100:103], v[136:139], v[218:221], v[100:103]
	v_mfma_f32_16x16x32_bf16 v[96:99], v[182:185], v[218:221], v[96:99]
	v_mfma_f32_16x16x32_bf16 v[124:127], v[178:181], v[194:197], v[124:127]
	v_mfma_f32_16x16x32_bf16 v[120:123], v[186:189], v[194:197], v[120:123]
	v_mfma_f32_16x16x32_bf16 v[116:119], v[178:181], v[202:205], v[116:119]
	v_mfma_f32_16x16x32_bf16 v[112:115], v[186:189], v[202:205], v[112:115]
	v_mfma_f32_16x16x32_bf16 v[108:111], v[178:181], v[214:217], v[108:111]
	v_mfma_f32_16x16x32_bf16 v[104:107], v[186:189], v[214:217], v[104:107]
	v_mfma_f32_16x16x32_bf16 v[100:103], v[178:181], v[222:225], v[100:103]
	v_mfma_f32_16x16x32_bf16 v[96:99], v[186:189], v[222:225], v[96:99]
	s_barrier
	v_readfirstlane_b32 s15, v168
	v_lshl_add_u64 v[246:247], v[242:243], 0, s[94:95]
	s_mov_b32 m0, s15
	v_readfirstlane_b32 s15, v169
	ds_read_b128 v[226:229], v163
	ds_read_b128 v[230:233], v163 offset:1024
	ds_read_b128 v[234:237], v163 offset:2048
	ds_read_b128 v[238:241], v163 offset:3072
	global_load_lds_dwordx4 v[246:247], off
	v_lshl_add_u64 v[246:247], v[244:245], 0, s[94:95]
	s_mov_b32 m0, s15
	s_nop 0
	global_load_lds_dwordx4 v[246:247], off
	s_barrier
	s_waitcnt lgkmcnt(0)
	s_waitcnt lgkmcnt(0)
	v_mfma_f32_16x16x32_bf16 v[92:95], v[226:229], v[190:193], v[92:95]
	v_mfma_f32_16x16x32_bf16 v[88:91], v[234:237], v[190:193], v[88:91]
	v_mfma_f32_16x16x32_bf16 v[84:87], v[226:229], v[198:201], v[84:87]
	v_mfma_f32_16x16x32_bf16 v[80:83], v[234:237], v[198:201], v[80:83]
	v_mfma_f32_16x16x32_bf16 v[76:79], v[226:229], v[208:211], v[76:79]
	v_mfma_f32_16x16x32_bf16 v[72:75], v[234:237], v[208:211], v[72:75]
	v_mfma_f32_16x16x32_bf16 v[68:71], v[226:229], v[218:221], v[68:71]
	v_mfma_f32_16x16x32_bf16 v[64:67], v[234:237], v[218:221], v[64:67]
	v_mfma_f32_16x16x32_bf16 v[92:95], v[230:233], v[194:197], v[92:95]
	v_mfma_f32_16x16x32_bf16 v[88:91], v[238:241], v[194:197], v[88:91]
	v_mfma_f32_16x16x32_bf16 v[84:87], v[230:233], v[202:205], v[84:87]
	v_mfma_f32_16x16x32_bf16 v[80:83], v[238:241], v[202:205], v[80:83]
	v_mfma_f32_16x16x32_bf16 v[76:79], v[230:233], v[214:217], v[76:79]
	v_mfma_f32_16x16x32_bf16 v[72:75], v[238:241], v[214:217], v[72:75]
	v_mfma_f32_16x16x32_bf16 v[68:71], v[230:233], v[222:225], v[68:71]
	v_mfma_f32_16x16x32_bf16 v[64:67], v[238:241], v[222:225], v[64:67]
	v_readfirstlane_b32 s15, v170
	v_lshl_add_u64 v[152:153], v[152:153], 0, s[64:65]
	s_mov_b32 m0, s15
	v_readfirstlane_b32 s15, v171
	s_barrier
	ds_read_b128 v[190:193], v160 offset:49152
	ds_read_b128 v[194:197], v160 offset:50176
	ds_read_b128 v[198:201], v159 offset:49152
	ds_read_b128 v[202:205], v159 offset:50176
	ds_read_b128 v[208:211], v158 offset:49152
	ds_read_b128 v[214:217], v158 offset:50176
	ds_read_b128 v[218:221], v157 offset:49152
	ds_read_b128 v[222:225], v157 offset:50176
	global_load_lds_dwordx4 v[152:153], off
	v_lshl_add_u64 v[152:153], v[154:155], 0, s[64:65]
	s_mov_b32 m0, s15
	s_nop 0
	global_load_lds_dwordx4 v[152:153], off
	s_barrier
; #define STAGE(P, BASE, br, kt) STAGET(tid_, P, BASE, br, kt)
; #define LDA(dst, b, h) UFOR(m, 4) UFOR(k, 2) \
;     dst[m][k] = *reinterpret_cast<const bf16x8*>((char*)SA(b, h) + lds_byte(wr * 64 + m * 16 + fr, k * 32 + fq * 8))
; #define LDB(dst, b, h) UFOR(n, 2) UFOR(k, 2) \
;     dst[n][k] = *reinterpret_cast<const bf16x8*>((char*)SB(b, h) + lds_byte(wc * 32 + n * 16 + fr, k * 32 + fq * 8))
; #define MMA(ai, bj, At, Bq) do { __builtin_amdgcn_s_setprio(1); \
;     UFOR(m, 4) UFOR(n, 2) UFOR(k, 2) \
;       acc[ai][bj][m][n] = __builtin_amdgcn_mfma_f32_16x16x32_bf16(Bq[n][k], At[m][k], acc[ai][bj][m][n], 0, 0, 0); \
;     __builtin_amdgcn_s_setprio(0); } while (0)
; #define WAIT_V(n) asm volatile("s_waitcnt vmcnt(" #n ")" ::: "memory")
; #define WAIT_L(n) asm volatile("s_waitcnt lgkmcnt(" #n ")" ::: "memory")
; #define BAR __builtin_amdgcn_s_barrier()
; #define SCHED __builtin_amdgcn_sched_barrier(0)
; template <int EPI, int K, int KL> ...
;     ...
;     BAR; WAIT_L(0); MMA(1, 0, At, B0); BAR; SCHED;
;     STAGE(SB(1, 1), Bt, bcol + HALF, t + 3);
;     WAIT_V(6); BAR; MMA(1, 1, At, B1); BAR;
;   }
;   { LDB(B0, 0, 0); LDA(At, 0, 0); STAGE(SA(1, 1), A, brow + HALF, nt - 1);
;     BAR; WAIT_L(0); MMA(0, 0, At, B0); BAR;
;     LDB(B1, 0, 1); BAR; WAIT_L(0); MMA(0, 1, At, B1); BAR;
	s_waitcnt lgkmcnt(0)
	s_waitcnt lgkmcnt(0)
	v_mfma_f32_16x16x32_bf16 v[60:63], v[136:139], v[190:193], v[60:63]
	v_mfma_f32_16x16x32_bf16 v[56:59], v[182:185], v[190:193], v[56:59]
	v_mfma_f32_16x16x32_bf16 v[52:55], v[136:139], v[198:201], v[52:55]
	v_mfma_f32_16x16x32_bf16 v[48:51], v[182:185], v[198:201], v[48:51]
	v_mfma_f32_16x16x32_bf16 v[44:47], v[136:139], v[208:211], v[44:47]
	v_mfma_f32_16x16x32_bf16 v[40:43], v[182:185], v[208:211], v[40:43]
	v_mfma_f32_16x16x32_bf16 v[36:39], v[136:139], v[218:221], v[36:39]
	v_mfma_f32_16x16x32_bf16 v[32:35], v[182:185], v[218:221], v[32:35]
	v_mfma_f32_16x16x32_bf16 v[60:63], v[178:181], v[194:197], v[60:63]
	v_mfma_f32_16x16x32_bf16 v[56:59], v[186:189], v[194:197], v[56:59]
	v_mfma_f32_16x16x32_bf16 v[52:55], v[178:181], v[202:205], v[52:55]
	v_mfma_f32_16x16x32_bf16 v[48:51], v[186:189], v[202:205], v[48:51]
	v_mfma_f32_16x16x32_bf16 v[44:47], v[178:181], v[214:217], v[44:47]
	v_mfma_f32_16x16x32_bf16 v[40:43], v[186:189], v[214:217], v[40:43]
	v_mfma_f32_16x16x32_bf16 v[36:39], v[178:181], v[222:225], v[36:39]
	v_mfma_f32_16x16x32_bf16 v[32:35], v[186:189], v[222:225], v[32:35]
	s_barrier
	v_readfirstlane_b32 s15, v172
	v_lshl_add_u64 v[136:137], v[242:243], 0, s[10:11]
	s_mov_b32 m0, s15
	v_readfirstlane_b32 s15, v174
	global_load_lds_dwordx4 v[136:137], off
	v_lshl_add_u64 v[136:137], v[244:245], 0, s[10:11]
	s_mov_b32 m0, s15
	s_nop 0
	global_load_lds_dwordx4 v[136:137], off
	s_waitcnt vmcnt(6)
	s_barrier
	v_mfma_f32_16x16x32_bf16 v[28:31], v[226:229], v[190:193], v[28:31]
	v_mfma_f32_16x16x32_bf16 v[24:27], v[234:237], v[190:193], v[24:27]
	v_mfma_f32_16x16x32_bf16 v[20:23], v[226:229], v[198:201], v[20:23]
	v_mfma_f32_16x16x32_bf16 v[16:19], v[234:237], v[198:201], v[16:19]
	v_mfma_f32_16x16x32_bf16 v[12:15], v[226:229], v[208:211], v[12:15]
	v_mfma_f32_16x16x32_bf16 v[8:11], v[234:237], v[208:211], v[8:11]
	v_mfma_f32_16x16x32_bf16 v[4:7], v[226:229], v[218:221], v[4:7]
	v_mfma_f32_16x16x32_bf16 v[0:3], v[234:237], v[218:221], v[0:3]
	v_mfma_f32_16x16x32_bf16 v[28:31], v[230:233], v[194:197], v[28:31]
	v_mfma_f32_16x16x32_bf16 v[24:27], v[238:241], v[194:197], v[24:27]
	v_mfma_f32_16x16x32_bf16 v[20:23], v[230:233], v[202:205], v[20:23]
	v_mfma_f32_16x16x32_bf16 v[16:19], v[238:241], v[202:205], v[16:19]
	v_mfma_f32_16x16x32_bf16 v[12:15], v[230:233], v[214:217], v[12:15]
	v_mfma_f32_16x16x32_bf16 v[8:11], v[238:241], v[214:217], v[8:11]
	v_mfma_f32_16x16x32_bf16 v[4:7], v[230:233], v[222:225], v[4:7]
	v_mfma_f32_16x16x32_bf16 v[0:3], v[238:241], v[222:225], v[0:3]
	s_add_i32 s14, s14, 2
	v_lshl_add_u64 v[144:145], v[144:145], 0, s[20:21]
	v_lshl_add_u64 v[146:147], v[146:147], 0, s[20:21]
	v_lshl_add_u64 v[148:149], v[148:149], 0, s[20:21]
	s_cmp_lt_u32 s14, 4
	v_lshl_add_u64 v[150:151], v[150:151], 0, s[20:21]
	s_barrier
	s_cbranch_scc1 .LBB0_1204
	s_add_u32 s14, s46, 0x160380
	s_addc_u32 s15, s47, 0
	v_lshl_add_u64 v[142:143], s[14:15], 0, v[142:143]
	v_readfirstlane_b32 s18, v176
	v_lshl_add_u64 v[128:129], v[128:129], 1, v[142:143]
	s_mov_b32 m0, s18
	ds_read_b128 v[136:139], v175
	ds_read_b128 v[144:147], v175 offset:1024
	ds_read_b128 v[148:151], v175 offset:2048
	ds_read_b128 v[168:171], v175 offset:3072
	ds_read_b128 v[178:181], v160
	ds_read_b128 v[182:185], v160 offset:1024
	ds_read_b128 v[186:189], v159
	ds_read_b128 v[190:193], v159 offset:1024
	ds_read_b128 v[194:197], v158
	ds_read_b128 v[198:201], v158 offset:1024
	ds_read_b128 v[202:205], v157
	ds_read_b128 v[208:211], v157 offset:1024
	global_load_lds_dwordx4 v[128:129], off
	v_lshl_add_u64 v[128:129], s[14:15], 0, v[140:141]
	v_readfirstlane_b32 s14, v177
	v_lshl_add_u64 v[128:129], v[130:131], 1, v[128:129]
	s_mov_b32 m0, s14
	s_nop 0
	global_load_lds_dwordx4 v[128:129], off
	s_barrier
	s_waitcnt lgkmcnt(0)
	s_waitcnt lgkmcnt(0)
	v_mfma_f32_16x16x32_bf16 v[124:127], v[136:139], v[178:181], v[124:127]
	v_mfma_f32_16x16x32_bf16 v[120:123], v[148:151], v[178:181], v[120:123]
	v_mfma_f32_16x16x32_bf16 v[116:119], v[136:139], v[186:189], v[116:119]
	v_mfma_f32_16x16x32_bf16 v[112:115], v[148:151], v[186:189], v[112:115]
	v_mfma_f32_16x16x32_bf16 v[108:111], v[136:139], v[194:197], v[108:111]
	v_mfma_f32_16x16x32_bf16 v[104:107], v[148:151], v[194:197], v[104:107]
	v_mfma_f32_16x16x32_bf16 v[100:103], v[136:139], v[202:205], v[100:103]
	v_mfma_f32_16x16x32_bf16 v[96:99], v[148:151], v[202:205], v[96:99]
	v_mfma_f32_16x16x32_bf16 v[124:127], v[144:147], v[182:185], v[124:127]
	v_mfma_f32_16x16x32_bf16 v[120:123], v[168:171], v[182:185], v[120:123]
	v_mfma_f32_16x16x32_bf16 v[116:119], v[144:147], v[190:193], v[116:119]
	v_mfma_f32_16x16x32_bf16 v[112:115], v[168:171], v[190:193], v[112:115]
	v_mfma_f32_16x16x32_bf16 v[108:111], v[144:147], v[198:201], v[108:111]
	v_mfma_f32_16x16x32_bf16 v[104:107], v[168:171], v[198:201], v[104:107]
	v_mfma_f32_16x16x32_bf16 v[100:103], v[144:147], v[208:211], v[100:103]
	v_mfma_f32_16x16x32_bf16 v[96:99], v[168:171], v[208:211], v[96:99]
	s_barrier
	ds_read_b128 v[128:131], v173
	ds_read_b128 v[140:143], v173 offset:1024
	ds_read_b128 v[174:177], v173 offset:2048
	ds_read_b128 v[214:217], v173 offset:3072
	s_barrier
; #define LDA(dst, b, h) UFOR(m, 4) UFOR(k, 2) \
;     dst[m][k] = *reinterpret_cast<const bf16x8*>((char*)SA(b, h) + lds_byte(wr * 64 + m * 16 + fr, k * 32 + fq * 8))
; #define LDB(dst, b, h) UFOR(n, 2) UFOR(k, 2) \
;     dst[n][k] = *reinterpret_cast<const bf16x8*>((char*)SB(b, h) + lds_byte(wc * 32 + n * 16 + fr, k * 32 + fq * 8))
; #define MMA(ai, bj, At, Bq) do { __builtin_amdgcn_s_setprio(1); \
;     UFOR(m, 4) UFOR(n, 2) UFOR(k, 2) \
;       acc[ai][bj][m][n] = __builtin_amdgcn_mfma_f32_16x16x32_bf16(Bq[n][k], At[m][k], acc[ai][bj][m][n], 0, 0, 0); \
;     __builtin_amdgcn_s_setprio(0); } while (0)
; #define WAIT_V(n) asm volatile("s_waitcnt vmcnt(" #n ")" ::: "memory")
; #define WAIT_L(n) asm volatile("s_waitcnt lgkmcnt(" #n ")" ::: "memory")
; #define BAR __builtin_amdgcn_s_barrier()
; template <int EPI, int K, int KL> ...
;     ...
;     LDB(B1, 0, 1); BAR; WAIT_L(0); MMA(0, 1, At, B1); BAR;
;     LDA(At, 0, 1); WAIT_V(4); BAR; WAIT_L(0); MMA(1, 0, At, B0); MMA(1, 1, At, B1); BAR; }
;   { LDB(B0, 1, 0); LDA(At, 1, 0); WAIT_V(2); BAR; WAIT_L(0); MMA(0, 0, At, B0); BAR;
	s_waitcnt lgkmcnt(0)
	s_waitcnt lgkmcnt(0)
	v_mfma_f32_16x16x32_bf16 v[92:95], v[128:131], v[178:181], v[92:95]
	v_mfma_f32_16x16x32_bf16 v[88:91], v[174:177], v[178:181], v[88:91]
	v_mfma_f32_16x16x32_bf16 v[84:87], v[128:131], v[186:189], v[84:87]
	v_mfma_f32_16x16x32_bf16 v[80:83], v[174:177], v[186:189], v[80:83]
	v_mfma_f32_16x16x32_bf16 v[76:79], v[128:131], v[194:197], v[76:79]
	v_mfma_f32_16x16x32_bf16 v[68:71], v[128:131], v[202:205], v[68:71]
	v_mfma_f32_16x16x32_bf16 v[64:67], v[174:177], v[202:205], v[64:67]
	v_mfma_f32_16x16x32_bf16 v[92:95], v[140:143], v[182:185], v[92:95]
	v_mfma_f32_16x16x32_bf16 v[88:91], v[214:217], v[182:185], v[88:91]
	v_mfma_f32_16x16x32_bf16 v[84:87], v[140:143], v[190:193], v[84:87]
	v_mfma_f32_16x16x32_bf16 v[80:83], v[214:217], v[190:193], v[80:83]
	v_mfma_f32_16x16x32_bf16 v[76:79], v[140:143], v[198:201], v[76:79]
	v_mfma_f32_16x16x32_bf16 v[72:75], v[174:177], v[194:197], v[72:75]
	v_mfma_f32_16x16x32_bf16 v[68:71], v[140:143], v[208:211], v[68:71]
	v_mfma_f32_16x16x32_bf16 v[64:67], v[214:217], v[208:211], v[64:67]
	v_mfma_f32_16x16x32_bf16 v[178:181], v[214:217], v[198:201], v[72:75]
	s_barrier
	s_nop 2
	ds_read_b128 v[72:75], v160 offset:16384
	ds_read_b128 v[182:185], v160 offset:17408
	ds_read_b128 v[186:189], v159 offset:16384
	ds_read_b128 v[190:193], v159 offset:17408
	ds_read_b128 v[194:197], v158 offset:16384
	ds_read_b128 v[198:201], v158 offset:17408
	ds_read_b128 v[202:205], v157 offset:16384
	ds_read_b128 v[208:211], v157 offset:17408
	s_waitcnt vmcnt(4)
	s_barrier
	s_waitcnt lgkmcnt(0)
	s_waitcnt lgkmcnt(0)
	v_mfma_f32_16x16x32_bf16 v[48:51], v[148:151], v[186:189], v[48:51]
	v_mfma_f32_16x16x32_bf16 v[60:63], v[136:139], v[72:75], v[60:63]
	v_mfma_f32_16x16x32_bf16 v[56:59], v[148:151], v[72:75], v[56:59]
	v_mfma_f32_16x16x32_bf16 v[52:55], v[136:139], v[186:189], v[52:55]
	v_mfma_f32_16x16x32_bf16 v[48:51], v[168:171], v[190:193], v[48:51]
	v_mfma_f32_16x16x32_bf16 v[44:47], v[136:139], v[194:197], v[44:47]
	v_mfma_f32_16x16x32_bf16 v[40:43], v[148:151], v[194:197], v[40:43]
	v_mfma_f32_16x16x32_bf16 v[36:39], v[136:139], v[202:205], v[36:39]
	v_mfma_f32_16x16x32_bf16 v[32:35], v[148:151], v[202:205], v[32:35]
	v_mfma_f32_16x16x32_bf16 v[218:221], v[144:147], v[182:185], v[60:63]
	v_mfma_f32_16x16x32_bf16 v[222:225], v[168:171], v[182:185], v[56:59]
	v_mfma_f32_16x16x32_bf16 v[226:229], v[144:147], v[190:193], v[52:55]
	v_mfma_f32_16x16x32_bf16 v[230:233], v[144:147], v[198:201], v[44:47]
	v_mfma_f32_16x16x32_bf16 v[234:237], v[168:171], v[198:201], v[40:43]
	v_mfma_f32_16x16x32_bf16 v[136:139], v[144:147], v[208:211], v[36:39]
	v_mfma_f32_16x16x32_bf16 v[144:147], v[168:171], v[208:211], v[32:35]
	v_mfma_f32_16x16x32_bf16 v[28:31], v[128:131], v[72:75], v[28:31]
	v_mfma_f32_16x16x32_bf16 v[24:27], v[174:177], v[72:75], v[24:27]
	v_mfma_f32_16x16x32_bf16 v[20:23], v[128:131], v[186:189], v[20:23]
	v_mfma_f32_16x16x32_bf16 v[16:19], v[174:177], v[186:189], v[16:19]
	v_mfma_f32_16x16x32_bf16 v[12:15], v[128:131], v[194:197], v[12:15]
	v_mfma_f32_16x16x32_bf16 v[8:11], v[174:177], v[194:197], v[8:11]
	v_mfma_f32_16x16x32_bf16 v[4:7], v[128:131], v[202:205], v[4:7]
	v_mfma_f32_16x16x32_bf16 v[0:3], v[174:177], v[202:205], v[0:3]
	v_mfma_f32_16x16x32_bf16 v[148:151], v[140:143], v[182:185], v[28:31]
	v_mfma_f32_16x16x32_bf16 v[168:171], v[214:217], v[182:185], v[24:27]
	v_mfma_f32_16x16x32_bf16 v[182:185], v[140:143], v[190:193], v[20:23]
	v_mfma_f32_16x16x32_bf16 v[186:189], v[214:217], v[190:193], v[16:19]
	v_mfma_f32_16x16x32_bf16 v[190:193], v[140:143], v[198:201], v[12:15]
	v_mfma_f32_16x16x32_bf16 v[194:197], v[214:217], v[198:201], v[8:11]
	v_mfma_f32_16x16x32_bf16 v[128:131], v[140:143], v[208:211], v[4:7]
	v_mfma_f32_16x16x32_bf16 v[140:143], v[214:217], v[208:211], v[0:3]
	s_barrier
	ds_read_b128 v[172:175], v166
	ds_read_b128 v[198:201], v166 offset:1024
	ds_read_b128 v[202:205], v166 offset:2048
	ds_read_b128 v[164:167], v166 offset:3072
	ds_read_b128 v[20:23], v160 offset:32768
	ds_read_b128 v[24:27], v160 offset:33792
	ds_read_b128 v[28:31], v159 offset:32768
	ds_read_b128 v[32:35], v159 offset:33792
	ds_read_b128 v[36:39], v158 offset:32768
	ds_read_b128 v[208:211], v158 offset:33792
	ds_read_b128 v[214:217], v157 offset:32768
	ds_read_b128 v[238:241], v157 offset:33792
	s_waitcnt vmcnt(2)
	s_barrier
; #define LDA(dst, b, h) UFOR(m, 4) UFOR(k, 2) \
;     dst[m][k] = *reinterpret_cast<const bf16x8*>((char*)SA(b, h) + lds_byte(wr * 64 + m * 16 + fr, k * 32 + fq * 8))
; #define LDB(dst, b, h) UFOR(n, 2) UFOR(k, 2) \
;     dst[n][k] = *reinterpret_cast<const bf16x8*>((char*)SB(b, h) + lds_byte(wc * 32 + n * 16 + fr, k * 32 + fq * 8))
; #define MMA(ai, bj, At, Bq) do { __builtin_amdgcn_s_setprio(1); \
;     UFOR(m, 4) UFOR(n, 2) UFOR(k, 2) \
;       acc[ai][bj][m][n] = __builtin_amdgcn_mfma_f32_16x16x32_bf16(Bq[n][k], At[m][k], acc[ai][bj][m][n], 0, 0, 0); \
;     __builtin_amdgcn_s_setprio(0); } while (0)
; #define WAIT_V(n) asm volatile("s_waitcnt vmcnt(" #n ")" ::: "memory")
; #define WAIT_L(n) asm volatile("s_waitcnt lgkmcnt(" #n ")" ::: "memory")
; #define BAR __builtin_amdgcn_s_barrier()
; template <int EPI, int K, int KL> ...
;     ...
;   { LDB(B0, 1, 0); LDA(At, 1, 0); WAIT_V(2); BAR; WAIT_L(0); MMA(0, 0, At, B0); BAR;
;     LDB(B1, 1, 1); WAIT_V(0); BAR; WAIT_L(0); MMA(0, 1, At, B1); BAR;
;     LDA(At, 1, 1); BAR; WAIT_L(0); MMA(1, 0, At, B0); MMA(1, 1, At, B1); BAR; }
;   if (wr == 0) BAR;
; __device__ __forceinline__ void gemm_ctx_splitk_down(const u16* A, const u16* Bt, float* P2, const EpiArgs& e0) {
;     ...
;   for (int u = bid_; u < 16 * P2_PARTS; u += gridDim.x) {
	s_waitcnt lgkmcnt(0)
	s_waitcnt lgkmcnt(0)
	v_mfma_f32_16x16x32_bf16 v[0:3], v[172:175], v[20:23], v[124:127]
	v_mfma_f32_16x16x32_bf16 v[44:47], v[198:201], v[24:27], v[0:3]
	v_mfma_f32_16x16x32_bf16 v[0:3], v[202:205], v[20:23], v[120:123]
	v_mfma_f32_16x16x32_bf16 v[52:55], v[164:167], v[24:27], v[0:3]
	v_mfma_f32_16x16x32_bf16 v[0:3], v[172:175], v[28:31], v[116:119]
	v_mfma_f32_16x16x32_bf16 v[40:43], v[198:201], v[32:35], v[0:3]
	v_mfma_f32_16x16x32_bf16 v[0:3], v[202:205], v[28:31], v[112:115]
	v_mfma_f32_16x16x32_bf16 v[16:19], v[164:167], v[32:35], v[0:3]
	v_mfma_f32_16x16x32_bf16 v[0:3], v[172:175], v[36:39], v[108:111]
	v_mfma_f32_16x16x32_bf16 v[8:11], v[198:201], v[208:211], v[0:3]
	v_mfma_f32_16x16x32_bf16 v[0:3], v[202:205], v[36:39], v[104:107]
	v_mfma_f32_16x16x32_bf16 v[12:15], v[164:167], v[208:211], v[0:3]
	v_mfma_f32_16x16x32_bf16 v[0:3], v[172:175], v[214:217], v[100:103]
	v_mfma_f32_16x16x32_bf16 v[4:7], v[202:205], v[214:217], v[96:99]
	v_mfma_f32_16x16x32_bf16 v[0:3], v[198:201], v[238:241], v[0:3]
	v_mfma_f32_16x16x32_bf16 v[4:7], v[164:167], v[238:241], v[4:7]
	s_barrier
	ds_read_b128 v[108:111], v163
	ds_read_b128 v[242:245], v163 offset:1024
	ds_read_b128 v[246:249], v163 offset:2048
	ds_read_b128 v[152:155], v163 offset:3072
	s_waitcnt vmcnt(0)
	s_barrier
	s_waitcnt lgkmcnt(0)
	s_waitcnt lgkmcnt(0)
	v_mfma_f32_16x16x32_bf16 v[56:59], v[108:111], v[20:23], v[92:95]
	v_mfma_f32_16x16x32_bf16 v[20:23], v[246:249], v[20:23], v[88:91]
	v_mfma_f32_16x16x32_bf16 v[72:75], v[152:155], v[24:27], v[20:23]
	v_mfma_f32_16x16x32_bf16 v[20:23], v[108:111], v[28:31], v[84:87]
	v_mfma_f32_16x16x32_bf16 v[60:63], v[242:245], v[24:27], v[56:59]
	v_mfma_f32_16x16x32_bf16 v[56:59], v[242:245], v[32:35], v[20:23]
	v_mfma_f32_16x16x32_bf16 v[20:23], v[246:249], v[28:31], v[80:83]
	v_mfma_f32_16x16x32_bf16 v[20:23], v[152:155], v[32:35], v[20:23]
	v_mfma_f32_16x16x32_bf16 v[24:27], v[108:111], v[36:39], v[76:79]
	v_mfma_f32_16x16x32_bf16 v[28:31], v[246:249], v[36:39], v[178:181]
	v_mfma_f32_16x16x32_bf16 v[32:35], v[108:111], v[214:217], v[68:71]
	v_mfma_f32_16x16x32_bf16 v[36:39], v[246:249], v[214:217], v[64:67]
	v_mfma_f32_16x16x32_bf16 v[24:27], v[242:245], v[208:211], v[24:27]
	v_mfma_f32_16x16x32_bf16 v[28:31], v[152:155], v[208:211], v[28:31]
	v_mfma_f32_16x16x32_bf16 v[32:35], v[242:245], v[238:241], v[32:35]
	v_mfma_f32_16x16x32_bf16 v[36:39], v[152:155], v[238:241], v[36:39]
	s_barrier
	ds_read_b128 v[88:91], v160 offset:49152
	ds_read_b128 v[92:95], v160 offset:50176
	ds_read_b128 v[96:99], v159 offset:49152
	ds_read_b128 v[100:103], v159 offset:50176
	ds_read_b128 v[104:107], v158 offset:49152
	ds_read_b128 v[158:161], v158 offset:50176
	ds_read_b128 v[176:179], v157 offset:49152
	ds_read_b128 v[208:211], v157 offset:50176
	s_barrier
	s_waitcnt lgkmcnt(0)
	s_waitcnt lgkmcnt(0)
	v_mfma_f32_16x16x32_bf16 v[48:51], v[202:205], v[96:99], v[48:51]
	v_mfma_f32_16x16x32_bf16 v[64:67], v[172:175], v[88:91], v[218:221]
	v_mfma_f32_16x16x32_bf16 v[116:119], v[164:167], v[100:103], v[48:51]
	v_mfma_f32_16x16x32_bf16 v[48:51], v[172:175], v[104:107], v[230:233]
	v_mfma_f32_16x16x32_bf16 v[120:123], v[198:201], v[92:95], v[64:67]
	v_mfma_f32_16x16x32_bf16 v[64:67], v[202:205], v[88:91], v[222:225]
	v_mfma_f32_16x16x32_bf16 v[76:79], v[198:201], v[158:161], v[48:51]
	v_mfma_f32_16x16x32_bf16 v[48:51], v[202:205], v[104:107], v[234:237]
	v_mfma_f32_16x16x32_bf16 v[124:127], v[164:167], v[92:95], v[64:67]
	v_mfma_f32_16x16x32_bf16 v[64:67], v[172:175], v[96:99], v[226:229]
	v_mfma_f32_16x16x32_bf16 v[80:83], v[164:167], v[158:161], v[48:51]
	v_mfma_f32_16x16x32_bf16 v[48:51], v[172:175], v[176:179], v[136:139]
	v_mfma_f32_16x16x32_bf16 v[112:115], v[198:201], v[100:103], v[64:67]
	v_mfma_f32_16x16x32_bf16 v[64:67], v[198:201], v[208:211], v[48:51]
	v_mfma_f32_16x16x32_bf16 v[48:51], v[202:205], v[176:179], v[144:147]
	v_mfma_f32_16x16x32_bf16 v[68:71], v[164:167], v[208:211], v[48:51]
	v_mfma_f32_16x16x32_bf16 v[48:51], v[108:111], v[88:91], v[148:151]
	v_mfma_f32_16x16x32_bf16 v[84:87], v[242:245], v[92:95], v[48:51]
	v_mfma_f32_16x16x32_bf16 v[48:51], v[246:249], v[88:91], v[168:171]
	v_mfma_f32_16x16x32_bf16 v[88:91], v[152:155], v[92:95], v[48:51]
	v_mfma_f32_16x16x32_bf16 v[48:51], v[108:111], v[96:99], v[182:185]
	v_mfma_f32_16x16x32_bf16 v[92:95], v[242:245], v[100:103], v[48:51]
	v_mfma_f32_16x16x32_bf16 v[48:51], v[246:249], v[96:99], v[186:189]
	v_mfma_f32_16x16x32_bf16 v[96:99], v[152:155], v[100:103], v[48:51]
	v_mfma_f32_16x16x32_bf16 v[48:51], v[108:111], v[104:107], v[190:193]
	v_mfma_f32_16x16x32_bf16 v[100:103], v[242:245], v[158:161], v[48:51]
	v_mfma_f32_16x16x32_bf16 v[48:51], v[246:249], v[104:107], v[194:197]
	v_mfma_f32_16x16x32_bf16 v[104:107], v[152:155], v[158:161], v[48:51]
	v_mfma_f32_16x16x32_bf16 v[48:51], v[108:111], v[176:179], v[128:131]
	v_mfma_f32_16x16x32_bf16 v[108:111], v[242:245], v[208:211], v[48:51]
	v_mfma_f32_16x16x32_bf16 v[48:51], v[246:249], v[176:179], v[140:143]
	v_mfma_f32_16x16x32_bf16 v[48:51], v[152:155], v[208:211], v[48:51]
	s_movk_i32 s14, 0x100
	v_cmp_gt_u32_e32 vcc, s14, v132
	s_barrier
	s_and_saveexec_b64 s[44:45], vcc
	s_cbranch_execz .LBB0_1200
	s_barrier
	s_branch .LBB0_1200
